# GEMM loops: s_setprio roles swapped (load segment prio 1, MFMA segment prio 0), middle flips dropped
# speedup vs baseline: 1.0016x; 1.0016x over previous
; #define PG8_STAGE(bufoff, gbase, voff) do { _Pragma("unroll") for (int _i = 0; _i < 2; ++_i) \
;         __builtin_amdgcn_global_load_lds((const unsigned*)((const char*)(gbase) + (voff)[_i]), (PG8_LAS unsigned*)(lds + (bufoff) + ldsw + _i * 8192), 16, 0, 0); } while (0)
; #define PG8_LDA(dst, b, h) do { _Pragma("unroll") for (int m = 0; m < 4; ++m) _Pragma("unroll") for (int k = 0; k < 2; ++k) dst[m][k] = *(const PG8_LAS bf16x8*)(lds + PG8_SA(b, h) + aoff + m * 2048 + k * 1024); } while (0)
; #define PG8_LDB(dst, b, h) do { _Pragma("unroll") for (int n = 0; n < 2; ++n) _Pragma("unroll") for (int k = 0; k < 2; ++k) dst[n][k] = *(const PG8_LAS bf16x8*)(lds + PG8_SB(b, h) + boff + n * 2048 + k * 1024); } while (0)
; #define PG8_MMA(ai, bj, At, Bt) do { __builtin_amdgcn_s_setprio(1); _Pragma("unroll") for (int m = 0; m < 4; ++m) _Pragma("unroll") for (int n = 0; n < 2; ++n) _Pragma("unroll") for (int k = 0; k < 2; ++k) \
;         acc[ai][bj][m][n] = __builtin_amdgcn_mfma_f32_16x16x32_bf16(Bt[n][k], At[m][k], acc[ai][bj][m][n], 0, 0, 0); __builtin_amdgcn_s_setprio(0); } while (0)
; #define PG8_WAIT_V(n) asm volatile("s_waitcnt vmcnt(" #n ")" ::: "memory")
; #define PG8_WAIT_L(n) asm volatile("s_waitcnt lgkmcnt(" #n ")" ::: "memory")
; #define PG8_BAR __builtin_amdgcn_s_barrier()
; #define PG8_SCHED __builtin_amdgcn_sched_barrier(0)
; template <class Epi, class Sched, bool ALIGN_EPI = false, bool SP2 = false>
; __device__ __forceinline__ void gemm_phase(PG8_LAS unsigned char* lds, const Gemm g, const Sched& S, const Epi& E) {
;     ...
;             PG8_LDB(B0, 0, 0); PG8_LDB(B1, 0, 1); PG8_SCHED; PG8_LDA(At, 0, 0); PG8_STAGE(PG8_SA(1, 1), a1 + hstep, voffA);
;             PG8_WAIT_V(8); PG8_WAIT_L(0); PG8_BAR; PG8_MMA(0, 0, At, B0); PG8_MMA(0, 1, At, B1); PG8_BAR; PG8_SCHED;
;             PG8_LDA(At, 0, 1); PG8_STAGE(PG8_SB(0, 0), b2, voffB); PG8_STAGE(PG8_SB(0, 1), b2 + hstep, voffB); PG8_STAGE(PG8_SA(0, 0), a2, voffA);
;             PG8_WAIT_V(8); PG8_WAIT_L(0); PG8_BAR; PG8_MMA(1, 0, At, B0); PG8_MMA(1, 1, At, B1); PG8_BAR; PG8_SCHED;
.LBB0_175:
	ds_read_b128 v[140:143], v177
	ds_read_b128 v[144:147], v177 offset:1024
	ds_read_b128 v[148:151], v177 offset:2048
	ds_read_b128 v[152:155], v177 offset:3072
	ds_read_b128 v[156:159], v178
	ds_read_b128 v[160:163], v178 offset:1024
	ds_read_b128 v[164:167], v178 offset:2048
	ds_read_b128 v[168:171], v178 offset:3072
	s_add_u32 s60, s58, 0xfffc0080
	s_addc_u32 s61, s59, -1
	s_cmp_eq_u32 s74, 12
	s_cselect_b32 s63, s3, s61
	s_cselect_b32 s62, s41, s60
	s_cselect_b32 s61, s45, s73
	s_cselect_b32 s60, s71, s72
	v_lshl_add_u64 v[172:173], s[58:59], 0, v[136:137]
	s_add_i32 m0, s28, 0xc000
	ds_read_b128 v[182:185], v179
	ds_read_b128 v[186:189], v179 offset:1024
	ds_read_b128 v[190:193], v179 offset:2048
	ds_read_b128 v[194:197], v179 offset:3072
	ds_read_b128 v[202:205], v179 offset:4096
	ds_read_b128 v[206:209], v179 offset:5120
	ds_read_b128 v[210:213], v179 offset:6144
	ds_read_b128 v[214:217], v179 offset:7168
	global_load_lds_dwordx4 v[172:173], off
	v_lshl_add_u64 v[172:173], s[58:59], 0, v[138:139]
	s_add_i32 m0, s28, 0xe000
	s_nop 0
	global_load_lds_dwordx4 v[172:173], off
	s_waitcnt vmcnt(8)
	s_waitcnt lgkmcnt(0)
	s_barrier
	s_setprio 0
	s_waitcnt lgkmcnt(0)
	v_mfma_f32_16x16x32_bf16 v[124:127], v[140:143], v[182:185], v[124:127]
	v_mfma_f32_16x16x32_bf16 v[120:123], v[148:151], v[182:185], v[120:123]
	v_mfma_f32_16x16x32_bf16 v[108:111], v[140:143], v[190:193], v[108:111]
	v_mfma_f32_16x16x32_bf16 v[104:107], v[148:151], v[190:193], v[104:107]
	v_mfma_f32_16x16x32_bf16 v[92:95], v[140:143], v[202:205], v[92:95]
	v_mfma_f32_16x16x32_bf16 v[88:91], v[148:151], v[202:205], v[88:91]
	v_mfma_f32_16x16x32_bf16 v[76:79], v[140:143], v[210:213], v[76:79]
	v_mfma_f32_16x16x32_bf16 v[72:75], v[148:151], v[210:213], v[72:75]
	v_mfma_f32_16x16x32_bf16 v[124:127], v[144:147], v[186:189], v[124:127]
	v_mfma_f32_16x16x32_bf16 v[120:123], v[152:155], v[186:189], v[120:123]
	v_mfma_f32_16x16x32_bf16 v[108:111], v[144:147], v[194:197], v[108:111]
	v_mfma_f32_16x16x32_bf16 v[104:107], v[152:155], v[194:197], v[104:107]
	v_mfma_f32_16x16x32_bf16 v[92:95], v[144:147], v[206:209], v[92:95]
	v_mfma_f32_16x16x32_bf16 v[88:91], v[152:155], v[206:209], v[88:91]
	v_mfma_f32_16x16x32_bf16 v[76:79], v[144:147], v[214:217], v[76:79]
	v_mfma_f32_16x16x32_bf16 v[72:75], v[152:155], v[214:217], v[72:75]
	v_mfma_f32_16x16x32_bf16 v[116:119], v[156:159], v[182:185], v[116:119]
	v_mfma_f32_16x16x32_bf16 v[112:115], v[164:167], v[182:185], v[112:115]
	v_mfma_f32_16x16x32_bf16 v[100:103], v[156:159], v[190:193], v[100:103]
	v_mfma_f32_16x16x32_bf16 v[96:99], v[164:167], v[190:193], v[96:99]
	v_mfma_f32_16x16x32_bf16 v[84:87], v[156:159], v[202:205], v[84:87]
	v_mfma_f32_16x16x32_bf16 v[80:83], v[164:167], v[202:205], v[80:83]
	v_mfma_f32_16x16x32_bf16 v[68:71], v[156:159], v[210:213], v[68:71]
	v_mfma_f32_16x16x32_bf16 v[64:67], v[164:167], v[210:213], v[64:67]
	v_mfma_f32_16x16x32_bf16 v[116:119], v[160:163], v[186:189], v[116:119]
	v_mfma_f32_16x16x32_bf16 v[112:115], v[168:171], v[186:189], v[112:115]
	v_mfma_f32_16x16x32_bf16 v[100:103], v[160:163], v[194:197], v[100:103]
	v_mfma_f32_16x16x32_bf16 v[96:99], v[168:171], v[194:197], v[96:99]
	v_mfma_f32_16x16x32_bf16 v[84:87], v[160:163], v[206:209], v[84:87]
	v_mfma_f32_16x16x32_bf16 v[80:83], v[168:171], v[206:209], v[80:83]
	v_mfma_f32_16x16x32_bf16 v[68:71], v[160:163], v[214:217], v[68:71]
	v_mfma_f32_16x16x32_bf16 v[64:67], v[168:171], v[214:217], v[64:67]
	s_setprio 1
	s_barrier
	s_add_i32 s75, s67, s21
	v_lshl_add_u64 v[172:173], s[60:61], 0, v[132:133]
	s_mov_b32 m0, s75
	ds_read_b128 v[182:185], v179 offset:16384
	ds_read_b128 v[186:189], v179 offset:17408
	ds_read_b128 v[190:193], v179 offset:18432
	ds_read_b128 v[194:197], v179 offset:19456
	ds_read_b128 v[202:205], v179 offset:20480
	ds_read_b128 v[206:209], v179 offset:21504
	ds_read_b128 v[210:213], v179 offset:22528
	ds_read_b128 v[214:217], v179 offset:23552
	global_load_lds_dwordx4 v[172:173], off
	s_add_i32 m0, s75, 0x2000
	s_add_u32 s76, s60, 0x40000
	v_lshl_add_u64 v[198:199], s[60:61], 0, v[128:129]
	s_addc_u32 s77, s61, 0
	s_add_i32 s75, s68, s21
	global_load_lds_dwordx4 v[198:199], off
	v_lshl_add_u64 v[218:219], s[76:77], 0, v[132:133]
	s_mov_b32 m0, s75
	v_lshl_add_u64 v[220:221], s[62:63], 0, v[130:131]
	global_load_lds_dwordx4 v[218:219], off
	v_lshl_add_u64 v[218:219], s[76:77], 0, v[128:129]
	s_add_i32 m0, s75, 0x2000
	s_nop 0
	global_load_lds_dwordx4 v[218:219], off
	v_lshl_add_u64 v[218:219], s[62:63], 0, v[134:135]
	s_mov_b32 m0, s28
	s_nop 0
	global_load_lds_dwordx4 v[218:219], off
	s_mov_b32 m0, s29
	s_nop 0
	global_load_lds_dwordx4 v[220:221], off
	s_waitcnt vmcnt(8)
	s_waitcnt lgkmcnt(0)
	s_barrier
; #define PG8_STAGE(bufoff, gbase, voff) do { _Pragma("unroll") for (int _i = 0; _i < 2; ++_i) \
;         __builtin_amdgcn_global_load_lds((const unsigned*)((const char*)(gbase) + (voff)[_i]), (PG8_LAS unsigned*)(lds + (bufoff) + ldsw + _i * 8192), 16, 0, 0); } while (0)
; #define PG8_LDA(dst, b, h) do { _Pragma("unroll") for (int m = 0; m < 4; ++m) _Pragma("unroll") for (int k = 0; k < 2; ++k) dst[m][k] = *(const PG8_LAS bf16x8*)(lds + PG8_SA(b, h) + aoff + m * 2048 + k * 1024); } while (0)
; #define PG8_LDB(dst, b, h) do { _Pragma("unroll") for (int n = 0; n < 2; ++n) _Pragma("unroll") for (int k = 0; k < 2; ++k) dst[n][k] = *(const PG8_LAS bf16x8*)(lds + PG8_SB(b, h) + boff + n * 2048 + k * 1024); } while (0)
; #define PG8_MMA(ai, bj, At, Bt) do { __builtin_amdgcn_s_setprio(1); _Pragma("unroll") for (int m = 0; m < 4; ++m) _Pragma("unroll") for (int n = 0; n < 2; ++n) _Pragma("unroll") for (int k = 0; k < 2; ++k) \
;         acc[ai][bj][m][n] = __builtin_amdgcn_mfma_f32_16x16x32_bf16(Bt[n][k], At[m][k], acc[ai][bj][m][n], 0, 0, 0); __builtin_amdgcn_s_setprio(0); } while (0)
; #define PG8_WAIT_V(n) asm volatile("s_waitcnt vmcnt(" #n ")" ::: "memory")
; #define PG8_WAIT_L(n) asm volatile("s_waitcnt lgkmcnt(" #n ")" ::: "memory")
; #define PG8_BAR __builtin_amdgcn_s_barrier()
; #define PG8_SCHED __builtin_amdgcn_sched_barrier(0)
; template <class Epi, class Sched, bool ALIGN_EPI = false, bool SP2 = false>
; __device__ __forceinline__ void gemm_phase(PG8_LAS unsigned char* lds, const Gemm g, const Sched& S, const Epi& E) {
;     ...
;             PG8_WAIT_V(8); PG8_WAIT_L(0); PG8_BAR; PG8_MMA(1, 0, At, B0); PG8_MMA(1, 1, At, B1); PG8_BAR; PG8_SCHED;
;             PG8_LDB(B0, 1, 0); PG8_LDB(B1, 1, 1); PG8_SCHED; PG8_LDA(At, 1, 0); PG8_STAGE(PG8_SA(0, 1), a2 + hstep, voffA);
;             PG8_WAIT_V(8); PG8_WAIT_L(0); PG8_BAR; PG8_MMA(0, 0, At, B0); PG8_MMA(0, 1, At, B1); PG8_BAR; PG8_SCHED;
	s_setprio 0
	s_waitcnt lgkmcnt(0)
	v_mfma_f32_16x16x32_bf16 v[60:63], v[140:143], v[182:185], v[60:63]
	v_mfma_f32_16x16x32_bf16 v[56:59], v[148:151], v[182:185], v[56:59]
	v_mfma_f32_16x16x32_bf16 v[44:47], v[140:143], v[190:193], v[44:47]
	v_mfma_f32_16x16x32_bf16 v[40:43], v[148:151], v[190:193], v[40:43]
	v_mfma_f32_16x16x32_bf16 v[28:31], v[140:143], v[202:205], v[28:31]
	v_mfma_f32_16x16x32_bf16 v[24:27], v[148:151], v[202:205], v[24:27]
	v_mfma_f32_16x16x32_bf16 v[12:15], v[140:143], v[210:213], v[12:15]
	v_mfma_f32_16x16x32_bf16 v[8:11], v[148:151], v[210:213], v[8:11]
	v_mfma_f32_16x16x32_bf16 v[60:63], v[144:147], v[186:189], v[60:63]
	v_mfma_f32_16x16x32_bf16 v[56:59], v[152:155], v[186:189], v[56:59]
	v_mfma_f32_16x16x32_bf16 v[44:47], v[144:147], v[194:197], v[44:47]
	v_mfma_f32_16x16x32_bf16 v[40:43], v[152:155], v[194:197], v[40:43]
	v_mfma_f32_16x16x32_bf16 v[28:31], v[144:147], v[206:209], v[28:31]
	v_mfma_f32_16x16x32_bf16 v[24:27], v[152:155], v[206:209], v[24:27]
	v_mfma_f32_16x16x32_bf16 v[12:15], v[144:147], v[214:217], v[12:15]
	v_mfma_f32_16x16x32_bf16 v[8:11], v[152:155], v[214:217], v[8:11]
	v_mfma_f32_16x16x32_bf16 v[52:55], v[156:159], v[182:185], v[52:55]
	v_mfma_f32_16x16x32_bf16 v[48:51], v[164:167], v[182:185], v[48:51]
	v_mfma_f32_16x16x32_bf16 v[36:39], v[156:159], v[190:193], v[36:39]
	v_mfma_f32_16x16x32_bf16 v[32:35], v[164:167], v[190:193], v[32:35]
	v_mfma_f32_16x16x32_bf16 v[20:23], v[156:159], v[202:205], v[20:23]
	v_mfma_f32_16x16x32_bf16 v[16:19], v[164:167], v[202:205], v[16:19]
	v_mfma_f32_16x16x32_bf16 v[4:7], v[156:159], v[210:213], v[4:7]
	v_mfma_f32_16x16x32_bf16 v[0:3], v[164:167], v[210:213], v[0:3]
	v_mfma_f32_16x16x32_bf16 v[52:55], v[160:163], v[186:189], v[52:55]
	v_mfma_f32_16x16x32_bf16 v[48:51], v[168:171], v[186:189], v[48:51]
	v_mfma_f32_16x16x32_bf16 v[36:39], v[160:163], v[194:197], v[36:39]
	v_mfma_f32_16x16x32_bf16 v[32:35], v[168:171], v[194:197], v[32:35]
	v_mfma_f32_16x16x32_bf16 v[20:23], v[160:163], v[206:209], v[20:23]
	v_mfma_f32_16x16x32_bf16 v[16:19], v[168:171], v[206:209], v[16:19]
	v_mfma_f32_16x16x32_bf16 v[4:7], v[160:163], v[214:217], v[4:7]
	v_mfma_f32_16x16x32_bf16 v[0:3], v[168:171], v[214:217], v[0:3]
	s_setprio 1
	s_barrier
	s_add_i32 s75, 0, 0x18000
	s_add_i32 s76, 0, 0x1c000
	v_add_u32_e32 v152, s75, v175
	v_add_u32_e32 v168, s76, v175
	ds_read_b128 v[140:143], v152
	ds_read_b128 v[144:147], v152 offset:1024
	ds_read_b128 v[148:151], v152 offset:2048
	ds_read_b128 v[152:155], v152 offset:3072
	ds_read_b128 v[156:159], v168
	ds_read_b128 v[160:163], v168 offset:1024
	ds_read_b128 v[164:167], v168 offset:2048
	ds_read_b128 v[168:171], v168 offset:3072
	s_add_u32 s62, s62, 0x40000
	s_addc_u32 s63, s63, 0
	s_mov_b32 m0, s30
	v_lshl_add_u64 v[222:223], s[62:63], 0, v[134:135]
	ds_read_b128 v[182:185], v179 offset:32768
	ds_read_b128 v[186:189], v179 offset:33792
	ds_read_b128 v[190:193], v179 offset:34816
	ds_read_b128 v[194:197], v179 offset:35840
	ds_read_b128 v[202:205], v179 offset:36864
	ds_read_b128 v[206:209], v179 offset:37888
	ds_read_b128 v[210:213], v179 offset:38912
	ds_read_b128 v[214:217], v179 offset:39936
	global_load_lds_dwordx4 v[222:223], off
	v_lshl_add_u64 v[222:223], s[62:63], 0, v[130:131]
	s_mov_b32 m0, s31
	s_nop 0
	global_load_lds_dwordx4 v[222:223], off
	s_waitcnt vmcnt(8)
	s_waitcnt lgkmcnt(0)
	s_barrier
	s_setprio 0
	s_waitcnt lgkmcnt(0)
	v_mfma_f32_16x16x32_bf16 v[124:127], v[140:143], v[182:185], v[124:127]
	v_mfma_f32_16x16x32_bf16 v[120:123], v[148:151], v[182:185], v[120:123]
	v_mfma_f32_16x16x32_bf16 v[108:111], v[140:143], v[190:193], v[108:111]
	v_mfma_f32_16x16x32_bf16 v[104:107], v[148:151], v[190:193], v[104:107]
	v_mfma_f32_16x16x32_bf16 v[92:95], v[140:143], v[202:205], v[92:95]
	v_mfma_f32_16x16x32_bf16 v[88:91], v[148:151], v[202:205], v[88:91]
	v_mfma_f32_16x16x32_bf16 v[76:79], v[140:143], v[210:213], v[76:79]
	v_mfma_f32_16x16x32_bf16 v[72:75], v[148:151], v[210:213], v[72:75]
	v_mfma_f32_16x16x32_bf16 v[124:127], v[144:147], v[186:189], v[124:127]
	v_mfma_f32_16x16x32_bf16 v[120:123], v[152:155], v[186:189], v[120:123]
	v_mfma_f32_16x16x32_bf16 v[108:111], v[144:147], v[194:197], v[108:111]
	v_mfma_f32_16x16x32_bf16 v[104:107], v[152:155], v[194:197], v[104:107]
	v_mfma_f32_16x16x32_bf16 v[92:95], v[144:147], v[206:209], v[92:95]
	v_mfma_f32_16x16x32_bf16 v[88:91], v[152:155], v[206:209], v[88:91]
	v_mfma_f32_16x16x32_bf16 v[76:79], v[144:147], v[214:217], v[76:79]
	v_mfma_f32_16x16x32_bf16 v[72:75], v[152:155], v[214:217], v[72:75]
	v_mfma_f32_16x16x32_bf16 v[116:119], v[156:159], v[182:185], v[116:119]
	v_mfma_f32_16x16x32_bf16 v[112:115], v[164:167], v[182:185], v[112:115]
	v_mfma_f32_16x16x32_bf16 v[100:103], v[156:159], v[190:193], v[100:103]
	v_mfma_f32_16x16x32_bf16 v[96:99], v[164:167], v[190:193], v[96:99]
	v_mfma_f32_16x16x32_bf16 v[84:87], v[156:159], v[202:205], v[84:87]
	v_mfma_f32_16x16x32_bf16 v[80:83], v[164:167], v[202:205], v[80:83]
	v_mfma_f32_16x16x32_bf16 v[68:71], v[156:159], v[210:213], v[68:71]
	v_mfma_f32_16x16x32_bf16 v[64:67], v[164:167], v[210:213], v[64:67]
	v_mfma_f32_16x16x32_bf16 v[116:119], v[160:163], v[186:189], v[116:119]
	v_mfma_f32_16x16x32_bf16 v[112:115], v[168:171], v[186:189], v[112:115]
	v_mfma_f32_16x16x32_bf16 v[100:103], v[160:163], v[194:197], v[100:103]
	v_mfma_f32_16x16x32_bf16 v[96:99], v[168:171], v[194:197], v[96:99]
	v_mfma_f32_16x16x32_bf16 v[84:87], v[160:163], v[206:209], v[84:87]
	v_mfma_f32_16x16x32_bf16 v[80:83], v[168:171], v[206:209], v[80:83]
	v_mfma_f32_16x16x32_bf16 v[68:71], v[160:163], v[214:217], v[68:71]
	v_mfma_f32_16x16x32_bf16 v[64:67], v[168:171], v[214:217], v[64:67]
	s_setprio 1
	s_barrier
; #define PG8_STAGE(bufoff, gbase, voff) do { _Pragma("unroll") for (int _i = 0; _i < 2; ++_i) \
;         __builtin_amdgcn_global_load_lds((const unsigned*)((const char*)(gbase) + (voff)[_i]), (PG8_LAS unsigned*)(lds + (bufoff) + ldsw + _i * 8192), 16, 0, 0); } while (0)
; #define PG8_LDA(dst, b, h) do { _Pragma("unroll") for (int m = 0; m < 4; ++m) _Pragma("unroll") for (int k = 0; k < 2; ++k) dst[m][k] = *(const PG8_LAS bf16x8*)(lds + PG8_SA(b, h) + aoff + m * 2048 + k * 1024); } while (0)
; #define PG8_MMA(ai, bj, At, Bt) do { __builtin_amdgcn_s_setprio(1); _Pragma("unroll") for (int m = 0; m < 4; ++m) _Pragma("unroll") for (int n = 0; n < 2; ++n) _Pragma("unroll") for (int k = 0; k < 2; ++k) \
;         acc[ai][bj][m][n] = __builtin_amdgcn_mfma_f32_16x16x32_bf16(Bt[n][k], At[m][k], acc[ai][bj][m][n], 0, 0, 0); __builtin_amdgcn_s_setprio(0); } while (0)
; #define PG8_WAIT_V(n) asm volatile("s_waitcnt vmcnt(" #n ")" ::: "memory")
; #define PG8_WAIT_L(n) asm volatile("s_waitcnt lgkmcnt(" #n ")" ::: "memory")
; #define PG8_BAR __builtin_amdgcn_s_barrier()
; #define PG8_SCHED __builtin_amdgcn_sched_barrier(0)
; template <class Epi, class Sched, bool ALIGN_EPI = false, bool SP2 = false>
; __device__ __forceinline__ void gemm_phase(PG8_LAS unsigned char* lds, const Gemm g, const Sched& S, const Epi& E) {
;     ...
;         for (int t = 0; t < nt; t += 2) {
;             const bool last = (t == nt - 2);
;             const char* a1 = cA + (size_t)(t + 1) * kstep;
;             const char* a2 = last ? nA : cA + (size_t)(t + 2) * kstep; const char* b2 = last ? nB : cB + (size_t)(t + 2) * kstep;
;     ...
;             PG8_LDA(At, 1, 1); PG8_STAGE(PG8_SB(1, 0), b3, voffB); PG8_STAGE(PG8_SB(1, 1), b3 + hstep, voffB); PG8_STAGE(PG8_SA(1, 0), a3, voffA);
;             PG8_WAIT_V(8); PG8_WAIT_L(0); PG8_BAR; PG8_MMA(1, 0, At, B0); PG8_MMA(1, 1, At, B1); PG8_BAR; PG8_SCHED;
	s_add_i32 s62, s75, s21
	v_lshl_add_u64 v[172:173], v[172:173], 0, s[36:37]
	s_mov_b32 m0, s62
	ds_read_b128 v[182:185], v179 offset:49152
	ds_read_b128 v[186:189], v179 offset:50176
	ds_read_b128 v[190:193], v179 offset:51200
	ds_read_b128 v[194:197], v179 offset:52224
	ds_read_b128 v[202:205], v179 offset:53248
	ds_read_b128 v[206:209], v179 offset:54272
	ds_read_b128 v[210:213], v179 offset:55296
	ds_read_b128 v[214:217], v179 offset:56320
	global_load_lds_dwordx4 v[172:173], off
	s_add_i32 m0, s62, 0x2000
	s_add_u32 s60, s60, 0x40080
	v_lshl_add_u64 v[172:173], v[198:199], 0, s[36:37]
	s_addc_u32 s61, s61, 0
	s_add_i32 s62, s76, s21
	global_load_lds_dwordx4 v[172:173], off
	v_lshl_add_u64 v[172:173], s[60:61], 0, v[132:133]
	s_mov_b32 m0, s62
	s_nop 0
	global_load_lds_dwordx4 v[172:173], off
	v_lshl_add_u64 v[172:173], s[60:61], 0, v[128:129]
	s_add_i32 m0, s62, 0x2000
	s_nop 0
	global_load_lds_dwordx4 v[172:173], off
	v_lshl_add_u64 v[172:173], v[218:219], 0, s[36:37]
	s_mov_b32 m0, s65
	s_nop 0
	global_load_lds_dwordx4 v[172:173], off
	v_lshl_add_u64 v[172:173], v[220:221], 0, s[36:37]
	s_mov_b32 m0, s66
	s_nop 0
	global_load_lds_dwordx4 v[172:173], off
	s_waitcnt vmcnt(8)
	s_waitcnt lgkmcnt(0)
	s_barrier
	s_setprio 0
	s_waitcnt lgkmcnt(0)
	v_mfma_f32_16x16x32_bf16 v[60:63], v[140:143], v[182:185], v[60:63]
	v_mfma_f32_16x16x32_bf16 v[56:59], v[148:151], v[182:185], v[56:59]
	v_mfma_f32_16x16x32_bf16 v[44:47], v[140:143], v[190:193], v[44:47]
	v_mfma_f32_16x16x32_bf16 v[40:43], v[148:151], v[190:193], v[40:43]
	v_mfma_f32_16x16x32_bf16 v[28:31], v[140:143], v[202:205], v[28:31]
	v_mfma_f32_16x16x32_bf16 v[24:27], v[148:151], v[202:205], v[24:27]
	v_mfma_f32_16x16x32_bf16 v[12:15], v[140:143], v[210:213], v[12:15]
	v_mfma_f32_16x16x32_bf16 v[8:11], v[148:151], v[210:213], v[8:11]
	v_mfma_f32_16x16x32_bf16 v[60:63], v[144:147], v[186:189], v[60:63]
	v_mfma_f32_16x16x32_bf16 v[56:59], v[152:155], v[186:189], v[56:59]
	v_mfma_f32_16x16x32_bf16 v[44:47], v[144:147], v[194:197], v[44:47]
	v_mfma_f32_16x16x32_bf16 v[40:43], v[152:155], v[194:197], v[40:43]
	v_mfma_f32_16x16x32_bf16 v[28:31], v[144:147], v[206:209], v[28:31]
	v_mfma_f32_16x16x32_bf16 v[24:27], v[152:155], v[206:209], v[24:27]
	v_mfma_f32_16x16x32_bf16 v[12:15], v[144:147], v[214:217], v[12:15]
	v_mfma_f32_16x16x32_bf16 v[8:11], v[152:155], v[214:217], v[8:11]
	v_mfma_f32_16x16x32_bf16 v[52:55], v[156:159], v[182:185], v[52:55]
	v_mfma_f32_16x16x32_bf16 v[48:51], v[164:167], v[182:185], v[48:51]
	v_mfma_f32_16x16x32_bf16 v[36:39], v[156:159], v[190:193], v[36:39]
	v_mfma_f32_16x16x32_bf16 v[32:35], v[164:167], v[190:193], v[32:35]
	v_mfma_f32_16x16x32_bf16 v[20:23], v[156:159], v[202:205], v[20:23]
	v_mfma_f32_16x16x32_bf16 v[16:19], v[164:167], v[202:205], v[16:19]
	v_mfma_f32_16x16x32_bf16 v[4:7], v[156:159], v[210:213], v[4:7]
	v_mfma_f32_16x16x32_bf16 v[0:3], v[164:167], v[210:213], v[0:3]
	v_mfma_f32_16x16x32_bf16 v[52:55], v[160:163], v[186:189], v[52:55]
	v_mfma_f32_16x16x32_bf16 v[48:51], v[168:171], v[186:189], v[48:51]
	v_mfma_f32_16x16x32_bf16 v[36:39], v[160:163], v[194:197], v[36:39]
	v_mfma_f32_16x16x32_bf16 v[32:35], v[168:171], v[194:197], v[32:35]
	v_mfma_f32_16x16x32_bf16 v[20:23], v[160:163], v[206:209], v[20:23]
	v_mfma_f32_16x16x32_bf16 v[16:19], v[168:171], v[206:209], v[16:19]
	v_mfma_f32_16x16x32_bf16 v[4:7], v[160:163], v[214:217], v[4:7]
	v_mfma_f32_16x16x32_bf16 v[0:3], v[168:171], v[214:217], v[0:3]
	s_setprio 1
	s_barrier
	s_add_i32 s74, s74, 2
	s_add_u32 s58, s58, 0x100
	s_addc_u32 s59, s59, 0
	s_add_u32 s72, s72, 0x100
	s_addc_u32 s73, s73, 0
	s_cmp_gt_u32 s74, 13
	s_cbranch_scc0 .LBB0_175
	s_and_b64 vcc, exec, s[38:39]
	s_cbranch_vccz .LBB0_178
	s_barrier

; #define PG8_STAGE(bufoff, gbase, voff) do { _Pragma("unroll") for (int _i = 0; _i < 2; ++_i) \
;         __builtin_amdgcn_global_load_lds((const unsigned*)((const char*)(gbase) + (voff)[_i]), (PG8_LAS unsigned*)(lds + (bufoff) + ldsw + _i * 8192), 16, 0, 0); } while (0)
; #define PG8_LDA(dst, b, h) do { _Pragma("unroll") for (int m = 0; m < 4; ++m) _Pragma("unroll") for (int k = 0; k < 2; ++k) dst[m][k] = *(const PG8_LAS bf16x8*)(lds + PG8_SA(b, h) + aoff + m * 2048 + k * 1024); } while (0)
; #define PG8_LDB(dst, b, h) do { _Pragma("unroll") for (int n = 0; n < 2; ++n) _Pragma("unroll") for (int k = 0; k < 2; ++k) dst[n][k] = *(const PG8_LAS bf16x8*)(lds + PG8_SB(b, h) + boff + n * 2048 + k * 1024); } while (0)
; #define PG8_MMA(ai, bj, At, Bt) do { __builtin_amdgcn_s_setprio(1); _Pragma("unroll") for (int m = 0; m < 4; ++m) _Pragma("unroll") for (int n = 0; n < 2; ++n) _Pragma("unroll") for (int k = 0; k < 2; ++k) \
;         acc[ai][bj][m][n] = __builtin_amdgcn_mfma_f32_16x16x32_bf16(Bt[n][k], At[m][k], acc[ai][bj][m][n], 0, 0, 0); __builtin_amdgcn_s_setprio(0); } while (0)
; #define PG8_WAIT_V(n) asm volatile("s_waitcnt vmcnt(" #n ")" ::: "memory")
; #define PG8_WAIT_L(n) asm volatile("s_waitcnt lgkmcnt(" #n ")" ::: "memory")
; #define PG8_BAR __builtin_amdgcn_s_barrier()
; #define PG8_SCHED __builtin_amdgcn_sched_barrier(0)
; template <class Epi, class Sched, bool ALIGN_EPI = false, bool SP2 = false>
; __device__ __forceinline__ void gemm_phase(PG8_LAS unsigned char* lds, const Gemm g, const Sched& S, const Epi& E) {
;     ...
;             PG8_LDB(B0, 0, 0); PG8_LDB(B1, 0, 1); PG8_SCHED; PG8_LDA(At, 0, 0); PG8_STAGE(PG8_SA(1, 1), a1 + hstep, voffA);
;             PG8_WAIT_V(8); PG8_WAIT_L(0); PG8_BAR; PG8_MMA(0, 0, At, B0); PG8_MMA(0, 1, At, B1); PG8_BAR; PG8_SCHED;
;             PG8_LDA(At, 0, 1); PG8_STAGE(PG8_SB(0, 0), b2, voffB); PG8_STAGE(PG8_SB(0, 1), b2 + hstep, voffB); PG8_STAGE(PG8_SA(0, 0), a2, voffA);
;             PG8_WAIT_V(8); PG8_WAIT_L(0); PG8_BAR; PG8_MMA(1, 0, At, B0); PG8_MMA(1, 1, At, B1); PG8_BAR; PG8_SCHED;
.LBB0_245:
	ds_read_b128 v[128:131], v156
	ds_read_b128 v[132:135], v156 offset:1024
	ds_read_b128 v[148:151], v156 offset:2048
	ds_read_b128 v[162:165], v156 offset:3072
	ds_read_b128 v[166:169], v157
	ds_read_b128 v[170:173], v157 offset:1024
	ds_read_b128 v[174:177], v157 offset:2048
	ds_read_b128 v[178:181], v157 offset:3072
	s_add_u32 s58, s56, 0xfff50080
	s_addc_u32 s59, s57, -1
	s_cmp_eq_u32 s85, 40
	s_cselect_b32 s61, s47, s59
	s_cselect_b32 s60, s46, s58
	s_cselect_b32 s59, s51, s84
	s_cselect_b32 s58, s50, s83
	s_mov_b32 m0, s71
	v_lshl_add_u64 v[152:153], s[56:57], 0, v[144:145]
	ds_read_b128 v[182:185], v158
	ds_read_b128 v[186:189], v158 offset:1024
	ds_read_b128 v[190:193], v158 offset:2048
	ds_read_b128 v[194:197], v158 offset:3072
	ds_read_b128 v[202:205], v158 offset:4096
	ds_read_b128 v[206:209], v158 offset:5120
	ds_read_b128 v[210:213], v158 offset:6144
	ds_read_b128 v[214:217], v158 offset:7168
	global_load_lds_dwordx4 v[152:153], off
	v_lshl_add_u64 v[152:153], s[56:57], 0, v[146:147]
	s_mov_b32 m0, s72
	s_nop 0
	global_load_lds_dwordx4 v[152:153], off
	s_waitcnt vmcnt(8)
	s_waitcnt lgkmcnt(0)
	s_barrier
	s_setprio 0
	s_waitcnt lgkmcnt(0)
	v_mfma_f32_16x16x32_bf16 v[124:127], v[128:131], v[182:185], v[124:127]
	v_mfma_f32_16x16x32_bf16 v[120:123], v[148:151], v[182:185], v[120:123]
	v_mfma_f32_16x16x32_bf16 v[108:111], v[128:131], v[190:193], v[108:111]
	v_mfma_f32_16x16x32_bf16 v[104:107], v[148:151], v[190:193], v[104:107]
	v_mfma_f32_16x16x32_bf16 v[92:95], v[128:131], v[202:205], v[92:95]
	v_mfma_f32_16x16x32_bf16 v[88:91], v[148:151], v[202:205], v[88:91]
	v_mfma_f32_16x16x32_bf16 v[76:79], v[128:131], v[210:213], v[76:79]
	v_mfma_f32_16x16x32_bf16 v[72:75], v[148:151], v[210:213], v[72:75]
	v_mfma_f32_16x16x32_bf16 v[124:127], v[132:135], v[186:189], v[124:127]
	v_mfma_f32_16x16x32_bf16 v[120:123], v[162:165], v[186:189], v[120:123]
	v_mfma_f32_16x16x32_bf16 v[108:111], v[132:135], v[194:197], v[108:111]
	v_mfma_f32_16x16x32_bf16 v[104:107], v[162:165], v[194:197], v[104:107]
	v_mfma_f32_16x16x32_bf16 v[92:95], v[132:135], v[206:209], v[92:95]
	v_mfma_f32_16x16x32_bf16 v[88:91], v[162:165], v[206:209], v[88:91]
	v_mfma_f32_16x16x32_bf16 v[76:79], v[132:135], v[214:217], v[76:79]
	v_mfma_f32_16x16x32_bf16 v[72:75], v[162:165], v[214:217], v[72:75]
	v_mfma_f32_16x16x32_bf16 v[116:119], v[166:169], v[182:185], v[116:119]
	v_mfma_f32_16x16x32_bf16 v[112:115], v[174:177], v[182:185], v[112:115]
	v_mfma_f32_16x16x32_bf16 v[100:103], v[166:169], v[190:193], v[100:103]
	v_mfma_f32_16x16x32_bf16 v[96:99], v[174:177], v[190:193], v[96:99]
	v_mfma_f32_16x16x32_bf16 v[84:87], v[166:169], v[202:205], v[84:87]
	v_mfma_f32_16x16x32_bf16 v[80:83], v[174:177], v[202:205], v[80:83]
	v_mfma_f32_16x16x32_bf16 v[68:71], v[166:169], v[210:213], v[68:71]
	v_mfma_f32_16x16x32_bf16 v[64:67], v[174:177], v[210:213], v[64:67]
	v_mfma_f32_16x16x32_bf16 v[116:119], v[170:173], v[186:189], v[116:119]
	v_mfma_f32_16x16x32_bf16 v[112:115], v[178:181], v[186:189], v[112:115]
	v_mfma_f32_16x16x32_bf16 v[100:103], v[170:173], v[194:197], v[100:103]
	v_mfma_f32_16x16x32_bf16 v[96:99], v[178:181], v[194:197], v[96:99]
	v_mfma_f32_16x16x32_bf16 v[84:87], v[170:173], v[206:209], v[84:87]
	v_mfma_f32_16x16x32_bf16 v[80:83], v[178:181], v[206:209], v[80:83]
	v_mfma_f32_16x16x32_bf16 v[68:71], v[170:173], v[214:217], v[68:71]
	v_mfma_f32_16x16x32_bf16 v[64:67], v[178:181], v[214:217], v[64:67]
	s_setprio 1
	s_barrier
	s_mov_b32 m0, s73
	v_lshl_add_u64 v[152:153], s[58:59], 0, v[138:139]
	s_add_u32 s86, s58, 0xb0000
	ds_read_b128 v[182:185], v158 offset:16384
	ds_read_b128 v[186:189], v158 offset:17408
	ds_read_b128 v[190:193], v158 offset:18432
	ds_read_b128 v[194:197], v158 offset:19456
	ds_read_b128 v[202:205], v158 offset:20480
	ds_read_b128 v[206:209], v158 offset:21504
	ds_read_b128 v[210:213], v158 offset:22528
	ds_read_b128 v[214:217], v158 offset:23552
	global_load_lds_dwordx4 v[152:153], off
	v_lshl_add_u64 v[198:199], s[58:59], 0, v[142:143]
	s_mov_b32 m0, s74
	s_addc_u32 s87, s59, 0
	global_load_lds_dwordx4 v[198:199], off
	v_lshl_add_u64 v[218:219], s[86:87], 0, v[138:139]
	s_mov_b32 m0, s75
	v_lshl_add_u64 v[220:221], s[60:61], 0, v[140:141]
	global_load_lds_dwordx4 v[218:219], off
	v_lshl_add_u64 v[218:219], s[86:87], 0, v[142:143]
	s_mov_b32 m0, s76
	s_nop 0
	global_load_lds_dwordx4 v[218:219], off
	v_lshl_add_u64 v[218:219], s[60:61], 0, v[136:137]
	s_mov_b32 m0, s28
	s_nop 0
	global_load_lds_dwordx4 v[218:219], off
	s_mov_b32 m0, s29
	s_nop 0
	global_load_lds_dwordx4 v[220:221], off
	s_waitcnt vmcnt(8)
	s_waitcnt lgkmcnt(0)
	s_barrier
; #define PG8_STAGE(bufoff, gbase, voff) do { _Pragma("unroll") for (int _i = 0; _i < 2; ++_i) \
;         __builtin_amdgcn_global_load_lds((const unsigned*)((const char*)(gbase) + (voff)[_i]), (PG8_LAS unsigned*)(lds + (bufoff) + ldsw + _i * 8192), 16, 0, 0); } while (0)
; #define PG8_LDA(dst, b, h) do { _Pragma("unroll") for (int m = 0; m < 4; ++m) _Pragma("unroll") for (int k = 0; k < 2; ++k) dst[m][k] = *(const PG8_LAS bf16x8*)(lds + PG8_SA(b, h) + aoff + m * 2048 + k * 1024); } while (0)
; #define PG8_LDB(dst, b, h) do { _Pragma("unroll") for (int n = 0; n < 2; ++n) _Pragma("unroll") for (int k = 0; k < 2; ++k) dst[n][k] = *(const PG8_LAS bf16x8*)(lds + PG8_SB(b, h) + boff + n * 2048 + k * 1024); } while (0)
; #define PG8_MMA(ai, bj, At, Bt) do { __builtin_amdgcn_s_setprio(1); _Pragma("unroll") for (int m = 0; m < 4; ++m) _Pragma("unroll") for (int n = 0; n < 2; ++n) _Pragma("unroll") for (int k = 0; k < 2; ++k) \
;         acc[ai][bj][m][n] = __builtin_amdgcn_mfma_f32_16x16x32_bf16(Bt[n][k], At[m][k], acc[ai][bj][m][n], 0, 0, 0); __builtin_amdgcn_s_setprio(0); } while (0)
; #define PG8_WAIT_V(n) asm volatile("s_waitcnt vmcnt(" #n ")" ::: "memory")
; #define PG8_WAIT_L(n) asm volatile("s_waitcnt lgkmcnt(" #n ")" ::: "memory")
; #define PG8_BAR __builtin_amdgcn_s_barrier()
; #define PG8_SCHED __builtin_amdgcn_sched_barrier(0)
; template <class Epi, class Sched, bool ALIGN_EPI = false, bool SP2 = false>
; __device__ __forceinline__ void gemm_phase(PG8_LAS unsigned char* lds, const Gemm g, const Sched& S, const Epi& E) {
;     ...
;             PG8_WAIT_V(8); PG8_WAIT_L(0); PG8_BAR; PG8_MMA(1, 0, At, B0); PG8_MMA(1, 1, At, B1); PG8_BAR; PG8_SCHED;
;             PG8_LDB(B0, 1, 0); PG8_LDB(B1, 1, 1); PG8_SCHED; PG8_LDA(At, 1, 0); PG8_STAGE(PG8_SA(0, 1), a2 + hstep, voffA);
;             PG8_WAIT_V(8); PG8_WAIT_L(0); PG8_BAR; PG8_MMA(0, 0, At, B0); PG8_MMA(0, 1, At, B1); PG8_BAR; PG8_SCHED;
	s_setprio 0
	s_waitcnt lgkmcnt(0)
	v_mfma_f32_16x16x32_bf16 v[60:63], v[128:131], v[182:185], v[60:63]
	v_mfma_f32_16x16x32_bf16 v[56:59], v[148:151], v[182:185], v[56:59]
	v_mfma_f32_16x16x32_bf16 v[44:47], v[128:131], v[190:193], v[44:47]
	v_mfma_f32_16x16x32_bf16 v[40:43], v[148:151], v[190:193], v[40:43]
	v_mfma_f32_16x16x32_bf16 v[32:35], v[128:131], v[202:205], v[32:35]
	v_mfma_f32_16x16x32_bf16 v[24:27], v[148:151], v[202:205], v[24:27]
	v_mfma_f32_16x16x32_bf16 v[16:19], v[128:131], v[210:213], v[16:19]
	v_mfma_f32_16x16x32_bf16 v[8:11], v[148:151], v[210:213], v[8:11]
	v_mfma_f32_16x16x32_bf16 v[60:63], v[132:135], v[186:189], v[60:63]
	v_mfma_f32_16x16x32_bf16 v[56:59], v[162:165], v[186:189], v[56:59]
	v_mfma_f32_16x16x32_bf16 v[44:47], v[132:135], v[194:197], v[44:47]
	v_mfma_f32_16x16x32_bf16 v[40:43], v[162:165], v[194:197], v[40:43]
	v_mfma_f32_16x16x32_bf16 v[32:35], v[132:135], v[206:209], v[32:35]
	v_mfma_f32_16x16x32_bf16 v[24:27], v[162:165], v[206:209], v[24:27]
	v_mfma_f32_16x16x32_bf16 v[16:19], v[132:135], v[214:217], v[16:19]
	v_mfma_f32_16x16x32_bf16 v[8:11], v[162:165], v[214:217], v[8:11]
	v_mfma_f32_16x16x32_bf16 v[52:55], v[166:169], v[182:185], v[52:55]
	v_mfma_f32_16x16x32_bf16 v[48:51], v[174:177], v[182:185], v[48:51]
	v_mfma_f32_16x16x32_bf16 v[36:39], v[166:169], v[190:193], v[36:39]
	v_mfma_f32_16x16x32_bf16 v[28:31], v[174:177], v[190:193], v[28:31]
	v_mfma_f32_16x16x32_bf16 v[20:23], v[166:169], v[202:205], v[20:23]
	v_mfma_f32_16x16x32_bf16 v[12:15], v[174:177], v[202:205], v[12:15]
	v_mfma_f32_16x16x32_bf16 v[4:7], v[166:169], v[210:213], v[4:7]
	v_mfma_f32_16x16x32_bf16 v[0:3], v[174:177], v[210:213], v[0:3]
	v_mfma_f32_16x16x32_bf16 v[52:55], v[170:173], v[186:189], v[52:55]
	v_mfma_f32_16x16x32_bf16 v[48:51], v[178:181], v[186:189], v[48:51]
	v_mfma_f32_16x16x32_bf16 v[36:39], v[170:173], v[194:197], v[36:39]
	v_mfma_f32_16x16x32_bf16 v[28:31], v[178:181], v[194:197], v[28:31]
	v_mfma_f32_16x16x32_bf16 v[20:23], v[170:173], v[206:209], v[20:23]
	v_mfma_f32_16x16x32_bf16 v[12:15], v[178:181], v[206:209], v[12:15]
	v_mfma_f32_16x16x32_bf16 v[4:7], v[170:173], v[214:217], v[4:7]
	v_mfma_f32_16x16x32_bf16 v[0:3], v[178:181], v[214:217], v[0:3]
	s_setprio 1
	s_barrier
	ds_read_b128 v[128:131], v160
	ds_read_b128 v[132:135], v160 offset:1024
	ds_read_b128 v[148:151], v160 offset:2048
	ds_read_b128 v[162:165], v160 offset:3072
	ds_read_b128 v[166:169], v161
	ds_read_b128 v[170:173], v161 offset:1024
	ds_read_b128 v[174:177], v161 offset:2048
	ds_read_b128 v[178:181], v161 offset:3072
	s_add_u32 s60, s60, 0xb0000
	s_addc_u32 s61, s61, 0
	s_mov_b32 m0, s30
	v_lshl_add_u64 v[222:223], s[60:61], 0, v[136:137]
	ds_read_b128 v[182:185], v158 offset:32768
	ds_read_b128 v[186:189], v158 offset:33792
	ds_read_b128 v[190:193], v158 offset:34816
	ds_read_b128 v[194:197], v158 offset:35840
	ds_read_b128 v[202:205], v158 offset:36864
	ds_read_b128 v[206:209], v158 offset:37888
	ds_read_b128 v[210:213], v158 offset:38912
	ds_read_b128 v[214:217], v158 offset:39936
	global_load_lds_dwordx4 v[222:223], off
	v_lshl_add_u64 v[222:223], s[60:61], 0, v[140:141]
	s_mov_b32 m0, s31
	s_nop 0
	global_load_lds_dwordx4 v[222:223], off
	s_waitcnt vmcnt(8)
	s_waitcnt lgkmcnt(0)
	s_barrier
	s_setprio 0
	s_waitcnt lgkmcnt(0)
	v_mfma_f32_16x16x32_bf16 v[124:127], v[128:131], v[182:185], v[124:127]
	v_mfma_f32_16x16x32_bf16 v[120:123], v[148:151], v[182:185], v[120:123]
	v_mfma_f32_16x16x32_bf16 v[108:111], v[128:131], v[190:193], v[108:111]
	v_mfma_f32_16x16x32_bf16 v[104:107], v[148:151], v[190:193], v[104:107]
	v_mfma_f32_16x16x32_bf16 v[92:95], v[128:131], v[202:205], v[92:95]
	v_mfma_f32_16x16x32_bf16 v[88:91], v[148:151], v[202:205], v[88:91]
	v_mfma_f32_16x16x32_bf16 v[76:79], v[128:131], v[210:213], v[76:79]
	v_mfma_f32_16x16x32_bf16 v[72:75], v[148:151], v[210:213], v[72:75]
	v_mfma_f32_16x16x32_bf16 v[124:127], v[132:135], v[186:189], v[124:127]
	v_mfma_f32_16x16x32_bf16 v[120:123], v[162:165], v[186:189], v[120:123]
	v_mfma_f32_16x16x32_bf16 v[108:111], v[132:135], v[194:197], v[108:111]
	v_mfma_f32_16x16x32_bf16 v[104:107], v[162:165], v[194:197], v[104:107]
	v_mfma_f32_16x16x32_bf16 v[92:95], v[132:135], v[206:209], v[92:95]
	v_mfma_f32_16x16x32_bf16 v[88:91], v[162:165], v[206:209], v[88:91]
	v_mfma_f32_16x16x32_bf16 v[76:79], v[132:135], v[214:217], v[76:79]
	v_mfma_f32_16x16x32_bf16 v[72:75], v[162:165], v[214:217], v[72:75]
	v_mfma_f32_16x16x32_bf16 v[116:119], v[166:169], v[182:185], v[116:119]
	v_mfma_f32_16x16x32_bf16 v[112:115], v[174:177], v[182:185], v[112:115]
	v_mfma_f32_16x16x32_bf16 v[100:103], v[166:169], v[190:193], v[100:103]
	v_mfma_f32_16x16x32_bf16 v[96:99], v[174:177], v[190:193], v[96:99]
	v_mfma_f32_16x16x32_bf16 v[84:87], v[166:169], v[202:205], v[84:87]
	v_mfma_f32_16x16x32_bf16 v[80:83], v[174:177], v[202:205], v[80:83]
	v_mfma_f32_16x16x32_bf16 v[68:71], v[166:169], v[210:213], v[68:71]
	v_mfma_f32_16x16x32_bf16 v[64:67], v[174:177], v[210:213], v[64:67]
	v_mfma_f32_16x16x32_bf16 v[116:119], v[170:173], v[186:189], v[116:119]
	v_mfma_f32_16x16x32_bf16 v[112:115], v[178:181], v[186:189], v[112:115]
	v_mfma_f32_16x16x32_bf16 v[100:103], v[170:173], v[194:197], v[100:103]
	v_mfma_f32_16x16x32_bf16 v[96:99], v[178:181], v[194:197], v[96:99]
	v_mfma_f32_16x16x32_bf16 v[84:87], v[170:173], v[206:209], v[84:87]
	v_mfma_f32_16x16x32_bf16 v[80:83], v[178:181], v[206:209], v[80:83]
	v_mfma_f32_16x16x32_bf16 v[68:71], v[170:173], v[214:217], v[68:71]
	v_mfma_f32_16x16x32_bf16 v[64:67], v[178:181], v[214:217], v[64:67]
	s_setprio 1
	s_barrier
; #define PG8_STAGE(bufoff, gbase, voff) do { _Pragma("unroll") for (int _i = 0; _i < 2; ++_i) \
;         __builtin_amdgcn_global_load_lds((const unsigned*)((const char*)(gbase) + (voff)[_i]), (PG8_LAS unsigned*)(lds + (bufoff) + ldsw + _i * 8192), 16, 0, 0); } while (0)
; #define PG8_LDA(dst, b, h) do { _Pragma("unroll") for (int m = 0; m < 4; ++m) _Pragma("unroll") for (int k = 0; k < 2; ++k) dst[m][k] = *(const PG8_LAS bf16x8*)(lds + PG8_SA(b, h) + aoff + m * 2048 + k * 1024); } while (0)
; #define PG8_MMA(ai, bj, At, Bt) do { __builtin_amdgcn_s_setprio(1); _Pragma("unroll") for (int m = 0; m < 4; ++m) _Pragma("unroll") for (int n = 0; n < 2; ++n) _Pragma("unroll") for (int k = 0; k < 2; ++k) \
;         acc[ai][bj][m][n] = __builtin_amdgcn_mfma_f32_16x16x32_bf16(Bt[n][k], At[m][k], acc[ai][bj][m][n], 0, 0, 0); __builtin_amdgcn_s_setprio(0); } while (0)
; #define PG8_WAIT_V(n) asm volatile("s_waitcnt vmcnt(" #n ")" ::: "memory")
; #define PG8_WAIT_L(n) asm volatile("s_waitcnt lgkmcnt(" #n ")" ::: "memory")
; #define PG8_BAR __builtin_amdgcn_s_barrier()
; #define PG8_SCHED __builtin_amdgcn_sched_barrier(0)
; template <class Epi, class Sched, bool ALIGN_EPI = false, bool SP2 = false>
; __device__ __forceinline__ void gemm_phase(PG8_LAS unsigned char* lds, const Gemm g, const Sched& S, const Epi& E) {
;     ...
;         for (int t = 0; t < nt; t += 2) {
;             const bool last = (t == nt - 2);
;             const char* a1 = cA + (size_t)(t + 1) * kstep;
;             const char* a2 = last ? nA : cA + (size_t)(t + 2) * kstep; const char* b2 = last ? nB : cB + (size_t)(t + 2) * kstep;
;     ...
;             PG8_LDA(At, 1, 1); PG8_STAGE(PG8_SB(1, 0), b3, voffB); PG8_STAGE(PG8_SB(1, 1), b3 + hstep, voffB); PG8_STAGE(PG8_SA(1, 0), a3, voffA);
;             PG8_WAIT_V(8); PG8_WAIT_L(0); PG8_BAR; PG8_MMA(1, 0, At, B0); PG8_MMA(1, 1, At, B1); PG8_BAR; PG8_SCHED;
	s_add_i32 s60, s77, s21
	v_lshl_add_u64 v[152:153], v[152:153], 0, s[40:41]
	s_mov_b32 m0, s60
	ds_read_b128 v[182:185], v158 offset:49152
	ds_read_b128 v[186:189], v158 offset:50176
	ds_read_b128 v[190:193], v158 offset:51200
	ds_read_b128 v[194:197], v158 offset:52224
	ds_read_b128 v[202:205], v158 offset:53248
	ds_read_b128 v[206:209], v158 offset:54272
	ds_read_b128 v[210:213], v158 offset:55296
	ds_read_b128 v[214:217], v158 offset:56320
	global_load_lds_dwordx4 v[152:153], off
	s_add_i32 m0, s60, 0x2000
	s_add_u32 s58, s58, 0xb0080
	v_lshl_add_u64 v[152:153], v[198:199], 0, s[40:41]
	s_addc_u32 s59, s59, 0
	s_add_i32 s60, s78, s21
	global_load_lds_dwordx4 v[152:153], off
	v_lshl_add_u64 v[152:153], s[58:59], 0, v[138:139]
	s_mov_b32 m0, s60
	s_nop 0
	global_load_lds_dwordx4 v[152:153], off
	v_lshl_add_u64 v[152:153], s[58:59], 0, v[142:143]
	s_add_i32 m0, s60, 0x2000
	s_nop 0
	global_load_lds_dwordx4 v[152:153], off
	v_lshl_add_u64 v[152:153], v[218:219], 0, s[40:41]
	s_mov_b32 m0, s64
	s_nop 0
	global_load_lds_dwordx4 v[152:153], off
	v_lshl_add_u64 v[152:153], v[220:221], 0, s[40:41]
	s_mov_b32 m0, s65
	s_nop 0
	global_load_lds_dwordx4 v[152:153], off
	s_waitcnt vmcnt(8)
	s_waitcnt lgkmcnt(0)
	s_barrier
	s_setprio 0
	s_waitcnt lgkmcnt(0)
	v_mfma_f32_16x16x32_bf16 v[60:63], v[128:131], v[182:185], v[60:63]
	v_mfma_f32_16x16x32_bf16 v[56:59], v[148:151], v[182:185], v[56:59]
	v_mfma_f32_16x16x32_bf16 v[44:47], v[128:131], v[190:193], v[44:47]
	v_mfma_f32_16x16x32_bf16 v[40:43], v[148:151], v[190:193], v[40:43]
	v_mfma_f32_16x16x32_bf16 v[32:35], v[128:131], v[202:205], v[32:35]
	v_mfma_f32_16x16x32_bf16 v[24:27], v[148:151], v[202:205], v[24:27]
	v_mfma_f32_16x16x32_bf16 v[16:19], v[128:131], v[210:213], v[16:19]
	v_mfma_f32_16x16x32_bf16 v[8:11], v[148:151], v[210:213], v[8:11]
	v_mfma_f32_16x16x32_bf16 v[60:63], v[132:135], v[186:189], v[60:63]
	v_mfma_f32_16x16x32_bf16 v[56:59], v[162:165], v[186:189], v[56:59]
	v_mfma_f32_16x16x32_bf16 v[44:47], v[132:135], v[194:197], v[44:47]
	v_mfma_f32_16x16x32_bf16 v[40:43], v[162:165], v[194:197], v[40:43]
	v_mfma_f32_16x16x32_bf16 v[32:35], v[132:135], v[206:209], v[32:35]
	v_mfma_f32_16x16x32_bf16 v[24:27], v[162:165], v[206:209], v[24:27]
	v_mfma_f32_16x16x32_bf16 v[16:19], v[132:135], v[214:217], v[16:19]
	v_mfma_f32_16x16x32_bf16 v[8:11], v[162:165], v[214:217], v[8:11]
	v_mfma_f32_16x16x32_bf16 v[52:55], v[166:169], v[182:185], v[52:55]
	v_mfma_f32_16x16x32_bf16 v[48:51], v[174:177], v[182:185], v[48:51]
	v_mfma_f32_16x16x32_bf16 v[36:39], v[166:169], v[190:193], v[36:39]
	v_mfma_f32_16x16x32_bf16 v[28:31], v[174:177], v[190:193], v[28:31]
	v_mfma_f32_16x16x32_bf16 v[20:23], v[166:169], v[202:205], v[20:23]
	v_mfma_f32_16x16x32_bf16 v[12:15], v[174:177], v[202:205], v[12:15]
	v_mfma_f32_16x16x32_bf16 v[4:7], v[166:169], v[210:213], v[4:7]
	v_mfma_f32_16x16x32_bf16 v[0:3], v[174:177], v[210:213], v[0:3]
	v_mfma_f32_16x16x32_bf16 v[52:55], v[170:173], v[186:189], v[52:55]
	v_mfma_f32_16x16x32_bf16 v[48:51], v[178:181], v[186:189], v[48:51]
	v_mfma_f32_16x16x32_bf16 v[36:39], v[170:173], v[194:197], v[36:39]
	v_mfma_f32_16x16x32_bf16 v[28:31], v[178:181], v[194:197], v[28:31]
	v_mfma_f32_16x16x32_bf16 v[20:23], v[170:173], v[206:209], v[20:23]
	v_mfma_f32_16x16x32_bf16 v[12:15], v[178:181], v[206:209], v[12:15]
	v_mfma_f32_16x16x32_bf16 v[4:7], v[170:173], v[214:217], v[4:7]
	v_mfma_f32_16x16x32_bf16 v[0:3], v[178:181], v[214:217], v[0:3]
	s_setprio 1
	s_barrier
	s_add_i32 s85, s85, 2
	s_add_u32 s56, s56, 0x100
	s_addc_u32 s57, s57, 0
	s_add_u32 s83, s83, 0x100
	s_addc_u32 s84, s84, 0
	s_cmp_gt_u32 s85, 41
	s_cbranch_scc0 .LBB0_245
	s_and_b64 vcc, exec, s[44:45]
	s_cbranch_vccz .LBB0_248
	s_barrier

; #define PG8_STAGE(bufoff, gbase, voff) do { _Pragma("unroll") for (int _i = 0; _i < 2; ++_i) \
;         __builtin_amdgcn_global_load_lds((const unsigned*)((const char*)(gbase) + (voff)[_i]), (PG8_LAS unsigned*)(lds + (bufoff) + ldsw + _i * 8192), 16, 0, 0); } while (0)
; #define PG8_LDA(dst, b, h) do { _Pragma("unroll") for (int m = 0; m < 4; ++m) _Pragma("unroll") for (int k = 0; k < 2; ++k) dst[m][k] = *(const PG8_LAS bf16x8*)(lds + PG8_SA(b, h) + aoff + m * 2048 + k * 1024); } while (0)
; #define PG8_LDB(dst, b, h) do { _Pragma("unroll") for (int n = 0; n < 2; ++n) _Pragma("unroll") for (int k = 0; k < 2; ++k) dst[n][k] = *(const PG8_LAS bf16x8*)(lds + PG8_SB(b, h) + boff + n * 2048 + k * 1024); } while (0)
; #define PG8_MMA(ai, bj, At, Bt) do { __builtin_amdgcn_s_setprio(1); _Pragma("unroll") for (int m = 0; m < 4; ++m) _Pragma("unroll") for (int n = 0; n < 2; ++n) _Pragma("unroll") for (int k = 0; k < 2; ++k) \
;         acc[ai][bj][m][n] = __builtin_amdgcn_mfma_f32_16x16x32_bf16(Bt[n][k], At[m][k], acc[ai][bj][m][n], 0, 0, 0); __builtin_amdgcn_s_setprio(0); } while (0)
; #define PG8_WAIT_V(n) asm volatile("s_waitcnt vmcnt(" #n ")" ::: "memory")
; #define PG8_WAIT_L(n) asm volatile("s_waitcnt lgkmcnt(" #n ")" ::: "memory")
; #define PG8_BAR __builtin_amdgcn_s_barrier()
; #define PG8_SCHED __builtin_amdgcn_sched_barrier(0)
; template <class Epi, class Sched, bool ALIGN_EPI = false, bool SP2 = false>
; __device__ __forceinline__ void gemm_phase(PG8_LAS unsigned char* lds, const Gemm g, const Sched& S, const Epi& E) {
;     ...
;             PG8_LDB(B0, 0, 0); PG8_LDB(B1, 0, 1); PG8_SCHED; PG8_LDA(At, 0, 0); PG8_STAGE(PG8_SA(1, 1), a1 + hstep, voffA);
;             PG8_WAIT_V(8); PG8_WAIT_L(0); PG8_BAR; PG8_MMA(0, 0, At, B0); PG8_MMA(0, 1, At, B1); PG8_BAR; PG8_SCHED;
;             PG8_LDA(At, 0, 1); PG8_STAGE(PG8_SB(0, 0), b2, voffB); PG8_STAGE(PG8_SB(0, 1), b2 + hstep, voffB); PG8_STAGE(PG8_SA(0, 0), a2, voffA);
;             PG8_WAIT_V(8); PG8_WAIT_L(0); PG8_BAR; PG8_MMA(1, 0, At, B0); PG8_MMA(1, 1, At, B1); PG8_BAR; PG8_SCHED;
.LBB0_325:
	ds_read_b128 v[140:143], v162
	ds_read_b128 v[144:147], v162 offset:1024
	ds_read_b128 v[148:151], v162 offset:2048
	ds_read_b128 v[152:155], v162 offset:3072
	ds_read_b128 v[168:171], v163
	ds_read_b128 v[172:175], v163 offset:1024
	ds_read_b128 v[176:179], v163 offset:2048
	ds_read_b128 v[180:183], v163 offset:3072
	s_add_u32 s74, s72, 0xfffc0080
	s_addc_u32 s75, s73, -1
	s_cmp_eq_u32 s84, 12
	s_cselect_b32 s77, s5, s75
	s_cselect_b32 s76, s61, s74
	s_cselect_b32 s75, s63, s83
	s_cselect_b32 s74, s71, s82
	v_lshl_add_u64 v[156:157], s[72:73], 0, v[136:137]
	s_add_i32 m0, s28, 0xc000
	ds_read_b128 v[184:187], v164
	ds_read_b128 v[188:191], v164 offset:1024
	ds_read_b128 v[192:195], v164 offset:2048
	ds_read_b128 v[196:199], v164 offset:3072
	ds_read_b128 v[202:205], v164 offset:4096
	ds_read_b128 v[206:209], v164 offset:5120
	ds_read_b128 v[210:213], v164 offset:6144
	ds_read_b128 v[214:217], v164 offset:7168
	global_load_lds_dwordx4 v[156:157], off
	v_lshl_add_u64 v[156:157], s[72:73], 0, v[138:139]
	s_add_i32 m0, s28, 0xe000
	s_nop 0
	global_load_lds_dwordx4 v[156:157], off
	s_waitcnt vmcnt(8)
	s_waitcnt lgkmcnt(0)
	s_barrier
	s_setprio 0
	s_waitcnt lgkmcnt(0)
	v_mfma_f32_16x16x32_bf16 v[124:127], v[140:143], v[184:187], v[124:127]
	v_mfma_f32_16x16x32_bf16 v[120:123], v[148:151], v[184:187], v[120:123]
	v_mfma_f32_16x16x32_bf16 v[108:111], v[140:143], v[192:195], v[108:111]
	v_mfma_f32_16x16x32_bf16 v[104:107], v[148:151], v[192:195], v[104:107]
	v_mfma_f32_16x16x32_bf16 v[92:95], v[140:143], v[202:205], v[92:95]
	v_mfma_f32_16x16x32_bf16 v[88:91], v[148:151], v[202:205], v[88:91]
	v_mfma_f32_16x16x32_bf16 v[76:79], v[140:143], v[210:213], v[76:79]
	v_mfma_f32_16x16x32_bf16 v[72:75], v[148:151], v[210:213], v[72:75]
	v_mfma_f32_16x16x32_bf16 v[124:127], v[144:147], v[188:191], v[124:127]
	v_mfma_f32_16x16x32_bf16 v[120:123], v[152:155], v[188:191], v[120:123]
	v_mfma_f32_16x16x32_bf16 v[108:111], v[144:147], v[196:199], v[108:111]
	v_mfma_f32_16x16x32_bf16 v[104:107], v[152:155], v[196:199], v[104:107]
	v_mfma_f32_16x16x32_bf16 v[92:95], v[144:147], v[206:209], v[92:95]
	v_mfma_f32_16x16x32_bf16 v[88:91], v[152:155], v[206:209], v[88:91]
	v_mfma_f32_16x16x32_bf16 v[76:79], v[144:147], v[214:217], v[76:79]
	v_mfma_f32_16x16x32_bf16 v[72:75], v[152:155], v[214:217], v[72:75]
	v_mfma_f32_16x16x32_bf16 v[116:119], v[168:171], v[184:187], v[116:119]
	v_mfma_f32_16x16x32_bf16 v[112:115], v[176:179], v[184:187], v[112:115]
	v_mfma_f32_16x16x32_bf16 v[100:103], v[168:171], v[192:195], v[100:103]
	v_mfma_f32_16x16x32_bf16 v[96:99], v[176:179], v[192:195], v[96:99]
	v_mfma_f32_16x16x32_bf16 v[84:87], v[168:171], v[202:205], v[84:87]
	v_mfma_f32_16x16x32_bf16 v[80:83], v[176:179], v[202:205], v[80:83]
	v_mfma_f32_16x16x32_bf16 v[68:71], v[168:171], v[210:213], v[68:71]
	v_mfma_f32_16x16x32_bf16 v[64:67], v[176:179], v[210:213], v[64:67]
	v_mfma_f32_16x16x32_bf16 v[116:119], v[172:175], v[188:191], v[116:119]
	v_mfma_f32_16x16x32_bf16 v[112:115], v[180:183], v[188:191], v[112:115]
	v_mfma_f32_16x16x32_bf16 v[100:103], v[172:175], v[196:199], v[100:103]
	v_mfma_f32_16x16x32_bf16 v[96:99], v[180:183], v[196:199], v[96:99]
	v_mfma_f32_16x16x32_bf16 v[84:87], v[172:175], v[206:209], v[84:87]
	v_mfma_f32_16x16x32_bf16 v[80:83], v[180:183], v[206:209], v[80:83]
	v_mfma_f32_16x16x32_bf16 v[68:71], v[172:175], v[214:217], v[68:71]
	v_mfma_f32_16x16x32_bf16 v[64:67], v[180:183], v[214:217], v[64:67]
	s_setprio 1
	s_barrier
	s_add_i32 s85, s79, s21
	v_lshl_add_u64 v[156:157], s[74:75], 0, v[130:131]
	s_mov_b32 m0, s85
	ds_read_b128 v[184:187], v164 offset:16384
	ds_read_b128 v[188:191], v164 offset:17408
	ds_read_b128 v[192:195], v164 offset:18432
	ds_read_b128 v[196:199], v164 offset:19456
	ds_read_b128 v[202:205], v164 offset:20480
	ds_read_b128 v[206:209], v164 offset:21504
	ds_read_b128 v[210:213], v164 offset:22528
	ds_read_b128 v[214:217], v164 offset:23552
	global_load_lds_dwordx4 v[156:157], off
	s_add_i32 m0, s85, 0x2000
	s_add_u32 s86, s74, 0x40000
	v_lshl_add_u64 v[218:219], s[74:75], 0, v[134:135]
	s_addc_u32 s87, s75, 0
	s_add_i32 s85, s80, s21
	global_load_lds_dwordx4 v[218:219], off
	v_lshl_add_u64 v[220:221], s[86:87], 0, v[130:131]
	s_mov_b32 m0, s85
	v_lshl_add_u64 v[222:223], s[76:77], 0, v[132:133]
	global_load_lds_dwordx4 v[220:221], off
	v_lshl_add_u64 v[220:221], s[86:87], 0, v[134:135]
	s_add_i32 m0, s85, 0x2000
	s_nop 0
	global_load_lds_dwordx4 v[220:221], off
	v_lshl_add_u64 v[220:221], s[76:77], 0, v[128:129]
	s_mov_b32 m0, s28
	s_nop 0
	global_load_lds_dwordx4 v[220:221], off
	s_mov_b32 m0, s29
	s_nop 0
	global_load_lds_dwordx4 v[222:223], off
	s_waitcnt vmcnt(8)
	s_waitcnt lgkmcnt(0)
	s_barrier
; #define PG8_STAGE(bufoff, gbase, voff) do { _Pragma("unroll") for (int _i = 0; _i < 2; ++_i) \
;         __builtin_amdgcn_global_load_lds((const unsigned*)((const char*)(gbase) + (voff)[_i]), (PG8_LAS unsigned*)(lds + (bufoff) + ldsw + _i * 8192), 16, 0, 0); } while (0)
; #define PG8_LDA(dst, b, h) do { _Pragma("unroll") for (int m = 0; m < 4; ++m) _Pragma("unroll") for (int k = 0; k < 2; ++k) dst[m][k] = *(const PG8_LAS bf16x8*)(lds + PG8_SA(b, h) + aoff + m * 2048 + k * 1024); } while (0)
; #define PG8_LDB(dst, b, h) do { _Pragma("unroll") for (int n = 0; n < 2; ++n) _Pragma("unroll") for (int k = 0; k < 2; ++k) dst[n][k] = *(const PG8_LAS bf16x8*)(lds + PG8_SB(b, h) + boff + n * 2048 + k * 1024); } while (0)
; #define PG8_MMA(ai, bj, At, Bt) do { __builtin_amdgcn_s_setprio(1); _Pragma("unroll") for (int m = 0; m < 4; ++m) _Pragma("unroll") for (int n = 0; n < 2; ++n) _Pragma("unroll") for (int k = 0; k < 2; ++k) \
;         acc[ai][bj][m][n] = __builtin_amdgcn_mfma_f32_16x16x32_bf16(Bt[n][k], At[m][k], acc[ai][bj][m][n], 0, 0, 0); __builtin_amdgcn_s_setprio(0); } while (0)
; #define PG8_WAIT_V(n) asm volatile("s_waitcnt vmcnt(" #n ")" ::: "memory")
; #define PG8_WAIT_L(n) asm volatile("s_waitcnt lgkmcnt(" #n ")" ::: "memory")
; #define PG8_BAR __builtin_amdgcn_s_barrier()
; #define PG8_SCHED __builtin_amdgcn_sched_barrier(0)
; template <class Epi, class Sched, bool ALIGN_EPI = false, bool SP2 = false>
; __device__ __forceinline__ void gemm_phase(PG8_LAS unsigned char* lds, const Gemm g, const Sched& S, const Epi& E) {
;     ...
;             PG8_WAIT_V(8); PG8_WAIT_L(0); PG8_BAR; PG8_MMA(1, 0, At, B0); PG8_MMA(1, 1, At, B1); PG8_BAR; PG8_SCHED;
;             PG8_LDB(B0, 1, 0); PG8_LDB(B1, 1, 1); PG8_SCHED; PG8_LDA(At, 1, 0); PG8_STAGE(PG8_SA(0, 1), a2 + hstep, voffA);
;             PG8_WAIT_V(8); PG8_WAIT_L(0); PG8_BAR; PG8_MMA(0, 0, At, B0); PG8_MMA(0, 1, At, B1); PG8_BAR; PG8_SCHED;
	s_setprio 0
	s_waitcnt lgkmcnt(0)
	v_mfma_f32_16x16x32_bf16 v[60:63], v[140:143], v[184:187], v[60:63]
	v_mfma_f32_16x16x32_bf16 v[56:59], v[148:151], v[184:187], v[56:59]
	v_mfma_f32_16x16x32_bf16 v[44:47], v[140:143], v[192:195], v[44:47]
	v_mfma_f32_16x16x32_bf16 v[40:43], v[148:151], v[192:195], v[40:43]
	v_mfma_f32_16x16x32_bf16 v[28:31], v[140:143], v[202:205], v[28:31]
	v_mfma_f32_16x16x32_bf16 v[24:27], v[148:151], v[202:205], v[24:27]
	v_mfma_f32_16x16x32_bf16 v[12:15], v[140:143], v[210:213], v[12:15]
	v_mfma_f32_16x16x32_bf16 v[8:11], v[148:151], v[210:213], v[8:11]
	v_mfma_f32_16x16x32_bf16 v[60:63], v[144:147], v[188:191], v[60:63]
	v_mfma_f32_16x16x32_bf16 v[56:59], v[152:155], v[188:191], v[56:59]
	v_mfma_f32_16x16x32_bf16 v[44:47], v[144:147], v[196:199], v[44:47]
	v_mfma_f32_16x16x32_bf16 v[40:43], v[152:155], v[196:199], v[40:43]
	v_mfma_f32_16x16x32_bf16 v[28:31], v[144:147], v[206:209], v[28:31]
	v_mfma_f32_16x16x32_bf16 v[24:27], v[152:155], v[206:209], v[24:27]
	v_mfma_f32_16x16x32_bf16 v[12:15], v[144:147], v[214:217], v[12:15]
	v_mfma_f32_16x16x32_bf16 v[8:11], v[152:155], v[214:217], v[8:11]
	v_mfma_f32_16x16x32_bf16 v[52:55], v[168:171], v[184:187], v[52:55]
	v_mfma_f32_16x16x32_bf16 v[48:51], v[176:179], v[184:187], v[48:51]
	v_mfma_f32_16x16x32_bf16 v[36:39], v[168:171], v[192:195], v[36:39]
	v_mfma_f32_16x16x32_bf16 v[32:35], v[176:179], v[192:195], v[32:35]
	v_mfma_f32_16x16x32_bf16 v[20:23], v[168:171], v[202:205], v[20:23]
	v_mfma_f32_16x16x32_bf16 v[16:19], v[176:179], v[202:205], v[16:19]
	v_mfma_f32_16x16x32_bf16 v[4:7], v[168:171], v[210:213], v[4:7]
	v_mfma_f32_16x16x32_bf16 v[0:3], v[176:179], v[210:213], v[0:3]
	v_mfma_f32_16x16x32_bf16 v[52:55], v[172:175], v[188:191], v[52:55]
	v_mfma_f32_16x16x32_bf16 v[48:51], v[180:183], v[188:191], v[48:51]
	v_mfma_f32_16x16x32_bf16 v[36:39], v[172:175], v[196:199], v[36:39]
	v_mfma_f32_16x16x32_bf16 v[32:35], v[180:183], v[196:199], v[32:35]
	v_mfma_f32_16x16x32_bf16 v[20:23], v[172:175], v[206:209], v[20:23]
	v_mfma_f32_16x16x32_bf16 v[16:19], v[180:183], v[206:209], v[16:19]
	v_mfma_f32_16x16x32_bf16 v[4:7], v[172:175], v[214:217], v[4:7]
	v_mfma_f32_16x16x32_bf16 v[0:3], v[180:183], v[214:217], v[0:3]
	s_setprio 1
	s_barrier
	s_add_i32 s85, 0, 0x18000
	s_add_i32 s86, 0, 0x1c000
	v_add_u32_e32 v152, s85, v160
	v_add_u32_e32 v167, s86, v160
	ds_read_b128 v[140:143], v152
	ds_read_b128 v[144:147], v152 offset:1024
	ds_read_b128 v[148:151], v152 offset:2048
	ds_read_b128 v[152:155], v152 offset:3072
	ds_read_b128 v[168:171], v167
	ds_read_b128 v[172:175], v167 offset:1024
	ds_read_b128 v[176:179], v167 offset:2048
	ds_read_b128 v[180:183], v167 offset:3072
	s_add_u32 s76, s76, 0x40000
	s_addc_u32 s77, s77, 0
	s_mov_b32 m0, s30
	v_lshl_add_u64 v[224:225], s[76:77], 0, v[128:129]
	ds_read_b128 v[184:187], v164 offset:32768
	ds_read_b128 v[188:191], v164 offset:33792
	ds_read_b128 v[192:195], v164 offset:34816
	ds_read_b128 v[196:199], v164 offset:35840
	ds_read_b128 v[202:205], v164 offset:36864
	ds_read_b128 v[206:209], v164 offset:37888
	ds_read_b128 v[210:213], v164 offset:38912
	ds_read_b128 v[214:217], v164 offset:39936
	global_load_lds_dwordx4 v[224:225], off
	v_lshl_add_u64 v[224:225], s[76:77], 0, v[132:133]
	s_mov_b32 m0, s31
	s_nop 0
	global_load_lds_dwordx4 v[224:225], off
	s_waitcnt vmcnt(8)
	s_waitcnt lgkmcnt(0)
	s_barrier
	s_setprio 0
	s_waitcnt lgkmcnt(0)
	v_mfma_f32_16x16x32_bf16 v[124:127], v[140:143], v[184:187], v[124:127]
	v_mfma_f32_16x16x32_bf16 v[120:123], v[148:151], v[184:187], v[120:123]
	v_mfma_f32_16x16x32_bf16 v[108:111], v[140:143], v[192:195], v[108:111]
	v_mfma_f32_16x16x32_bf16 v[104:107], v[148:151], v[192:195], v[104:107]
	v_mfma_f32_16x16x32_bf16 v[92:95], v[140:143], v[202:205], v[92:95]
	v_mfma_f32_16x16x32_bf16 v[88:91], v[148:151], v[202:205], v[88:91]
	v_mfma_f32_16x16x32_bf16 v[76:79], v[140:143], v[210:213], v[76:79]
	v_mfma_f32_16x16x32_bf16 v[72:75], v[148:151], v[210:213], v[72:75]
	v_mfma_f32_16x16x32_bf16 v[124:127], v[144:147], v[188:191], v[124:127]
	v_mfma_f32_16x16x32_bf16 v[120:123], v[152:155], v[188:191], v[120:123]
	v_mfma_f32_16x16x32_bf16 v[108:111], v[144:147], v[196:199], v[108:111]
	v_mfma_f32_16x16x32_bf16 v[104:107], v[152:155], v[196:199], v[104:107]
	v_mfma_f32_16x16x32_bf16 v[92:95], v[144:147], v[206:209], v[92:95]
	v_mfma_f32_16x16x32_bf16 v[88:91], v[152:155], v[206:209], v[88:91]
	v_mfma_f32_16x16x32_bf16 v[76:79], v[144:147], v[214:217], v[76:79]
	v_mfma_f32_16x16x32_bf16 v[72:75], v[152:155], v[214:217], v[72:75]
	v_mfma_f32_16x16x32_bf16 v[116:119], v[168:171], v[184:187], v[116:119]
	v_mfma_f32_16x16x32_bf16 v[112:115], v[176:179], v[184:187], v[112:115]
	v_mfma_f32_16x16x32_bf16 v[100:103], v[168:171], v[192:195], v[100:103]
	v_mfma_f32_16x16x32_bf16 v[96:99], v[176:179], v[192:195], v[96:99]
	v_mfma_f32_16x16x32_bf16 v[84:87], v[168:171], v[202:205], v[84:87]
	v_mfma_f32_16x16x32_bf16 v[80:83], v[176:179], v[202:205], v[80:83]
	v_mfma_f32_16x16x32_bf16 v[68:71], v[168:171], v[210:213], v[68:71]
	v_mfma_f32_16x16x32_bf16 v[64:67], v[176:179], v[210:213], v[64:67]
	v_mfma_f32_16x16x32_bf16 v[116:119], v[172:175], v[188:191], v[116:119]
	v_mfma_f32_16x16x32_bf16 v[112:115], v[180:183], v[188:191], v[112:115]
	v_mfma_f32_16x16x32_bf16 v[100:103], v[172:175], v[196:199], v[100:103]
	v_mfma_f32_16x16x32_bf16 v[96:99], v[180:183], v[196:199], v[96:99]
	v_mfma_f32_16x16x32_bf16 v[84:87], v[172:175], v[206:209], v[84:87]
	v_mfma_f32_16x16x32_bf16 v[80:83], v[180:183], v[206:209], v[80:83]
	v_mfma_f32_16x16x32_bf16 v[68:71], v[172:175], v[214:217], v[68:71]
	v_mfma_f32_16x16x32_bf16 v[64:67], v[180:183], v[214:217], v[64:67]
	s_setprio 1
	s_barrier
; #define PG8_STAGE(bufoff, gbase, voff) do { _Pragma("unroll") for (int _i = 0; _i < 2; ++_i) \
;         __builtin_amdgcn_global_load_lds((const unsigned*)((const char*)(gbase) + (voff)[_i]), (PG8_LAS unsigned*)(lds + (bufoff) + ldsw + _i * 8192), 16, 0, 0); } while (0)
; #define PG8_LDA(dst, b, h) do { _Pragma("unroll") for (int m = 0; m < 4; ++m) _Pragma("unroll") for (int k = 0; k < 2; ++k) dst[m][k] = *(const PG8_LAS bf16x8*)(lds + PG8_SA(b, h) + aoff + m * 2048 + k * 1024); } while (0)
; #define PG8_MMA(ai, bj, At, Bt) do { __builtin_amdgcn_s_setprio(1); _Pragma("unroll") for (int m = 0; m < 4; ++m) _Pragma("unroll") for (int n = 0; n < 2; ++n) _Pragma("unroll") for (int k = 0; k < 2; ++k) \
;         acc[ai][bj][m][n] = __builtin_amdgcn_mfma_f32_16x16x32_bf16(Bt[n][k], At[m][k], acc[ai][bj][m][n], 0, 0, 0); __builtin_amdgcn_s_setprio(0); } while (0)
; #define PG8_WAIT_V(n) asm volatile("s_waitcnt vmcnt(" #n ")" ::: "memory")
; #define PG8_WAIT_L(n) asm volatile("s_waitcnt lgkmcnt(" #n ")" ::: "memory")
; #define PG8_BAR __builtin_amdgcn_s_barrier()
; #define PG8_SCHED __builtin_amdgcn_sched_barrier(0)
; template <class Epi, class Sched, bool ALIGN_EPI = false, bool SP2 = false>
; __device__ __forceinline__ void gemm_phase(PG8_LAS unsigned char* lds, const Gemm g, const Sched& S, const Epi& E) {
;     ...
;         for (int t = 0; t < nt; t += 2) {
;             const bool last = (t == nt - 2);
;             const char* a1 = cA + (size_t)(t + 1) * kstep;
;             const char* a2 = last ? nA : cA + (size_t)(t + 2) * kstep; const char* b2 = last ? nB : cB + (size_t)(t + 2) * kstep;
;     ...
;             PG8_LDA(At, 1, 1); PG8_STAGE(PG8_SB(1, 0), b3, voffB); PG8_STAGE(PG8_SB(1, 1), b3 + hstep, voffB); PG8_STAGE(PG8_SA(1, 0), a3, voffA);
;             PG8_WAIT_V(8); PG8_WAIT_L(0); PG8_BAR; PG8_MMA(1, 0, At, B0); PG8_MMA(1, 1, At, B1); PG8_BAR; PG8_SCHED;
	s_add_i32 s76, s85, s21
	v_lshl_add_u64 v[156:157], v[156:157], 0, s[56:57]
	s_mov_b32 m0, s76
	ds_read_b128 v[184:187], v164 offset:49152
	ds_read_b128 v[188:191], v164 offset:50176
	ds_read_b128 v[192:195], v164 offset:51200
	ds_read_b128 v[196:199], v164 offset:52224
	ds_read_b128 v[202:205], v164 offset:53248
	ds_read_b128 v[206:209], v164 offset:54272
	ds_read_b128 v[210:213], v164 offset:55296
	ds_read_b128 v[214:217], v164 offset:56320
	global_load_lds_dwordx4 v[156:157], off
	s_add_i32 m0, s76, 0x2000
	s_add_u32 s74, s74, 0x40080
	v_lshl_add_u64 v[156:157], v[218:219], 0, s[56:57]
	s_addc_u32 s75, s75, 0
	s_add_i32 s76, s86, s21
	global_load_lds_dwordx4 v[156:157], off
	v_lshl_add_u64 v[156:157], s[74:75], 0, v[130:131]
	s_mov_b32 m0, s76
	s_nop 0
	global_load_lds_dwordx4 v[156:157], off
	v_lshl_add_u64 v[156:157], s[74:75], 0, v[134:135]
	s_add_i32 m0, s76, 0x2000
	s_nop 0
	global_load_lds_dwordx4 v[156:157], off
	v_lshl_add_u64 v[156:157], v[220:221], 0, s[56:57]
	s_mov_b32 m0, s39
	s_nop 0
	global_load_lds_dwordx4 v[156:157], off
	v_lshl_add_u64 v[156:157], v[222:223], 0, s[56:57]
	s_mov_b32 m0, s78
	s_nop 0
	global_load_lds_dwordx4 v[156:157], off
	s_waitcnt vmcnt(8)
	s_waitcnt lgkmcnt(0)
	s_barrier
	s_setprio 0
	s_waitcnt lgkmcnt(0)
	v_mfma_f32_16x16x32_bf16 v[60:63], v[140:143], v[184:187], v[60:63]
	v_mfma_f32_16x16x32_bf16 v[56:59], v[148:151], v[184:187], v[56:59]
	v_mfma_f32_16x16x32_bf16 v[44:47], v[140:143], v[192:195], v[44:47]
	v_mfma_f32_16x16x32_bf16 v[40:43], v[148:151], v[192:195], v[40:43]
	v_mfma_f32_16x16x32_bf16 v[28:31], v[140:143], v[202:205], v[28:31]
	v_mfma_f32_16x16x32_bf16 v[24:27], v[148:151], v[202:205], v[24:27]
	v_mfma_f32_16x16x32_bf16 v[12:15], v[140:143], v[210:213], v[12:15]
	v_mfma_f32_16x16x32_bf16 v[8:11], v[148:151], v[210:213], v[8:11]
	v_mfma_f32_16x16x32_bf16 v[60:63], v[144:147], v[188:191], v[60:63]
	v_mfma_f32_16x16x32_bf16 v[56:59], v[152:155], v[188:191], v[56:59]
	v_mfma_f32_16x16x32_bf16 v[44:47], v[144:147], v[196:199], v[44:47]
	v_mfma_f32_16x16x32_bf16 v[40:43], v[152:155], v[196:199], v[40:43]
	v_mfma_f32_16x16x32_bf16 v[28:31], v[144:147], v[206:209], v[28:31]
	v_mfma_f32_16x16x32_bf16 v[24:27], v[152:155], v[206:209], v[24:27]
	v_mfma_f32_16x16x32_bf16 v[12:15], v[144:147], v[214:217], v[12:15]
	v_mfma_f32_16x16x32_bf16 v[8:11], v[152:155], v[214:217], v[8:11]
	v_mfma_f32_16x16x32_bf16 v[52:55], v[168:171], v[184:187], v[52:55]
	v_mfma_f32_16x16x32_bf16 v[48:51], v[176:179], v[184:187], v[48:51]
	v_mfma_f32_16x16x32_bf16 v[36:39], v[168:171], v[192:195], v[36:39]
	v_mfma_f32_16x16x32_bf16 v[32:35], v[176:179], v[192:195], v[32:35]
	v_mfma_f32_16x16x32_bf16 v[20:23], v[168:171], v[202:205], v[20:23]
	v_mfma_f32_16x16x32_bf16 v[16:19], v[176:179], v[202:205], v[16:19]
	v_mfma_f32_16x16x32_bf16 v[4:7], v[168:171], v[210:213], v[4:7]
	v_mfma_f32_16x16x32_bf16 v[0:3], v[176:179], v[210:213], v[0:3]
	v_mfma_f32_16x16x32_bf16 v[52:55], v[172:175], v[188:191], v[52:55]
	v_mfma_f32_16x16x32_bf16 v[48:51], v[180:183], v[188:191], v[48:51]
	v_mfma_f32_16x16x32_bf16 v[36:39], v[172:175], v[196:199], v[36:39]
	v_mfma_f32_16x16x32_bf16 v[32:35], v[180:183], v[196:199], v[32:35]
	v_mfma_f32_16x16x32_bf16 v[20:23], v[172:175], v[206:209], v[20:23]
	v_mfma_f32_16x16x32_bf16 v[16:19], v[180:183], v[206:209], v[16:19]
	v_mfma_f32_16x16x32_bf16 v[4:7], v[172:175], v[214:217], v[4:7]
	v_mfma_f32_16x16x32_bf16 v[0:3], v[180:183], v[214:217], v[0:3]
	s_setprio 1
	s_barrier
	s_add_i32 s84, s84, 2
	s_add_u32 s72, s72, 0x100
	s_addc_u32 s73, s73, 0
	s_add_u32 s82, s82, 0x100
	s_addc_u32 s83, s83, 0
	s_cmp_gt_u32 s84, 13
	s_cbranch_scc0 .LBB0_325
	s_and_b64 vcc, exec, s[58:59]
	s_cbranch_vccz .LBB0_328
	s_barrier

; #define PG8_STAGE(bufoff, gbase, voff) do { _Pragma("unroll") for (int _i = 0; _i < 2; ++_i) \
;         __builtin_amdgcn_global_load_lds((const unsigned*)((const char*)(gbase) + (voff)[_i]), (PG8_LAS unsigned*)(lds + (bufoff) + ldsw + _i * 8192), 16, 0, 0); } while (0)
; #define PG8_LDA(dst, b, h) do { _Pragma("unroll") for (int m = 0; m < 4; ++m) _Pragma("unroll") for (int k = 0; k < 2; ++k) dst[m][k] = *(const PG8_LAS bf16x8*)(lds + PG8_SA(b, h) + aoff + m * 2048 + k * 1024); } while (0)
; #define PG8_LDB(dst, b, h) do { _Pragma("unroll") for (int n = 0; n < 2; ++n) _Pragma("unroll") for (int k = 0; k < 2; ++k) dst[n][k] = *(const PG8_LAS bf16x8*)(lds + PG8_SB(b, h) + boff + n * 2048 + k * 1024); } while (0)
; #define PG8_MMA(ai, bj, At, Bt) do { __builtin_amdgcn_s_setprio(1); _Pragma("unroll") for (int m = 0; m < 4; ++m) _Pragma("unroll") for (int n = 0; n < 2; ++n) _Pragma("unroll") for (int k = 0; k < 2; ++k) \
;         acc[ai][bj][m][n] = __builtin_amdgcn_mfma_f32_16x16x32_bf16(Bt[n][k], At[m][k], acc[ai][bj][m][n], 0, 0, 0); __builtin_amdgcn_s_setprio(0); } while (0)
; #define PG8_WAIT_V(n) asm volatile("s_waitcnt vmcnt(" #n ")" ::: "memory")
; #define PG8_WAIT_L(n) asm volatile("s_waitcnt lgkmcnt(" #n ")" ::: "memory")
; #define PG8_BAR __builtin_amdgcn_s_barrier()
; #define PG8_SCHED __builtin_amdgcn_sched_barrier(0)
; template <class Epi, class Sched, bool ALIGN_EPI = false, bool SP2 = false>
; __device__ __forceinline__ void gemm_phase(PG8_LAS unsigned char* lds, const Gemm g, const Sched& S, const Epi& E) {
;     ...
;             PG8_LDB(B0, 0, 0); PG8_LDB(B1, 0, 1); PG8_SCHED; PG8_LDA(At, 0, 0); PG8_STAGE(PG8_SA(1, 1), a1 + hstep, voffA);
;             PG8_WAIT_V(8); PG8_WAIT_L(0); PG8_BAR; PG8_MMA(0, 0, At, B0); PG8_MMA(0, 1, At, B1); PG8_BAR; PG8_SCHED;
;             PG8_LDA(At, 0, 1); PG8_STAGE(PG8_SB(0, 0), b2, voffB); PG8_STAGE(PG8_SB(0, 1), b2 + hstep, voffB); PG8_STAGE(PG8_SA(0, 0), a2, voffA);
;             PG8_WAIT_V(8); PG8_WAIT_L(0); PG8_BAR; PG8_MMA(1, 0, At, B0); PG8_MMA(1, 1, At, B1); PG8_BAR; PG8_SCHED;
.LBB0_582:
	ds_read_b128 v[128:131], v168
	ds_read_b128 v[132:135], v168 offset:1024
	ds_read_b128 v[136:139], v168 offset:2048
	ds_read_b128 v[140:143], v168 offset:3072
	ds_read_b128 v[158:161], v169
	ds_read_b128 v[162:165], v169 offset:1024
	ds_read_b128 v[172:175], v169 offset:2048
	ds_read_b128 v[176:179], v169 offset:3072
	s_add_u32 s58, s84, 0xfffc0080
	s_addc_u32 s59, s85, -1
	s_cmp_eq_u32 s91, 12
	s_cselect_b32 s89, s56, s59
	s_cselect_b32 s88, s57, s58
	s_cselect_b32 s87, s71, s90
	s_cselect_b32 s86, s73, s81
	v_lshl_add_u64 v[218:219], s[84:85], 0, v[154:155]
	s_add_i32 m0, s29, 0xc000
	ds_read_b128 v[180:183], v170
	ds_read_b128 v[184:187], v170 offset:1024
	ds_read_b128 v[188:191], v170 offset:2048
	ds_read_b128 v[192:195], v170 offset:3072
	ds_read_b128 v[196:199], v170 offset:4096
	ds_read_b128 v[206:209], v170 offset:5120
	ds_read_b128 v[210:213], v170 offset:6144
	ds_read_b128 v[214:217], v170 offset:7168
	global_load_lds_dwordx4 v[218:219], off
	v_lshl_add_u64 v[218:219], s[84:85], 0, v[156:157]
	s_add_i32 m0, s29, 0xe000
	s_nop 0
	global_load_lds_dwordx4 v[218:219], off
	s_waitcnt vmcnt(8)
	s_waitcnt lgkmcnt(0)
	s_barrier
	s_setprio 0
	s_waitcnt lgkmcnt(0)
	v_mfma_f32_16x16x32_bf16 v[124:127], v[128:131], v[180:183], v[124:127]
	v_mfma_f32_16x16x32_bf16 v[120:123], v[136:139], v[180:183], v[120:123]
	v_mfma_f32_16x16x32_bf16 v[108:111], v[128:131], v[188:191], v[108:111]
	v_mfma_f32_16x16x32_bf16 v[104:107], v[136:139], v[188:191], v[104:107]
	v_mfma_f32_16x16x32_bf16 v[96:99], v[128:131], v[196:199], v[96:99]
	v_mfma_f32_16x16x32_bf16 v[88:91], v[136:139], v[196:199], v[88:91]
	v_mfma_f32_16x16x32_bf16 v[80:83], v[128:131], v[210:213], v[80:83]
	v_mfma_f32_16x16x32_bf16 v[72:75], v[136:139], v[210:213], v[72:75]
	v_mfma_f32_16x16x32_bf16 v[124:127], v[132:135], v[184:187], v[124:127]
	v_mfma_f32_16x16x32_bf16 v[120:123], v[140:143], v[184:187], v[120:123]
	v_mfma_f32_16x16x32_bf16 v[108:111], v[132:135], v[192:195], v[108:111]
	v_mfma_f32_16x16x32_bf16 v[104:107], v[140:143], v[192:195], v[104:107]
	v_mfma_f32_16x16x32_bf16 v[96:99], v[132:135], v[206:209], v[96:99]
	v_mfma_f32_16x16x32_bf16 v[88:91], v[140:143], v[206:209], v[88:91]
	v_mfma_f32_16x16x32_bf16 v[80:83], v[132:135], v[214:217], v[80:83]
	v_mfma_f32_16x16x32_bf16 v[72:75], v[140:143], v[214:217], v[72:75]
	v_mfma_f32_16x16x32_bf16 v[116:119], v[158:161], v[180:183], v[116:119]
	v_mfma_f32_16x16x32_bf16 v[112:115], v[172:175], v[180:183], v[112:115]
	v_mfma_f32_16x16x32_bf16 v[100:103], v[158:161], v[188:191], v[100:103]
	v_mfma_f32_16x16x32_bf16 v[92:95], v[172:175], v[188:191], v[92:95]
	v_mfma_f32_16x16x32_bf16 v[84:87], v[158:161], v[196:199], v[84:87]
	v_mfma_f32_16x16x32_bf16 v[76:79], v[172:175], v[196:199], v[76:79]
	v_mfma_f32_16x16x32_bf16 v[68:71], v[158:161], v[210:213], v[68:71]
	v_mfma_f32_16x16x32_bf16 v[64:67], v[172:175], v[210:213], v[64:67]
	v_mfma_f32_16x16x32_bf16 v[116:119], v[162:165], v[184:187], v[116:119]
	v_mfma_f32_16x16x32_bf16 v[112:115], v[176:179], v[184:187], v[112:115]
	v_mfma_f32_16x16x32_bf16 v[100:103], v[162:165], v[192:195], v[100:103]
	v_mfma_f32_16x16x32_bf16 v[92:95], v[176:179], v[192:195], v[92:95]
	v_mfma_f32_16x16x32_bf16 v[84:87], v[162:165], v[206:209], v[84:87]
	v_mfma_f32_16x16x32_bf16 v[76:79], v[176:179], v[206:209], v[76:79]
	v_mfma_f32_16x16x32_bf16 v[68:71], v[162:165], v[214:217], v[68:71]
	v_mfma_f32_16x16x32_bf16 v[64:67], v[176:179], v[214:217], v[64:67]
	s_setprio 1
	s_barrier
	s_add_i32 s58, s11, s28
	v_lshl_add_u64 v[218:219], s[86:87], 0, v[148:149]
	s_mov_b32 m0, s58
	ds_read_b128 v[180:183], v170 offset:16384
	ds_read_b128 v[184:187], v170 offset:17408
	ds_read_b128 v[188:191], v170 offset:18432
	ds_read_b128 v[192:195], v170 offset:19456
	ds_read_b128 v[196:199], v170 offset:20480
	ds_read_b128 v[206:209], v170 offset:21504
	ds_read_b128 v[210:213], v170 offset:22528
	ds_read_b128 v[214:217], v170 offset:23552
	global_load_lds_dwordx4 v[218:219], off
	s_add_i32 m0, s58, 0x2000
	s_add_u32 s58, s86, 0x40000
	v_lshl_add_u64 v[220:221], s[86:87], 0, v[152:153]
	s_addc_u32 s59, s87, 0
	s_add_i32 s60, s83, s28
	global_load_lds_dwordx4 v[220:221], off
	v_lshl_add_u64 v[222:223], s[58:59], 0, v[148:149]
	s_mov_b32 m0, s60
	v_lshl_add_u64 v[224:225], s[88:89], 0, v[150:151]
	global_load_lds_dwordx4 v[222:223], off
	v_lshl_add_u64 v[222:223], s[58:59], 0, v[152:153]
	s_add_i32 m0, s60, 0x2000
	s_nop 0
	global_load_lds_dwordx4 v[222:223], off
	v_lshl_add_u64 v[222:223], s[88:89], 0, v[146:147]
	s_mov_b32 m0, s29
	s_nop 0
	global_load_lds_dwordx4 v[222:223], off
	s_mov_b32 m0, s30
	s_nop 0
	global_load_lds_dwordx4 v[224:225], off
	s_waitcnt vmcnt(8)
	s_waitcnt lgkmcnt(0)
	s_barrier
; #define PG8_STAGE(bufoff, gbase, voff) do { _Pragma("unroll") for (int _i = 0; _i < 2; ++_i) \
;         __builtin_amdgcn_global_load_lds((const unsigned*)((const char*)(gbase) + (voff)[_i]), (PG8_LAS unsigned*)(lds + (bufoff) + ldsw + _i * 8192), 16, 0, 0); } while (0)
; #define PG8_LDA(dst, b, h) do { _Pragma("unroll") for (int m = 0; m < 4; ++m) _Pragma("unroll") for (int k = 0; k < 2; ++k) dst[m][k] = *(const PG8_LAS bf16x8*)(lds + PG8_SA(b, h) + aoff + m * 2048 + k * 1024); } while (0)
; #define PG8_LDB(dst, b, h) do { _Pragma("unroll") for (int n = 0; n < 2; ++n) _Pragma("unroll") for (int k = 0; k < 2; ++k) dst[n][k] = *(const PG8_LAS bf16x8*)(lds + PG8_SB(b, h) + boff + n * 2048 + k * 1024); } while (0)
; #define PG8_MMA(ai, bj, At, Bt) do { __builtin_amdgcn_s_setprio(1); _Pragma("unroll") for (int m = 0; m < 4; ++m) _Pragma("unroll") for (int n = 0; n < 2; ++n) _Pragma("unroll") for (int k = 0; k < 2; ++k) \
;         acc[ai][bj][m][n] = __builtin_amdgcn_mfma_f32_16x16x32_bf16(Bt[n][k], At[m][k], acc[ai][bj][m][n], 0, 0, 0); __builtin_amdgcn_s_setprio(0); } while (0)
; #define PG8_WAIT_V(n) asm volatile("s_waitcnt vmcnt(" #n ")" ::: "memory")
; #define PG8_WAIT_L(n) asm volatile("s_waitcnt lgkmcnt(" #n ")" ::: "memory")
; #define PG8_BAR __builtin_amdgcn_s_barrier()
; #define PG8_SCHED __builtin_amdgcn_sched_barrier(0)
; template <class Epi, class Sched, bool ALIGN_EPI = false, bool SP2 = false>
; __device__ __forceinline__ void gemm_phase(PG8_LAS unsigned char* lds, const Gemm g, const Sched& S, const Epi& E) {
;     ...
;             PG8_WAIT_V(8); PG8_WAIT_L(0); PG8_BAR; PG8_MMA(1, 0, At, B0); PG8_MMA(1, 1, At, B1); PG8_BAR; PG8_SCHED;
;             PG8_LDB(B0, 1, 0); PG8_LDB(B1, 1, 1); PG8_SCHED; PG8_LDA(At, 1, 0); PG8_STAGE(PG8_SA(0, 1), a2 + hstep, voffA);
;             PG8_WAIT_V(8); PG8_WAIT_L(0); PG8_BAR; PG8_MMA(0, 0, At, B0); PG8_MMA(0, 1, At, B1); PG8_BAR; PG8_SCHED;
	s_setprio 0
	s_waitcnt lgkmcnt(0)
	v_mfma_f32_16x16x32_bf16 v[60:63], v[128:131], v[180:183], v[60:63]
	v_mfma_f32_16x16x32_bf16 v[56:59], v[136:139], v[180:183], v[56:59]
	v_mfma_f32_16x16x32_bf16 v[48:51], v[128:131], v[188:191], v[48:51]
	v_mfma_f32_16x16x32_bf16 v[40:43], v[136:139], v[188:191], v[40:43]
	v_mfma_f32_16x16x32_bf16 v[32:35], v[128:131], v[196:199], v[32:35]
	v_mfma_f32_16x16x32_bf16 v[24:27], v[136:139], v[196:199], v[24:27]
	v_mfma_f32_16x16x32_bf16 v[16:19], v[128:131], v[210:213], v[16:19]
	v_mfma_f32_16x16x32_bf16 v[8:11], v[136:139], v[210:213], v[8:11]
	v_mfma_f32_16x16x32_bf16 v[60:63], v[132:135], v[184:187], v[60:63]
	v_mfma_f32_16x16x32_bf16 v[56:59], v[140:143], v[184:187], v[56:59]
	v_mfma_f32_16x16x32_bf16 v[48:51], v[132:135], v[192:195], v[48:51]
	v_mfma_f32_16x16x32_bf16 v[40:43], v[140:143], v[192:195], v[40:43]
	v_mfma_f32_16x16x32_bf16 v[32:35], v[132:135], v[206:209], v[32:35]
	v_mfma_f32_16x16x32_bf16 v[24:27], v[140:143], v[206:209], v[24:27]
	v_mfma_f32_16x16x32_bf16 v[16:19], v[132:135], v[214:217], v[16:19]
	v_mfma_f32_16x16x32_bf16 v[8:11], v[140:143], v[214:217], v[8:11]
	v_mfma_f32_16x16x32_bf16 v[52:55], v[158:161], v[180:183], v[52:55]
	v_mfma_f32_16x16x32_bf16 v[44:47], v[172:175], v[180:183], v[44:47]
	v_mfma_f32_16x16x32_bf16 v[36:39], v[158:161], v[188:191], v[36:39]
	v_mfma_f32_16x16x32_bf16 v[28:31], v[172:175], v[188:191], v[28:31]
	v_mfma_f32_16x16x32_bf16 v[20:23], v[158:161], v[196:199], v[20:23]
	v_mfma_f32_16x16x32_bf16 v[12:15], v[172:175], v[196:199], v[12:15]
	v_mfma_f32_16x16x32_bf16 v[4:7], v[158:161], v[210:213], v[4:7]
	v_mfma_f32_16x16x32_bf16 v[0:3], v[172:175], v[210:213], v[0:3]
	v_mfma_f32_16x16x32_bf16 v[52:55], v[162:165], v[184:187], v[52:55]
	v_mfma_f32_16x16x32_bf16 v[44:47], v[176:179], v[184:187], v[44:47]
	v_mfma_f32_16x16x32_bf16 v[36:39], v[162:165], v[192:195], v[36:39]
	v_mfma_f32_16x16x32_bf16 v[28:31], v[176:179], v[192:195], v[28:31]
	v_mfma_f32_16x16x32_bf16 v[20:23], v[162:165], v[206:209], v[20:23]
	v_mfma_f32_16x16x32_bf16 v[12:15], v[176:179], v[206:209], v[12:15]
	v_mfma_f32_16x16x32_bf16 v[4:7], v[162:165], v[214:217], v[4:7]
	v_mfma_f32_16x16x32_bf16 v[0:3], v[176:179], v[214:217], v[0:3]
	s_setprio 1
	s_barrier
	s_add_i32 s60, 0, 0x18000
	s_add_i32 s61, 0, 0x1c000
	v_add_u32_e32 v140, s60, v166
	v_add_u32_e32 v176, s61, v166
	ds_read_b128 v[128:131], v140
	ds_read_b128 v[132:135], v140 offset:1024
	ds_read_b128 v[136:139], v140 offset:2048
	ds_read_b128 v[140:143], v140 offset:3072
	ds_read_b128 v[158:161], v176
	ds_read_b128 v[162:165], v176 offset:1024
	ds_read_b128 v[172:175], v176 offset:2048
	ds_read_b128 v[176:179], v176 offset:3072
	s_add_u32 s58, s88, 0x40000
	s_addc_u32 s59, s89, 0
	s_mov_b32 m0, s31
	v_lshl_add_u64 v[226:227], s[58:59], 0, v[146:147]
	ds_read_b128 v[180:183], v170 offset:32768
	ds_read_b128 v[184:187], v170 offset:33792
	ds_read_b128 v[188:191], v170 offset:34816
	ds_read_b128 v[192:195], v170 offset:35840
	ds_read_b128 v[196:199], v170 offset:36864
	ds_read_b128 v[206:209], v170 offset:37888
	ds_read_b128 v[210:213], v170 offset:38912
	ds_read_b128 v[214:217], v170 offset:39936
	global_load_lds_dwordx4 v[226:227], off
	v_lshl_add_u64 v[226:227], s[58:59], 0, v[150:151]
	s_mov_b32 m0, s37
	s_nop 0
	global_load_lds_dwordx4 v[226:227], off
	s_waitcnt vmcnt(8)
	s_waitcnt lgkmcnt(0)
	s_barrier
	s_setprio 0
	s_waitcnt lgkmcnt(0)
	v_mfma_f32_16x16x32_bf16 v[124:127], v[128:131], v[180:183], v[124:127]
	v_mfma_f32_16x16x32_bf16 v[120:123], v[136:139], v[180:183], v[120:123]
	v_mfma_f32_16x16x32_bf16 v[108:111], v[128:131], v[188:191], v[108:111]
	v_mfma_f32_16x16x32_bf16 v[104:107], v[136:139], v[188:191], v[104:107]
	v_mfma_f32_16x16x32_bf16 v[96:99], v[128:131], v[196:199], v[96:99]
	v_mfma_f32_16x16x32_bf16 v[88:91], v[136:139], v[196:199], v[88:91]
	v_mfma_f32_16x16x32_bf16 v[80:83], v[128:131], v[210:213], v[80:83]
	v_mfma_f32_16x16x32_bf16 v[72:75], v[136:139], v[210:213], v[72:75]
	v_mfma_f32_16x16x32_bf16 v[124:127], v[132:135], v[184:187], v[124:127]
	v_mfma_f32_16x16x32_bf16 v[120:123], v[140:143], v[184:187], v[120:123]
	v_mfma_f32_16x16x32_bf16 v[108:111], v[132:135], v[192:195], v[108:111]
	v_mfma_f32_16x16x32_bf16 v[104:107], v[140:143], v[192:195], v[104:107]
	v_mfma_f32_16x16x32_bf16 v[96:99], v[132:135], v[206:209], v[96:99]
	v_mfma_f32_16x16x32_bf16 v[88:91], v[140:143], v[206:209], v[88:91]
	v_mfma_f32_16x16x32_bf16 v[80:83], v[132:135], v[214:217], v[80:83]
	v_mfma_f32_16x16x32_bf16 v[72:75], v[140:143], v[214:217], v[72:75]
	v_mfma_f32_16x16x32_bf16 v[116:119], v[158:161], v[180:183], v[116:119]
	v_mfma_f32_16x16x32_bf16 v[112:115], v[172:175], v[180:183], v[112:115]
	v_mfma_f32_16x16x32_bf16 v[100:103], v[158:161], v[188:191], v[100:103]
	v_mfma_f32_16x16x32_bf16 v[92:95], v[172:175], v[188:191], v[92:95]
	v_mfma_f32_16x16x32_bf16 v[84:87], v[158:161], v[196:199], v[84:87]
	v_mfma_f32_16x16x32_bf16 v[76:79], v[172:175], v[196:199], v[76:79]
	v_mfma_f32_16x16x32_bf16 v[68:71], v[158:161], v[210:213], v[68:71]
	v_mfma_f32_16x16x32_bf16 v[64:67], v[172:175], v[210:213], v[64:67]
	v_mfma_f32_16x16x32_bf16 v[116:119], v[162:165], v[184:187], v[116:119]
	v_mfma_f32_16x16x32_bf16 v[112:115], v[176:179], v[184:187], v[112:115]
	v_mfma_f32_16x16x32_bf16 v[100:103], v[162:165], v[192:195], v[100:103]
	v_mfma_f32_16x16x32_bf16 v[92:95], v[176:179], v[192:195], v[92:95]
	v_mfma_f32_16x16x32_bf16 v[84:87], v[162:165], v[206:209], v[84:87]
	v_mfma_f32_16x16x32_bf16 v[76:79], v[176:179], v[206:209], v[76:79]
	v_mfma_f32_16x16x32_bf16 v[68:71], v[162:165], v[214:217], v[68:71]
	v_mfma_f32_16x16x32_bf16 v[64:67], v[176:179], v[214:217], v[64:67]
	s_setprio 1
	s_barrier
; #define PG8_STAGE(bufoff, gbase, voff) do { _Pragma("unroll") for (int _i = 0; _i < 2; ++_i) \
;         __builtin_amdgcn_global_load_lds((const unsigned*)((const char*)(gbase) + (voff)[_i]), (PG8_LAS unsigned*)(lds + (bufoff) + ldsw + _i * 8192), 16, 0, 0); } while (0)
; #define PG8_LDA(dst, b, h) do { _Pragma("unroll") for (int m = 0; m < 4; ++m) _Pragma("unroll") for (int k = 0; k < 2; ++k) dst[m][k] = *(const PG8_LAS bf16x8*)(lds + PG8_SA(b, h) + aoff + m * 2048 + k * 1024); } while (0)
; #define PG8_MMA(ai, bj, At, Bt) do { __builtin_amdgcn_s_setprio(1); _Pragma("unroll") for (int m = 0; m < 4; ++m) _Pragma("unroll") for (int n = 0; n < 2; ++n) _Pragma("unroll") for (int k = 0; k < 2; ++k) \
;         acc[ai][bj][m][n] = __builtin_amdgcn_mfma_f32_16x16x32_bf16(Bt[n][k], At[m][k], acc[ai][bj][m][n], 0, 0, 0); __builtin_amdgcn_s_setprio(0); } while (0)
; #define PG8_WAIT_V(n) asm volatile("s_waitcnt vmcnt(" #n ")" ::: "memory")
; #define PG8_WAIT_L(n) asm volatile("s_waitcnt lgkmcnt(" #n ")" ::: "memory")
; #define PG8_BAR __builtin_amdgcn_s_barrier()
; #define PG8_SCHED __builtin_amdgcn_sched_barrier(0)
; template <class Epi, class Sched, bool ALIGN_EPI = false, bool SP2 = false>
; __device__ __forceinline__ void gemm_phase(PG8_LAS unsigned char* lds, const Gemm g, const Sched& S, const Epi& E) {
;     ...
;         for (int t = 0; t < nt; t += 2) {
;             const bool last = (t == nt - 2);
;             const char* a1 = cA + (size_t)(t + 1) * kstep;
;             const char* a2 = last ? nA : cA + (size_t)(t + 2) * kstep; const char* b2 = last ? nB : cB + (size_t)(t + 2) * kstep;
;     ...
;             PG8_LDA(At, 1, 1); PG8_STAGE(PG8_SB(1, 0), b3, voffB); PG8_STAGE(PG8_SB(1, 1), b3 + hstep, voffB); PG8_STAGE(PG8_SA(1, 0), a3, voffA);
;             PG8_WAIT_V(8); PG8_WAIT_L(0); PG8_BAR; PG8_MMA(1, 0, At, B0); PG8_MMA(1, 1, At, B1); PG8_BAR; PG8_SCHED;
	s_add_i32 s58, s60, s28
	v_lshl_add_u64 v[218:219], v[218:219], 0, s[66:67]
	s_mov_b32 m0, s58
	ds_read_b128 v[180:183], v170 offset:49152
	ds_read_b128 v[184:187], v170 offset:50176
	ds_read_b128 v[188:191], v170 offset:51200
	ds_read_b128 v[192:195], v170 offset:52224
	ds_read_b128 v[196:199], v170 offset:53248
	ds_read_b128 v[206:209], v170 offset:54272
	ds_read_b128 v[210:213], v170 offset:55296
	ds_read_b128 v[214:217], v170 offset:56320
	global_load_lds_dwordx4 v[218:219], off
	s_add_i32 m0, s58, 0x2000
	s_add_u32 s58, s86, 0x40080
	v_lshl_add_u64 v[218:219], v[220:221], 0, s[66:67]
	s_addc_u32 s59, s87, 0
	s_add_i32 s60, s61, s28
	global_load_lds_dwordx4 v[218:219], off
	v_lshl_add_u64 v[218:219], s[58:59], 0, v[148:149]
	s_mov_b32 m0, s60
	s_nop 0
	global_load_lds_dwordx4 v[218:219], off
	v_lshl_add_u64 v[218:219], s[58:59], 0, v[152:153]
	s_add_i32 m0, s60, 0x2000
	s_nop 0
	global_load_lds_dwordx4 v[218:219], off
	v_lshl_add_u64 v[218:219], v[222:223], 0, s[66:67]
	s_mov_b32 m0, s2
	s_nop 0
	global_load_lds_dwordx4 v[218:219], off
	v_lshl_add_u64 v[218:219], v[224:225], 0, s[66:67]
	s_mov_b32 m0, s3
	s_nop 0
	global_load_lds_dwordx4 v[218:219], off
	s_waitcnt vmcnt(8)
	s_waitcnt lgkmcnt(0)
	s_barrier
	s_setprio 0
	s_waitcnt lgkmcnt(0)
	v_mfma_f32_16x16x32_bf16 v[60:63], v[128:131], v[180:183], v[60:63]
	v_mfma_f32_16x16x32_bf16 v[56:59], v[136:139], v[180:183], v[56:59]
	v_mfma_f32_16x16x32_bf16 v[48:51], v[128:131], v[188:191], v[48:51]
	v_mfma_f32_16x16x32_bf16 v[40:43], v[136:139], v[188:191], v[40:43]
	v_mfma_f32_16x16x32_bf16 v[32:35], v[128:131], v[196:199], v[32:35]
	v_mfma_f32_16x16x32_bf16 v[24:27], v[136:139], v[196:199], v[24:27]
	v_mfma_f32_16x16x32_bf16 v[16:19], v[128:131], v[210:213], v[16:19]
	v_mfma_f32_16x16x32_bf16 v[8:11], v[136:139], v[210:213], v[8:11]
	v_mfma_f32_16x16x32_bf16 v[60:63], v[132:135], v[184:187], v[60:63]
	v_mfma_f32_16x16x32_bf16 v[56:59], v[140:143], v[184:187], v[56:59]
	v_mfma_f32_16x16x32_bf16 v[48:51], v[132:135], v[192:195], v[48:51]
	v_mfma_f32_16x16x32_bf16 v[40:43], v[140:143], v[192:195], v[40:43]
	v_mfma_f32_16x16x32_bf16 v[32:35], v[132:135], v[206:209], v[32:35]
	v_mfma_f32_16x16x32_bf16 v[24:27], v[140:143], v[206:209], v[24:27]
	v_mfma_f32_16x16x32_bf16 v[16:19], v[132:135], v[214:217], v[16:19]
	v_mfma_f32_16x16x32_bf16 v[8:11], v[140:143], v[214:217], v[8:11]
	v_mfma_f32_16x16x32_bf16 v[52:55], v[158:161], v[180:183], v[52:55]
	v_mfma_f32_16x16x32_bf16 v[44:47], v[172:175], v[180:183], v[44:47]
	v_mfma_f32_16x16x32_bf16 v[36:39], v[158:161], v[188:191], v[36:39]
	v_mfma_f32_16x16x32_bf16 v[28:31], v[172:175], v[188:191], v[28:31]
	v_mfma_f32_16x16x32_bf16 v[20:23], v[158:161], v[196:199], v[20:23]
	v_mfma_f32_16x16x32_bf16 v[12:15], v[172:175], v[196:199], v[12:15]
	v_mfma_f32_16x16x32_bf16 v[4:7], v[158:161], v[210:213], v[4:7]
	v_mfma_f32_16x16x32_bf16 v[0:3], v[172:175], v[210:213], v[0:3]
	v_mfma_f32_16x16x32_bf16 v[52:55], v[162:165], v[184:187], v[52:55]
	v_mfma_f32_16x16x32_bf16 v[44:47], v[176:179], v[184:187], v[44:47]
	v_mfma_f32_16x16x32_bf16 v[36:39], v[162:165], v[192:195], v[36:39]
	v_mfma_f32_16x16x32_bf16 v[28:31], v[176:179], v[192:195], v[28:31]
	v_mfma_f32_16x16x32_bf16 v[20:23], v[162:165], v[206:209], v[20:23]
	v_mfma_f32_16x16x32_bf16 v[12:15], v[176:179], v[206:209], v[12:15]
	v_mfma_f32_16x16x32_bf16 v[4:7], v[162:165], v[214:217], v[4:7]
	v_mfma_f32_16x16x32_bf16 v[0:3], v[176:179], v[214:217], v[0:3]
	s_setprio 1
	s_barrier
	s_add_i32 s91, s91, 2
	s_add_u32 s84, s84, 0x100
	s_addc_u32 s85, s85, 0
	s_add_u32 s81, s81, 0x100
	s_addc_u32 s90, s90, 0
	s_cmp_gt_u32 s91, 13
	s_cbranch_scc0 .LBB0_582
	s_and_b64 vcc, exec, s[68:69]
	s_cbranch_vccz .LBB0_585
	s_barrier

; #define PG8_STAGE(bufoff, gbase, voff) do { _Pragma("unroll") for (int _i = 0; _i < 2; ++_i) \
;         __builtin_amdgcn_global_load_lds((const unsigned*)((const char*)(gbase) + (voff)[_i]), (PG8_LAS unsigned*)(lds + (bufoff) + ldsw + _i * 8192), 16, 0, 0); } while (0)
; #define PG8_LDA(dst, b, h) do { _Pragma("unroll") for (int m = 0; m < 4; ++m) _Pragma("unroll") for (int k = 0; k < 2; ++k) dst[m][k] = *(const PG8_LAS bf16x8*)(lds + PG8_SA(b, h) + aoff + m * 2048 + k * 1024); } while (0)
; #define PG8_LDB(dst, b, h) do { _Pragma("unroll") for (int n = 0; n < 2; ++n) _Pragma("unroll") for (int k = 0; k < 2; ++k) dst[n][k] = *(const PG8_LAS bf16x8*)(lds + PG8_SB(b, h) + boff + n * 2048 + k * 1024); } while (0)
; #define PG8_MMA(ai, bj, At, Bt) do { __builtin_amdgcn_s_setprio(1); _Pragma("unroll") for (int m = 0; m < 4; ++m) _Pragma("unroll") for (int n = 0; n < 2; ++n) _Pragma("unroll") for (int k = 0; k < 2; ++k) \
;         acc[ai][bj][m][n] = __builtin_amdgcn_mfma_f32_16x16x32_bf16(Bt[n][k], At[m][k], acc[ai][bj][m][n], 0, 0, 0); __builtin_amdgcn_s_setprio(0); } while (0)
; #define PG8_WAIT_V(n) asm volatile("s_waitcnt vmcnt(" #n ")" ::: "memory")
; #define PG8_WAIT_L(n) asm volatile("s_waitcnt lgkmcnt(" #n ")" ::: "memory")
; #define PG8_BAR __builtin_amdgcn_s_barrier()
; #define PG8_SCHED __builtin_amdgcn_sched_barrier(0)
; template <class Epi, class Sched, bool ALIGN_EPI = false, bool SP2 = false>
; __device__ __forceinline__ void gemm_phase(PG8_LAS unsigned char* lds, const Gemm g, const Sched& S, const Epi& E) {
;     ...
;             PG8_LDB(B0, 0, 0); PG8_LDB(B1, 0, 1); PG8_SCHED; PG8_LDA(At, 0, 0); PG8_STAGE(PG8_SA(1, 1), a1 + hstep, voffA);
;             PG8_WAIT_V(8); PG8_WAIT_L(0); PG8_BAR; PG8_MMA(0, 0, At, B0); PG8_MMA(0, 1, At, B1); PG8_BAR; PG8_SCHED;
;             PG8_LDA(At, 0, 1); PG8_STAGE(PG8_SB(0, 0), b2, voffB); PG8_STAGE(PG8_SB(0, 1), b2 + hstep, voffB); PG8_STAGE(PG8_SA(0, 0), a2, voffA);
;             PG8_WAIT_V(8); PG8_WAIT_L(0); PG8_BAR; PG8_MMA(1, 0, At, B0); PG8_MMA(1, 1, At, B1); PG8_BAR; PG8_SCHED;
.LBB0_660:
	ds_read_b128 v[140:143], v190
	ds_read_b128 v[146:149], v190 offset:1024
	ds_read_b128 v[150:153], v190 offset:2048
	ds_read_b128 v[154:157], v190 offset:3072
	ds_read_b128 v[158:161], v191
	ds_read_b128 v[162:165], v191 offset:1024
	ds_read_b128 v[166:169], v191 offset:2048
	ds_read_b128 v[170:173], v191 offset:3072
	s_add_u32 s58, s80, 0xfffc0080
	s_addc_u32 s59, s81, -1
	s_cmp_eq_u32 s90, 12
	s_cselect_b32 s85, s5, s59
	s_cselect_b32 s84, s71, s58
	s_cselect_b32 s83, s73, s89
	s_cselect_b32 s82, s87, s88
	v_lshl_add_u64 v[186:187], s[80:81], 0, v[136:137]
	s_add_i32 m0, s20, 0xc000
	ds_read_b128 v[174:177], v192
	ds_read_b128 v[178:181], v192 offset:1024
	ds_read_b128 v[182:185], v192 offset:2048
	ds_read_b128 v[194:197], v192 offset:3072
	ds_read_b128 v[206:209], v192 offset:4096
	ds_read_b128 v[210:213], v192 offset:5120
	ds_read_b128 v[214:217], v192 offset:6144
	ds_read_b128 v[218:221], v192 offset:7168
	global_load_lds_dwordx4 v[186:187], off
	v_lshl_add_u64 v[186:187], s[80:81], 0, v[138:139]
	s_add_i32 m0, s20, 0xe000
	s_nop 0
	global_load_lds_dwordx4 v[186:187], off
	s_waitcnt vmcnt(8)
	s_waitcnt lgkmcnt(0)
	s_barrier
	s_setprio 0
	s_waitcnt lgkmcnt(0)
	v_mfma_f32_16x16x32_bf16 v[124:127], v[140:143], v[174:177], v[124:127]
	v_mfma_f32_16x16x32_bf16 v[120:123], v[150:153], v[174:177], v[120:123]
	v_mfma_f32_16x16x32_bf16 v[108:111], v[140:143], v[182:185], v[108:111]
	v_mfma_f32_16x16x32_bf16 v[104:107], v[150:153], v[182:185], v[104:107]
	v_mfma_f32_16x16x32_bf16 v[92:95], v[140:143], v[206:209], v[92:95]
	v_mfma_f32_16x16x32_bf16 v[88:91], v[150:153], v[206:209], v[88:91]
	v_mfma_f32_16x16x32_bf16 v[76:79], v[140:143], v[214:217], v[76:79]
	v_mfma_f32_16x16x32_bf16 v[72:75], v[150:153], v[214:217], v[72:75]
	v_mfma_f32_16x16x32_bf16 v[124:127], v[146:149], v[178:181], v[124:127]
	v_mfma_f32_16x16x32_bf16 v[120:123], v[154:157], v[178:181], v[120:123]
	v_mfma_f32_16x16x32_bf16 v[108:111], v[146:149], v[194:197], v[108:111]
	v_mfma_f32_16x16x32_bf16 v[104:107], v[154:157], v[194:197], v[104:107]
	v_mfma_f32_16x16x32_bf16 v[92:95], v[146:149], v[210:213], v[92:95]
	v_mfma_f32_16x16x32_bf16 v[88:91], v[154:157], v[210:213], v[88:91]
	v_mfma_f32_16x16x32_bf16 v[76:79], v[146:149], v[218:221], v[76:79]
	v_mfma_f32_16x16x32_bf16 v[72:75], v[154:157], v[218:221], v[72:75]
	v_mfma_f32_16x16x32_bf16 v[116:119], v[158:161], v[174:177], v[116:119]
	v_mfma_f32_16x16x32_bf16 v[112:115], v[166:169], v[174:177], v[112:115]
	v_mfma_f32_16x16x32_bf16 v[100:103], v[158:161], v[182:185], v[100:103]
	v_mfma_f32_16x16x32_bf16 v[96:99], v[166:169], v[182:185], v[96:99]
	v_mfma_f32_16x16x32_bf16 v[84:87], v[158:161], v[206:209], v[84:87]
	v_mfma_f32_16x16x32_bf16 v[80:83], v[166:169], v[206:209], v[80:83]
	v_mfma_f32_16x16x32_bf16 v[68:71], v[158:161], v[214:217], v[68:71]
	v_mfma_f32_16x16x32_bf16 v[64:67], v[166:169], v[214:217], v[64:67]
	v_mfma_f32_16x16x32_bf16 v[116:119], v[162:165], v[178:181], v[116:119]
	v_mfma_f32_16x16x32_bf16 v[112:115], v[170:173], v[178:181], v[112:115]
	v_mfma_f32_16x16x32_bf16 v[100:103], v[162:165], v[194:197], v[100:103]
	v_mfma_f32_16x16x32_bf16 v[96:99], v[170:173], v[194:197], v[96:99]
	v_mfma_f32_16x16x32_bf16 v[84:87], v[162:165], v[210:213], v[84:87]
	v_mfma_f32_16x16x32_bf16 v[80:83], v[170:173], v[210:213], v[80:83]
	v_mfma_f32_16x16x32_bf16 v[68:71], v[162:165], v[218:221], v[68:71]
	v_mfma_f32_16x16x32_bf16 v[64:67], v[170:173], v[218:221], v[64:67]
	s_setprio 1
	s_barrier
	s_add_i32 s58, s39, s11
	v_lshl_add_u64 v[186:187], s[82:83], 0, v[132:133]
	s_mov_b32 m0, s58
	ds_read_b128 v[174:177], v192 offset:16384
	ds_read_b128 v[178:181], v192 offset:17408
	ds_read_b128 v[182:185], v192 offset:18432
	ds_read_b128 v[194:197], v192 offset:19456
	ds_read_b128 v[206:209], v192 offset:20480
	ds_read_b128 v[210:213], v192 offset:21504
	ds_read_b128 v[214:217], v192 offset:22528
	ds_read_b128 v[218:221], v192 offset:23552
	global_load_lds_dwordx4 v[186:187], off
	s_add_i32 m0, s58, 0x2000
	s_add_u32 s58, s82, 0x40000
	v_lshl_add_u64 v[198:199], s[82:83], 0, v[128:129]
	s_addc_u32 s59, s83, 0
	s_add_i32 s60, s56, s11
	global_load_lds_dwordx4 v[198:199], off
	v_lshl_add_u64 v[222:223], s[58:59], 0, v[132:133]
	s_mov_b32 m0, s60
	v_lshl_add_u64 v[224:225], s[84:85], 0, v[130:131]
	global_load_lds_dwordx4 v[222:223], off
	v_lshl_add_u64 v[222:223], s[58:59], 0, v[128:129]
	s_add_i32 m0, s60, 0x2000
	s_nop 0
	global_load_lds_dwordx4 v[222:223], off
	v_lshl_add_u64 v[222:223], s[84:85], 0, v[134:135]
	s_mov_b32 m0, s20
	s_nop 0
	global_load_lds_dwordx4 v[222:223], off
	s_mov_b32 m0, s21
	s_nop 0
	global_load_lds_dwordx4 v[224:225], off
	s_waitcnt vmcnt(8)
	s_waitcnt lgkmcnt(0)
	s_barrier
; #define PG8_STAGE(bufoff, gbase, voff) do { _Pragma("unroll") for (int _i = 0; _i < 2; ++_i) \
;         __builtin_amdgcn_global_load_lds((const unsigned*)((const char*)(gbase) + (voff)[_i]), (PG8_LAS unsigned*)(lds + (bufoff) + ldsw + _i * 8192), 16, 0, 0); } while (0)
; #define PG8_LDA(dst, b, h) do { _Pragma("unroll") for (int m = 0; m < 4; ++m) _Pragma("unroll") for (int k = 0; k < 2; ++k) dst[m][k] = *(const PG8_LAS bf16x8*)(lds + PG8_SA(b, h) + aoff + m * 2048 + k * 1024); } while (0)
; #define PG8_LDB(dst, b, h) do { _Pragma("unroll") for (int n = 0; n < 2; ++n) _Pragma("unroll") for (int k = 0; k < 2; ++k) dst[n][k] = *(const PG8_LAS bf16x8*)(lds + PG8_SB(b, h) + boff + n * 2048 + k * 1024); } while (0)
; #define PG8_MMA(ai, bj, At, Bt) do { __builtin_amdgcn_s_setprio(1); _Pragma("unroll") for (int m = 0; m < 4; ++m) _Pragma("unroll") for (int n = 0; n < 2; ++n) _Pragma("unroll") for (int k = 0; k < 2; ++k) \
;         acc[ai][bj][m][n] = __builtin_amdgcn_mfma_f32_16x16x32_bf16(Bt[n][k], At[m][k], acc[ai][bj][m][n], 0, 0, 0); __builtin_amdgcn_s_setprio(0); } while (0)
; #define PG8_WAIT_V(n) asm volatile("s_waitcnt vmcnt(" #n ")" ::: "memory")
; #define PG8_WAIT_L(n) asm volatile("s_waitcnt lgkmcnt(" #n ")" ::: "memory")
; #define PG8_BAR __builtin_amdgcn_s_barrier()
; #define PG8_SCHED __builtin_amdgcn_sched_barrier(0)
; template <class Epi, class Sched, bool ALIGN_EPI = false, bool SP2 = false>
; __device__ __forceinline__ void gemm_phase(PG8_LAS unsigned char* lds, const Gemm g, const Sched& S, const Epi& E) {
;     ...
;             PG8_WAIT_V(8); PG8_WAIT_L(0); PG8_BAR; PG8_MMA(1, 0, At, B0); PG8_MMA(1, 1, At, B1); PG8_BAR; PG8_SCHED;
;             PG8_LDB(B0, 1, 0); PG8_LDB(B1, 1, 1); PG8_SCHED; PG8_LDA(At, 1, 0); PG8_STAGE(PG8_SA(0, 1), a2 + hstep, voffA);
;             PG8_WAIT_V(8); PG8_WAIT_L(0); PG8_BAR; PG8_MMA(0, 0, At, B0); PG8_MMA(0, 1, At, B1); PG8_BAR; PG8_SCHED;
	s_setprio 0
	s_waitcnt lgkmcnt(0)
	v_mfma_f32_16x16x32_bf16 v[60:63], v[140:143], v[174:177], v[60:63]
	v_mfma_f32_16x16x32_bf16 v[56:59], v[150:153], v[174:177], v[56:59]
	v_mfma_f32_16x16x32_bf16 v[44:47], v[140:143], v[182:185], v[44:47]
	v_mfma_f32_16x16x32_bf16 v[40:43], v[150:153], v[182:185], v[40:43]
	v_mfma_f32_16x16x32_bf16 v[28:31], v[140:143], v[206:209], v[28:31]
	v_mfma_f32_16x16x32_bf16 v[24:27], v[150:153], v[206:209], v[24:27]
	v_mfma_f32_16x16x32_bf16 v[12:15], v[140:143], v[214:217], v[12:15]
	v_mfma_f32_16x16x32_bf16 v[8:11], v[150:153], v[214:217], v[8:11]
	v_mfma_f32_16x16x32_bf16 v[60:63], v[146:149], v[178:181], v[60:63]
	v_mfma_f32_16x16x32_bf16 v[56:59], v[154:157], v[178:181], v[56:59]
	v_mfma_f32_16x16x32_bf16 v[44:47], v[146:149], v[194:197], v[44:47]
	v_mfma_f32_16x16x32_bf16 v[40:43], v[154:157], v[194:197], v[40:43]
	v_mfma_f32_16x16x32_bf16 v[28:31], v[146:149], v[210:213], v[28:31]
	v_mfma_f32_16x16x32_bf16 v[24:27], v[154:157], v[210:213], v[24:27]
	v_mfma_f32_16x16x32_bf16 v[12:15], v[146:149], v[218:221], v[12:15]
	v_mfma_f32_16x16x32_bf16 v[8:11], v[154:157], v[218:221], v[8:11]
	v_mfma_f32_16x16x32_bf16 v[52:55], v[158:161], v[174:177], v[52:55]
	v_mfma_f32_16x16x32_bf16 v[48:51], v[166:169], v[174:177], v[48:51]
	v_mfma_f32_16x16x32_bf16 v[36:39], v[158:161], v[182:185], v[36:39]
	v_mfma_f32_16x16x32_bf16 v[32:35], v[166:169], v[182:185], v[32:35]
	v_mfma_f32_16x16x32_bf16 v[20:23], v[158:161], v[206:209], v[20:23]
	v_mfma_f32_16x16x32_bf16 v[16:19], v[166:169], v[206:209], v[16:19]
	v_mfma_f32_16x16x32_bf16 v[4:7], v[158:161], v[214:217], v[4:7]
	v_mfma_f32_16x16x32_bf16 v[0:3], v[166:169], v[214:217], v[0:3]
	v_mfma_f32_16x16x32_bf16 v[52:55], v[162:165], v[178:181], v[52:55]
	v_mfma_f32_16x16x32_bf16 v[48:51], v[170:173], v[178:181], v[48:51]
	v_mfma_f32_16x16x32_bf16 v[36:39], v[162:165], v[194:197], v[36:39]
	v_mfma_f32_16x16x32_bf16 v[32:35], v[170:173], v[194:197], v[32:35]
	v_mfma_f32_16x16x32_bf16 v[20:23], v[162:165], v[210:213], v[20:23]
	v_mfma_f32_16x16x32_bf16 v[16:19], v[170:173], v[210:213], v[16:19]
	v_mfma_f32_16x16x32_bf16 v[4:7], v[162:165], v[218:221], v[4:7]
	v_mfma_f32_16x16x32_bf16 v[0:3], v[170:173], v[218:221], v[0:3]
	s_setprio 1
	s_barrier
	s_add_i32 s60, 0, 0x18000
	s_add_i32 s61, 0, 0x1c000
	v_add_u32_e32 v154, s60, v188
	v_add_u32_e32 v170, s61, v188
	ds_read_b128 v[140:143], v154
	ds_read_b128 v[146:149], v154 offset:1024
	ds_read_b128 v[150:153], v154 offset:2048
	ds_read_b128 v[154:157], v154 offset:3072
	ds_read_b128 v[158:161], v170
	ds_read_b128 v[162:165], v170 offset:1024
	ds_read_b128 v[166:169], v170 offset:2048
	ds_read_b128 v[170:173], v170 offset:3072
	s_add_u32 s58, s84, 0x40000
	s_addc_u32 s59, s85, 0
	s_mov_b32 m0, s28
	v_lshl_add_u64 v[226:227], s[58:59], 0, v[134:135]
	ds_read_b128 v[174:177], v192 offset:32768
	ds_read_b128 v[178:181], v192 offset:33792
	ds_read_b128 v[182:185], v192 offset:34816
	ds_read_b128 v[194:197], v192 offset:35840
	ds_read_b128 v[206:209], v192 offset:36864
	ds_read_b128 v[210:213], v192 offset:37888
	ds_read_b128 v[214:217], v192 offset:38912
	ds_read_b128 v[218:221], v192 offset:39936
	global_load_lds_dwordx4 v[226:227], off
	v_lshl_add_u64 v[226:227], s[58:59], 0, v[130:131]
	s_mov_b32 m0, s29
	s_nop 0
	global_load_lds_dwordx4 v[226:227], off
	s_waitcnt vmcnt(8)
	s_waitcnt lgkmcnt(0)
	s_barrier
	s_setprio 0
	s_waitcnt lgkmcnt(0)
	v_mfma_f32_16x16x32_bf16 v[124:127], v[140:143], v[174:177], v[124:127]
	v_mfma_f32_16x16x32_bf16 v[120:123], v[150:153], v[174:177], v[120:123]
	v_mfma_f32_16x16x32_bf16 v[108:111], v[140:143], v[182:185], v[108:111]
	v_mfma_f32_16x16x32_bf16 v[104:107], v[150:153], v[182:185], v[104:107]
	v_mfma_f32_16x16x32_bf16 v[92:95], v[140:143], v[206:209], v[92:95]
	v_mfma_f32_16x16x32_bf16 v[88:91], v[150:153], v[206:209], v[88:91]
	v_mfma_f32_16x16x32_bf16 v[76:79], v[140:143], v[214:217], v[76:79]
	v_mfma_f32_16x16x32_bf16 v[72:75], v[150:153], v[214:217], v[72:75]
	v_mfma_f32_16x16x32_bf16 v[124:127], v[146:149], v[178:181], v[124:127]
	v_mfma_f32_16x16x32_bf16 v[120:123], v[154:157], v[178:181], v[120:123]
	v_mfma_f32_16x16x32_bf16 v[108:111], v[146:149], v[194:197], v[108:111]
	v_mfma_f32_16x16x32_bf16 v[104:107], v[154:157], v[194:197], v[104:107]
	v_mfma_f32_16x16x32_bf16 v[92:95], v[146:149], v[210:213], v[92:95]
	v_mfma_f32_16x16x32_bf16 v[88:91], v[154:157], v[210:213], v[88:91]
	v_mfma_f32_16x16x32_bf16 v[76:79], v[146:149], v[218:221], v[76:79]
	v_mfma_f32_16x16x32_bf16 v[72:75], v[154:157], v[218:221], v[72:75]
	v_mfma_f32_16x16x32_bf16 v[116:119], v[158:161], v[174:177], v[116:119]
	v_mfma_f32_16x16x32_bf16 v[112:115], v[166:169], v[174:177], v[112:115]
	v_mfma_f32_16x16x32_bf16 v[100:103], v[158:161], v[182:185], v[100:103]
	v_mfma_f32_16x16x32_bf16 v[96:99], v[166:169], v[182:185], v[96:99]
	v_mfma_f32_16x16x32_bf16 v[84:87], v[158:161], v[206:209], v[84:87]
	v_mfma_f32_16x16x32_bf16 v[80:83], v[166:169], v[206:209], v[80:83]
	v_mfma_f32_16x16x32_bf16 v[68:71], v[158:161], v[214:217], v[68:71]
	v_mfma_f32_16x16x32_bf16 v[64:67], v[166:169], v[214:217], v[64:67]
	v_mfma_f32_16x16x32_bf16 v[116:119], v[162:165], v[178:181], v[116:119]
	v_mfma_f32_16x16x32_bf16 v[112:115], v[170:173], v[178:181], v[112:115]
	v_mfma_f32_16x16x32_bf16 v[100:103], v[162:165], v[194:197], v[100:103]
	v_mfma_f32_16x16x32_bf16 v[96:99], v[170:173], v[194:197], v[96:99]
	v_mfma_f32_16x16x32_bf16 v[84:87], v[162:165], v[210:213], v[84:87]
	v_mfma_f32_16x16x32_bf16 v[80:83], v[170:173], v[210:213], v[80:83]
	v_mfma_f32_16x16x32_bf16 v[68:71], v[162:165], v[218:221], v[68:71]
	v_mfma_f32_16x16x32_bf16 v[64:67], v[170:173], v[218:221], v[64:67]
	s_setprio 1
	s_barrier
; #define PG8_STAGE(bufoff, gbase, voff) do { _Pragma("unroll") for (int _i = 0; _i < 2; ++_i) \
;         __builtin_amdgcn_global_load_lds((const unsigned*)((const char*)(gbase) + (voff)[_i]), (PG8_LAS unsigned*)(lds + (bufoff) + ldsw + _i * 8192), 16, 0, 0); } while (0)
; #define PG8_LDA(dst, b, h) do { _Pragma("unroll") for (int m = 0; m < 4; ++m) _Pragma("unroll") for (int k = 0; k < 2; ++k) dst[m][k] = *(const PG8_LAS bf16x8*)(lds + PG8_SA(b, h) + aoff + m * 2048 + k * 1024); } while (0)
; #define PG8_MMA(ai, bj, At, Bt) do { __builtin_amdgcn_s_setprio(1); _Pragma("unroll") for (int m = 0; m < 4; ++m) _Pragma("unroll") for (int n = 0; n < 2; ++n) _Pragma("unroll") for (int k = 0; k < 2; ++k) \
;         acc[ai][bj][m][n] = __builtin_amdgcn_mfma_f32_16x16x32_bf16(Bt[n][k], At[m][k], acc[ai][bj][m][n], 0, 0, 0); __builtin_amdgcn_s_setprio(0); } while (0)
; #define PG8_WAIT_V(n) asm volatile("s_waitcnt vmcnt(" #n ")" ::: "memory")
; #define PG8_WAIT_L(n) asm volatile("s_waitcnt lgkmcnt(" #n ")" ::: "memory")
; #define PG8_BAR __builtin_amdgcn_s_barrier()
; #define PG8_SCHED __builtin_amdgcn_sched_barrier(0)
; template <class Epi, class Sched, bool ALIGN_EPI = false, bool SP2 = false>
; __device__ __forceinline__ void gemm_phase(PG8_LAS unsigned char* lds, const Gemm g, const Sched& S, const Epi& E) {
;     ...
;         for (int t = 0; t < nt; t += 2) {
;             const bool last = (t == nt - 2);
;             const char* a1 = cA + (size_t)(t + 1) * kstep;
;             const char* a2 = last ? nA : cA + (size_t)(t + 2) * kstep; const char* b2 = last ? nB : cB + (size_t)(t + 2) * kstep;
;     ...
;             PG8_LDA(At, 1, 1); PG8_STAGE(PG8_SB(1, 0), b3, voffB); PG8_STAGE(PG8_SB(1, 1), b3 + hstep, voffB); PG8_STAGE(PG8_SA(1, 0), a3, voffA);
;             PG8_WAIT_V(8); PG8_WAIT_L(0); PG8_BAR; PG8_MMA(1, 0, At, B0); PG8_MMA(1, 1, At, B1); PG8_BAR; PG8_SCHED;
	s_add_i32 s58, s60, s11
	v_lshl_add_u64 v[186:187], v[186:187], 0, s[66:67]
	s_mov_b32 m0, s58
	ds_read_b128 v[174:177], v192 offset:49152
	ds_read_b128 v[178:181], v192 offset:50176
	ds_read_b128 v[182:185], v192 offset:51200
	ds_read_b128 v[194:197], v192 offset:52224
	ds_read_b128 v[206:209], v192 offset:53248
	ds_read_b128 v[210:213], v192 offset:54272
	ds_read_b128 v[214:217], v192 offset:55296
	ds_read_b128 v[218:221], v192 offset:56320
	global_load_lds_dwordx4 v[186:187], off
	s_add_i32 m0, s58, 0x2000
	s_add_u32 s58, s82, 0x40080
	v_lshl_add_u64 v[186:187], v[198:199], 0, s[66:67]
	s_addc_u32 s59, s83, 0
	s_add_i32 s60, s61, s11
	global_load_lds_dwordx4 v[186:187], off
	v_lshl_add_u64 v[186:187], s[58:59], 0, v[132:133]
	s_mov_b32 m0, s60
	s_nop 0
	global_load_lds_dwordx4 v[186:187], off
	v_lshl_add_u64 v[186:187], s[58:59], 0, v[128:129]
	s_add_i32 m0, s60, 0x2000
	s_nop 0
	global_load_lds_dwordx4 v[186:187], off
	v_lshl_add_u64 v[186:187], v[222:223], 0, s[66:67]
	s_mov_b32 m0, s31
	s_nop 0
	global_load_lds_dwordx4 v[186:187], off
	v_lshl_add_u64 v[186:187], v[224:225], 0, s[66:67]
	s_mov_b32 m0, s37
	s_nop 0
	global_load_lds_dwordx4 v[186:187], off
	s_waitcnt vmcnt(8)
	s_waitcnt lgkmcnt(0)
	s_barrier
	s_setprio 0
	s_waitcnt lgkmcnt(0)
	v_mfma_f32_16x16x32_bf16 v[60:63], v[140:143], v[174:177], v[60:63]
	v_mfma_f32_16x16x32_bf16 v[56:59], v[150:153], v[174:177], v[56:59]
	v_mfma_f32_16x16x32_bf16 v[44:47], v[140:143], v[182:185], v[44:47]
	v_mfma_f32_16x16x32_bf16 v[40:43], v[150:153], v[182:185], v[40:43]
	v_mfma_f32_16x16x32_bf16 v[28:31], v[140:143], v[206:209], v[28:31]
	v_mfma_f32_16x16x32_bf16 v[24:27], v[150:153], v[206:209], v[24:27]
	v_mfma_f32_16x16x32_bf16 v[12:15], v[140:143], v[214:217], v[12:15]
	v_mfma_f32_16x16x32_bf16 v[8:11], v[150:153], v[214:217], v[8:11]
	v_mfma_f32_16x16x32_bf16 v[60:63], v[146:149], v[178:181], v[60:63]
	v_mfma_f32_16x16x32_bf16 v[56:59], v[154:157], v[178:181], v[56:59]
	v_mfma_f32_16x16x32_bf16 v[44:47], v[146:149], v[194:197], v[44:47]
	v_mfma_f32_16x16x32_bf16 v[40:43], v[154:157], v[194:197], v[40:43]
	v_mfma_f32_16x16x32_bf16 v[28:31], v[146:149], v[210:213], v[28:31]
	v_mfma_f32_16x16x32_bf16 v[24:27], v[154:157], v[210:213], v[24:27]
	v_mfma_f32_16x16x32_bf16 v[12:15], v[146:149], v[218:221], v[12:15]
	v_mfma_f32_16x16x32_bf16 v[8:11], v[154:157], v[218:221], v[8:11]
	v_mfma_f32_16x16x32_bf16 v[52:55], v[158:161], v[174:177], v[52:55]
	v_mfma_f32_16x16x32_bf16 v[48:51], v[166:169], v[174:177], v[48:51]
	v_mfma_f32_16x16x32_bf16 v[36:39], v[158:161], v[182:185], v[36:39]
	v_mfma_f32_16x16x32_bf16 v[32:35], v[166:169], v[182:185], v[32:35]
	v_mfma_f32_16x16x32_bf16 v[20:23], v[158:161], v[206:209], v[20:23]
	v_mfma_f32_16x16x32_bf16 v[16:19], v[166:169], v[206:209], v[16:19]
	v_mfma_f32_16x16x32_bf16 v[4:7], v[158:161], v[214:217], v[4:7]
	v_mfma_f32_16x16x32_bf16 v[0:3], v[166:169], v[214:217], v[0:3]
	v_mfma_f32_16x16x32_bf16 v[52:55], v[162:165], v[178:181], v[52:55]
	v_mfma_f32_16x16x32_bf16 v[48:51], v[170:173], v[178:181], v[48:51]
	v_mfma_f32_16x16x32_bf16 v[36:39], v[162:165], v[194:197], v[36:39]
	v_mfma_f32_16x16x32_bf16 v[32:35], v[170:173], v[194:197], v[32:35]
	v_mfma_f32_16x16x32_bf16 v[20:23], v[162:165], v[210:213], v[20:23]
	v_mfma_f32_16x16x32_bf16 v[16:19], v[170:173], v[210:213], v[16:19]
	v_mfma_f32_16x16x32_bf16 v[4:7], v[162:165], v[218:221], v[4:7]
	v_mfma_f32_16x16x32_bf16 v[0:3], v[170:173], v[218:221], v[0:3]
	s_setprio 1
	s_barrier
	s_add_i32 s90, s90, 2
	s_add_u32 s80, s80, 0x100
	s_addc_u32 s81, s81, 0
	s_add_u32 s88, s88, 0x100
	s_addc_u32 s89, s89, 0
	s_cmp_gt_u32 s90, 13
	s_cbranch_scc0 .LBB0_660
	s_and_b64 vcc, exec, s[68:69]
	s_cbranch_vccz .LBB0_663
	s_barrier

; #define PG8_STAGE(bufoff, gbase, voff) do { _Pragma("unroll") for (int _i = 0; _i < 2; ++_i) \
;         __builtin_amdgcn_global_load_lds((const unsigned*)((const char*)(gbase) + (voff)[_i]), (PG8_LAS unsigned*)(lds + (bufoff) + ldsw + _i * 8192), 16, 0, 0); } while (0)
; #define PG8_LDA(dst, b, h) do { _Pragma("unroll") for (int m = 0; m < 4; ++m) _Pragma("unroll") for (int k = 0; k < 2; ++k) dst[m][k] = *(const PG8_LAS bf16x8*)(lds + PG8_SA(b, h) + aoff + m * 2048 + k * 1024); } while (0)
; #define PG8_LDB(dst, b, h) do { _Pragma("unroll") for (int n = 0; n < 2; ++n) _Pragma("unroll") for (int k = 0; k < 2; ++k) dst[n][k] = *(const PG8_LAS bf16x8*)(lds + PG8_SB(b, h) + boff + n * 2048 + k * 1024); } while (0)
; #define PG8_MMA(ai, bj, At, Bt) do { __builtin_amdgcn_s_setprio(1); _Pragma("unroll") for (int m = 0; m < 4; ++m) _Pragma("unroll") for (int n = 0; n < 2; ++n) _Pragma("unroll") for (int k = 0; k < 2; ++k) \
;         acc[ai][bj][m][n] = __builtin_amdgcn_mfma_f32_16x16x32_bf16(Bt[n][k], At[m][k], acc[ai][bj][m][n], 0, 0, 0); __builtin_amdgcn_s_setprio(0); } while (0)
; #define PG8_WAIT_V(n) asm volatile("s_waitcnt vmcnt(" #n ")" ::: "memory")
; #define PG8_WAIT_L(n) asm volatile("s_waitcnt lgkmcnt(" #n ")" ::: "memory")
; #define PG8_BAR __builtin_amdgcn_s_barrier()
; #define PG8_SCHED __builtin_amdgcn_sched_barrier(0)
; template <class Epi, class Sched, bool ALIGN_EPI = false, bool SP2 = false>
; __device__ __forceinline__ void gemm_phase(PG8_LAS unsigned char* lds, const Gemm g, const Sched& S, const Epi& E) {
;     ...
;             PG8_LDB(B0, 0, 0); PG8_LDB(B1, 0, 1); PG8_SCHED; PG8_LDA(At, 0, 0); PG8_STAGE(PG8_SA(1, 1), a1 + hstep, voffA);
;             PG8_WAIT_V(8); PG8_WAIT_L(0); PG8_BAR; PG8_MMA(0, 0, At, B0); PG8_MMA(0, 1, At, B1); PG8_BAR; PG8_SCHED;
;             PG8_LDA(At, 0, 1); PG8_STAGE(PG8_SB(0, 0), b2, voffB); PG8_STAGE(PG8_SB(0, 1), b2 + hstep, voffB); PG8_STAGE(PG8_SA(0, 0), a2, voffA);
;             PG8_WAIT_V(8); PG8_WAIT_L(0); PG8_BAR; PG8_MMA(1, 0, At, B0); PG8_MMA(1, 1, At, B1); PG8_BAR; PG8_SCHED;
.LBB0_730:
	ds_read_b128 v[128:131], v167
	ds_read_b128 v[132:135], v167 offset:1024
	ds_read_b128 v[136:139], v167 offset:2048
	ds_read_b128 v[140:143], v167 offset:3072
	ds_read_b128 v[158:161], v168
	ds_read_b128 v[162:165], v168 offset:1024
	ds_read_b128 v[174:177], v168 offset:2048
	ds_read_b128 v[178:181], v168 offset:3072
	s_add_u32 s60, s76, 0xfff50080
	s_addc_u32 s61, s77, -1
	s_cmp_eq_u32 s59, 40
	s_cselect_b32 s81, s73, s61
	s_cselect_b32 s80, s72, s60
	s_cselect_b32 s79, s75, s58
	s_cselect_b32 s78, s74, s57
	s_mov_b32 m0, s84
	v_lshl_add_u64 v[198:199], s[76:77], 0, v[154:155]
	ds_read_b128 v[182:185], v169
	ds_read_b128 v[186:189], v169 offset:1024
	ds_read_b128 v[190:193], v169 offset:2048
	ds_read_b128 v[194:197], v169 offset:3072
	ds_read_b128 v[206:209], v169 offset:4096
	ds_read_b128 v[210:213], v169 offset:5120
	ds_read_b128 v[214:217], v169 offset:6144
	ds_read_b128 v[218:221], v169 offset:7168
	global_load_lds_dwordx4 v[198:199], off
	v_lshl_add_u64 v[198:199], s[76:77], 0, v[156:157]
	s_mov_b32 m0, s85
	s_nop 0
	global_load_lds_dwordx4 v[198:199], off
	s_waitcnt vmcnt(8)
	s_waitcnt lgkmcnt(0)
	s_barrier
	s_setprio 0
	s_waitcnt lgkmcnt(0)
	v_mfma_f32_16x16x32_bf16 v[124:127], v[128:131], v[182:185], v[124:127]
	v_mfma_f32_16x16x32_bf16 v[120:123], v[136:139], v[182:185], v[120:123]
	v_mfma_f32_16x16x32_bf16 v[108:111], v[128:131], v[190:193], v[108:111]
	v_mfma_f32_16x16x32_bf16 v[104:107], v[136:139], v[190:193], v[104:107]
	v_mfma_f32_16x16x32_bf16 v[92:95], v[128:131], v[206:209], v[92:95]
	v_mfma_f32_16x16x32_bf16 v[88:91], v[136:139], v[206:209], v[88:91]
	v_mfma_f32_16x16x32_bf16 v[76:79], v[128:131], v[214:217], v[76:79]
	v_mfma_f32_16x16x32_bf16 v[72:75], v[136:139], v[214:217], v[72:75]
	v_mfma_f32_16x16x32_bf16 v[124:127], v[132:135], v[186:189], v[124:127]
	v_mfma_f32_16x16x32_bf16 v[120:123], v[140:143], v[186:189], v[120:123]
	v_mfma_f32_16x16x32_bf16 v[108:111], v[132:135], v[194:197], v[108:111]
	v_mfma_f32_16x16x32_bf16 v[104:107], v[140:143], v[194:197], v[104:107]
	v_mfma_f32_16x16x32_bf16 v[92:95], v[132:135], v[210:213], v[92:95]
	v_mfma_f32_16x16x32_bf16 v[88:91], v[140:143], v[210:213], v[88:91]
	v_mfma_f32_16x16x32_bf16 v[76:79], v[132:135], v[218:221], v[76:79]
	v_mfma_f32_16x16x32_bf16 v[72:75], v[140:143], v[218:221], v[72:75]
	v_mfma_f32_16x16x32_bf16 v[116:119], v[158:161], v[182:185], v[116:119]
	v_mfma_f32_16x16x32_bf16 v[112:115], v[174:177], v[182:185], v[112:115]
	v_mfma_f32_16x16x32_bf16 v[100:103], v[158:161], v[190:193], v[100:103]
	v_mfma_f32_16x16x32_bf16 v[96:99], v[174:177], v[190:193], v[96:99]
	v_mfma_f32_16x16x32_bf16 v[84:87], v[158:161], v[206:209], v[84:87]
	v_mfma_f32_16x16x32_bf16 v[80:83], v[174:177], v[206:209], v[80:83]
	v_mfma_f32_16x16x32_bf16 v[68:71], v[158:161], v[214:217], v[68:71]
	v_mfma_f32_16x16x32_bf16 v[64:67], v[174:177], v[214:217], v[64:67]
	v_mfma_f32_16x16x32_bf16 v[116:119], v[162:165], v[186:189], v[116:119]
	v_mfma_f32_16x16x32_bf16 v[112:115], v[178:181], v[186:189], v[112:115]
	v_mfma_f32_16x16x32_bf16 v[100:103], v[162:165], v[194:197], v[100:103]
	v_mfma_f32_16x16x32_bf16 v[96:99], v[178:181], v[194:197], v[96:99]
	v_mfma_f32_16x16x32_bf16 v[84:87], v[162:165], v[210:213], v[84:87]
	v_mfma_f32_16x16x32_bf16 v[80:83], v[178:181], v[210:213], v[80:83]
	v_mfma_f32_16x16x32_bf16 v[68:71], v[162:165], v[218:221], v[68:71]
	v_mfma_f32_16x16x32_bf16 v[64:67], v[178:181], v[218:221], v[64:67]
	s_setprio 1
	s_barrier
	s_mov_b32 m0, s86
	v_lshl_add_u64 v[198:199], s[78:79], 0, v[148:149]
	s_add_u32 vcc_lo, s78, 0xb0000
	ds_read_b128 v[182:185], v169 offset:16384
	ds_read_b128 v[186:189], v169 offset:17408
	ds_read_b128 v[190:193], v169 offset:18432
	ds_read_b128 v[194:197], v169 offset:19456
	ds_read_b128 v[206:209], v169 offset:20480
	ds_read_b128 v[210:213], v169 offset:21504
	ds_read_b128 v[214:217], v169 offset:22528
	ds_read_b128 v[218:221], v169 offset:23552
	global_load_lds_dwordx4 v[198:199], off
	v_lshl_add_u64 v[222:223], s[78:79], 0, v[152:153]
	s_mov_b32 m0, s87
	s_addc_u32 vcc_hi, s79, 0
	global_load_lds_dwordx4 v[222:223], off
	v_lshl_add_u64 v[224:225], vcc, 0, v[148:149]
	s_mov_b32 m0, s88
	v_lshl_add_u64 v[226:227], s[80:81], 0, v[150:151]
	global_load_lds_dwordx4 v[224:225], off
	v_lshl_add_u64 v[224:225], vcc, 0, v[152:153]
	s_mov_b32 m0, s89
	s_nop 0
	global_load_lds_dwordx4 v[224:225], off
	v_lshl_add_u64 v[224:225], s[80:81], 0, v[146:147]
	s_mov_b32 m0, s29
	s_nop 0
	global_load_lds_dwordx4 v[224:225], off
	s_mov_b32 m0, s30
	s_nop 0
	global_load_lds_dwordx4 v[226:227], off
	s_waitcnt vmcnt(8)
	s_waitcnt lgkmcnt(0)
	s_barrier
; #define PG8_STAGE(bufoff, gbase, voff) do { _Pragma("unroll") for (int _i = 0; _i < 2; ++_i) \
;         __builtin_amdgcn_global_load_lds((const unsigned*)((const char*)(gbase) + (voff)[_i]), (PG8_LAS unsigned*)(lds + (bufoff) + ldsw + _i * 8192), 16, 0, 0); } while (0)
; #define PG8_LDA(dst, b, h) do { _Pragma("unroll") for (int m = 0; m < 4; ++m) _Pragma("unroll") for (int k = 0; k < 2; ++k) dst[m][k] = *(const PG8_LAS bf16x8*)(lds + PG8_SA(b, h) + aoff + m * 2048 + k * 1024); } while (0)
; #define PG8_LDB(dst, b, h) do { _Pragma("unroll") for (int n = 0; n < 2; ++n) _Pragma("unroll") for (int k = 0; k < 2; ++k) dst[n][k] = *(const PG8_LAS bf16x8*)(lds + PG8_SB(b, h) + boff + n * 2048 + k * 1024); } while (0)
; #define PG8_MMA(ai, bj, At, Bt) do { __builtin_amdgcn_s_setprio(1); _Pragma("unroll") for (int m = 0; m < 4; ++m) _Pragma("unroll") for (int n = 0; n < 2; ++n) _Pragma("unroll") for (int k = 0; k < 2; ++k) \
;         acc[ai][bj][m][n] = __builtin_amdgcn_mfma_f32_16x16x32_bf16(Bt[n][k], At[m][k], acc[ai][bj][m][n], 0, 0, 0); __builtin_amdgcn_s_setprio(0); } while (0)
; #define PG8_WAIT_V(n) asm volatile("s_waitcnt vmcnt(" #n ")" ::: "memory")
; #define PG8_WAIT_L(n) asm volatile("s_waitcnt lgkmcnt(" #n ")" ::: "memory")
; #define PG8_BAR __builtin_amdgcn_s_barrier()
; #define PG8_SCHED __builtin_amdgcn_sched_barrier(0)
; template <class Epi, class Sched, bool ALIGN_EPI = false, bool SP2 = false>
; __device__ __forceinline__ void gemm_phase(PG8_LAS unsigned char* lds, const Gemm g, const Sched& S, const Epi& E) {
;     ...
;             PG8_WAIT_V(8); PG8_WAIT_L(0); PG8_BAR; PG8_MMA(1, 0, At, B0); PG8_MMA(1, 1, At, B1); PG8_BAR; PG8_SCHED;
;             PG8_LDB(B0, 1, 0); PG8_LDB(B1, 1, 1); PG8_SCHED; PG8_LDA(At, 1, 0); PG8_STAGE(PG8_SA(0, 1), a2 + hstep, voffA);
;             PG8_WAIT_V(8); PG8_WAIT_L(0); PG8_BAR; PG8_MMA(0, 0, At, B0); PG8_MMA(0, 1, At, B1); PG8_BAR; PG8_SCHED;
	s_setprio 0
	s_waitcnt lgkmcnt(0)
	v_mfma_f32_16x16x32_bf16 v[60:63], v[128:131], v[182:185], v[60:63]
	v_mfma_f32_16x16x32_bf16 v[56:59], v[136:139], v[182:185], v[56:59]
	v_mfma_f32_16x16x32_bf16 v[44:47], v[128:131], v[190:193], v[44:47]
	v_mfma_f32_16x16x32_bf16 v[40:43], v[136:139], v[190:193], v[40:43]
	v_mfma_f32_16x16x32_bf16 v[32:35], v[128:131], v[206:209], v[32:35]
	v_mfma_f32_16x16x32_bf16 v[24:27], v[136:139], v[206:209], v[24:27]
	v_mfma_f32_16x16x32_bf16 v[16:19], v[128:131], v[214:217], v[16:19]
	v_mfma_f32_16x16x32_bf16 v[8:11], v[136:139], v[214:217], v[8:11]
	v_mfma_f32_16x16x32_bf16 v[60:63], v[132:135], v[186:189], v[60:63]
	v_mfma_f32_16x16x32_bf16 v[56:59], v[140:143], v[186:189], v[56:59]
	v_mfma_f32_16x16x32_bf16 v[44:47], v[132:135], v[194:197], v[44:47]
	v_mfma_f32_16x16x32_bf16 v[40:43], v[140:143], v[194:197], v[40:43]
	v_mfma_f32_16x16x32_bf16 v[32:35], v[132:135], v[210:213], v[32:35]
	v_mfma_f32_16x16x32_bf16 v[24:27], v[140:143], v[210:213], v[24:27]
	v_mfma_f32_16x16x32_bf16 v[16:19], v[132:135], v[218:221], v[16:19]
	v_mfma_f32_16x16x32_bf16 v[8:11], v[140:143], v[218:221], v[8:11]
	v_mfma_f32_16x16x32_bf16 v[52:55], v[158:161], v[182:185], v[52:55]
	v_mfma_f32_16x16x32_bf16 v[48:51], v[174:177], v[182:185], v[48:51]
	v_mfma_f32_16x16x32_bf16 v[36:39], v[158:161], v[190:193], v[36:39]
	v_mfma_f32_16x16x32_bf16 v[28:31], v[174:177], v[190:193], v[28:31]
	v_mfma_f32_16x16x32_bf16 v[20:23], v[158:161], v[206:209], v[20:23]
	v_mfma_f32_16x16x32_bf16 v[12:15], v[174:177], v[206:209], v[12:15]
	v_mfma_f32_16x16x32_bf16 v[4:7], v[158:161], v[214:217], v[4:7]
	v_mfma_f32_16x16x32_bf16 v[0:3], v[174:177], v[214:217], v[0:3]
	v_mfma_f32_16x16x32_bf16 v[52:55], v[162:165], v[186:189], v[52:55]
	v_mfma_f32_16x16x32_bf16 v[48:51], v[178:181], v[186:189], v[48:51]
	v_mfma_f32_16x16x32_bf16 v[36:39], v[162:165], v[194:197], v[36:39]
	v_mfma_f32_16x16x32_bf16 v[28:31], v[178:181], v[194:197], v[28:31]
	v_mfma_f32_16x16x32_bf16 v[20:23], v[162:165], v[210:213], v[20:23]
	v_mfma_f32_16x16x32_bf16 v[12:15], v[178:181], v[210:213], v[12:15]
	v_mfma_f32_16x16x32_bf16 v[4:7], v[162:165], v[218:221], v[4:7]
	v_mfma_f32_16x16x32_bf16 v[0:3], v[178:181], v[218:221], v[0:3]
	s_setprio 1
	s_barrier
	ds_read_b128 v[128:131], v171
	ds_read_b128 v[132:135], v171 offset:1024
	ds_read_b128 v[136:139], v171 offset:2048
	ds_read_b128 v[140:143], v171 offset:3072
	ds_read_b128 v[158:161], v172
	ds_read_b128 v[162:165], v172 offset:1024
	ds_read_b128 v[174:177], v172 offset:2048
	ds_read_b128 v[178:181], v172 offset:3072
	s_add_u32 s80, s80, 0xb0000
	s_addc_u32 s81, s81, 0
	s_mov_b32 m0, s31
	v_lshl_add_u64 v[228:229], s[80:81], 0, v[146:147]
	ds_read_b128 v[182:185], v169 offset:32768
	ds_read_b128 v[186:189], v169 offset:33792
	ds_read_b128 v[190:193], v169 offset:34816
	ds_read_b128 v[194:197], v169 offset:35840
	ds_read_b128 v[206:209], v169 offset:36864
	ds_read_b128 v[210:213], v169 offset:37888
	ds_read_b128 v[214:217], v169 offset:38912
	ds_read_b128 v[218:221], v169 offset:39936
	global_load_lds_dwordx4 v[228:229], off
	v_lshl_add_u64 v[228:229], s[80:81], 0, v[150:151]
	s_mov_b32 m0, s37
	s_nop 0
	global_load_lds_dwordx4 v[228:229], off
	s_waitcnt vmcnt(8)
	s_waitcnt lgkmcnt(0)
	s_barrier
	s_setprio 0
	s_waitcnt lgkmcnt(0)
	v_mfma_f32_16x16x32_bf16 v[124:127], v[128:131], v[182:185], v[124:127]
	v_mfma_f32_16x16x32_bf16 v[120:123], v[136:139], v[182:185], v[120:123]
	v_mfma_f32_16x16x32_bf16 v[108:111], v[128:131], v[190:193], v[108:111]
	v_mfma_f32_16x16x32_bf16 v[104:107], v[136:139], v[190:193], v[104:107]
	v_mfma_f32_16x16x32_bf16 v[92:95], v[128:131], v[206:209], v[92:95]
	v_mfma_f32_16x16x32_bf16 v[88:91], v[136:139], v[206:209], v[88:91]
	v_mfma_f32_16x16x32_bf16 v[76:79], v[128:131], v[214:217], v[76:79]
	v_mfma_f32_16x16x32_bf16 v[72:75], v[136:139], v[214:217], v[72:75]
	v_mfma_f32_16x16x32_bf16 v[124:127], v[132:135], v[186:189], v[124:127]
	v_mfma_f32_16x16x32_bf16 v[120:123], v[140:143], v[186:189], v[120:123]
	v_mfma_f32_16x16x32_bf16 v[108:111], v[132:135], v[194:197], v[108:111]
	v_mfma_f32_16x16x32_bf16 v[104:107], v[140:143], v[194:197], v[104:107]
	v_mfma_f32_16x16x32_bf16 v[92:95], v[132:135], v[210:213], v[92:95]
	v_mfma_f32_16x16x32_bf16 v[88:91], v[140:143], v[210:213], v[88:91]
	v_mfma_f32_16x16x32_bf16 v[76:79], v[132:135], v[218:221], v[76:79]
	v_mfma_f32_16x16x32_bf16 v[72:75], v[140:143], v[218:221], v[72:75]
	v_mfma_f32_16x16x32_bf16 v[116:119], v[158:161], v[182:185], v[116:119]
	v_mfma_f32_16x16x32_bf16 v[112:115], v[174:177], v[182:185], v[112:115]
	v_mfma_f32_16x16x32_bf16 v[100:103], v[158:161], v[190:193], v[100:103]
	v_mfma_f32_16x16x32_bf16 v[96:99], v[174:177], v[190:193], v[96:99]
	v_mfma_f32_16x16x32_bf16 v[84:87], v[158:161], v[206:209], v[84:87]
	v_mfma_f32_16x16x32_bf16 v[80:83], v[174:177], v[206:209], v[80:83]
	v_mfma_f32_16x16x32_bf16 v[68:71], v[158:161], v[214:217], v[68:71]
	v_mfma_f32_16x16x32_bf16 v[64:67], v[174:177], v[214:217], v[64:67]
	v_mfma_f32_16x16x32_bf16 v[116:119], v[162:165], v[186:189], v[116:119]
	v_mfma_f32_16x16x32_bf16 v[112:115], v[178:181], v[186:189], v[112:115]
	v_mfma_f32_16x16x32_bf16 v[100:103], v[162:165], v[194:197], v[100:103]
	v_mfma_f32_16x16x32_bf16 v[96:99], v[178:181], v[194:197], v[96:99]
	v_mfma_f32_16x16x32_bf16 v[84:87], v[162:165], v[210:213], v[84:87]
	v_mfma_f32_16x16x32_bf16 v[80:83], v[178:181], v[210:213], v[80:83]
	v_mfma_f32_16x16x32_bf16 v[68:71], v[162:165], v[218:221], v[68:71]
	v_mfma_f32_16x16x32_bf16 v[64:67], v[178:181], v[218:221], v[64:67]
	s_setprio 1
	s_barrier
; #define PG8_STAGE(bufoff, gbase, voff) do { _Pragma("unroll") for (int _i = 0; _i < 2; ++_i) \
;         __builtin_amdgcn_global_load_lds((const unsigned*)((const char*)(gbase) + (voff)[_i]), (PG8_LAS unsigned*)(lds + (bufoff) + ldsw + _i * 8192), 16, 0, 0); } while (0)
; #define PG8_LDA(dst, b, h) do { _Pragma("unroll") for (int m = 0; m < 4; ++m) _Pragma("unroll") for (int k = 0; k < 2; ++k) dst[m][k] = *(const PG8_LAS bf16x8*)(lds + PG8_SA(b, h) + aoff + m * 2048 + k * 1024); } while (0)
; #define PG8_MMA(ai, bj, At, Bt) do { __builtin_amdgcn_s_setprio(1); _Pragma("unroll") for (int m = 0; m < 4; ++m) _Pragma("unroll") for (int n = 0; n < 2; ++n) _Pragma("unroll") for (int k = 0; k < 2; ++k) \
;         acc[ai][bj][m][n] = __builtin_amdgcn_mfma_f32_16x16x32_bf16(Bt[n][k], At[m][k], acc[ai][bj][m][n], 0, 0, 0); __builtin_amdgcn_s_setprio(0); } while (0)
; #define PG8_WAIT_V(n) asm volatile("s_waitcnt vmcnt(" #n ")" ::: "memory")
; #define PG8_WAIT_L(n) asm volatile("s_waitcnt lgkmcnt(" #n ")" ::: "memory")
; #define PG8_BAR __builtin_amdgcn_s_barrier()
; #define PG8_SCHED __builtin_amdgcn_sched_barrier(0)
; template <class Epi, class Sched, bool ALIGN_EPI = false, bool SP2 = false>
; __device__ __forceinline__ void gemm_phase(PG8_LAS unsigned char* lds, const Gemm g, const Sched& S, const Epi& E) {
;     ...
;             PG8_LDA(At, 1, 1); PG8_STAGE(PG8_SB(1, 0), b3, voffB); PG8_STAGE(PG8_SB(1, 1), b3 + hstep, voffB); PG8_STAGE(PG8_SA(1, 0), a3, voffA);
;             PG8_WAIT_V(8); PG8_WAIT_L(0); PG8_BAR; PG8_MMA(1, 0, At, B0); PG8_MMA(1, 1, At, B1); PG8_BAR; PG8_SCHED;
	s_add_i32 s60, s90, s28
	v_lshl_add_u64 v[198:199], v[198:199], 0, s[68:69]
	s_mov_b32 m0, s60
	ds_read_b128 v[182:185], v169 offset:49152
	ds_read_b128 v[186:189], v169 offset:50176
	ds_read_b128 v[190:193], v169 offset:51200
	ds_read_b128 v[194:197], v169 offset:52224
	ds_read_b128 v[206:209], v169 offset:53248
	ds_read_b128 v[210:213], v169 offset:54272
	ds_read_b128 v[214:217], v169 offset:55296
	ds_read_b128 v[218:221], v169 offset:56320
	global_load_lds_dwordx4 v[198:199], off
	s_add_i32 m0, s60, 0x2000
	s_add_u32 s78, s78, 0xb0080
	v_lshl_add_u64 v[198:199], v[222:223], 0, s[68:69]
	s_addc_u32 s79, s79, 0
	s_add_i32 s60, s91, s28
	global_load_lds_dwordx4 v[198:199], off
	v_lshl_add_u64 v[198:199], s[78:79], 0, v[148:149]
	s_mov_b32 m0, s60
	s_nop 0
	global_load_lds_dwordx4 v[198:199], off
	v_lshl_add_u64 v[198:199], s[78:79], 0, v[152:153]
	s_add_i32 m0, s60, 0x2000
	s_nop 0
	global_load_lds_dwordx4 v[198:199], off
	v_lshl_add_u64 v[198:199], v[224:225], 0, s[68:69]
	s_mov_b32 m0, s82
	s_nop 0
	global_load_lds_dwordx4 v[198:199], off
	v_lshl_add_u64 v[198:199], v[226:227], 0, s[68:69]
	s_mov_b32 m0, s83
	s_nop 0
	global_load_lds_dwordx4 v[198:199], off
	s_waitcnt vmcnt(8)
	s_waitcnt lgkmcnt(0)
	s_barrier
	s_setprio 0
	s_waitcnt lgkmcnt(0)
	v_mfma_f32_16x16x32_bf16 v[60:63], v[128:131], v[182:185], v[60:63]
	v_mfma_f32_16x16x32_bf16 v[56:59], v[136:139], v[182:185], v[56:59]
	v_mfma_f32_16x16x32_bf16 v[44:47], v[128:131], v[190:193], v[44:47]
	v_mfma_f32_16x16x32_bf16 v[40:43], v[136:139], v[190:193], v[40:43]
	v_mfma_f32_16x16x32_bf16 v[32:35], v[128:131], v[206:209], v[32:35]
	v_mfma_f32_16x16x32_bf16 v[24:27], v[136:139], v[206:209], v[24:27]
	v_mfma_f32_16x16x32_bf16 v[16:19], v[128:131], v[214:217], v[16:19]
	v_mfma_f32_16x16x32_bf16 v[8:11], v[136:139], v[214:217], v[8:11]
	v_mfma_f32_16x16x32_bf16 v[60:63], v[132:135], v[186:189], v[60:63]
	v_mfma_f32_16x16x32_bf16 v[56:59], v[140:143], v[186:189], v[56:59]
	v_mfma_f32_16x16x32_bf16 v[44:47], v[132:135], v[194:197], v[44:47]
	v_mfma_f32_16x16x32_bf16 v[40:43], v[140:143], v[194:197], v[40:43]
	v_mfma_f32_16x16x32_bf16 v[32:35], v[132:135], v[210:213], v[32:35]
	v_mfma_f32_16x16x32_bf16 v[24:27], v[140:143], v[210:213], v[24:27]
	v_mfma_f32_16x16x32_bf16 v[16:19], v[132:135], v[218:221], v[16:19]
	v_mfma_f32_16x16x32_bf16 v[8:11], v[140:143], v[218:221], v[8:11]
	v_mfma_f32_16x16x32_bf16 v[52:55], v[158:161], v[182:185], v[52:55]
	v_mfma_f32_16x16x32_bf16 v[48:51], v[174:177], v[182:185], v[48:51]
	v_mfma_f32_16x16x32_bf16 v[36:39], v[158:161], v[190:193], v[36:39]
	v_mfma_f32_16x16x32_bf16 v[28:31], v[174:177], v[190:193], v[28:31]
	v_mfma_f32_16x16x32_bf16 v[20:23], v[158:161], v[206:209], v[20:23]
	v_mfma_f32_16x16x32_bf16 v[12:15], v[174:177], v[206:209], v[12:15]
	v_mfma_f32_16x16x32_bf16 v[4:7], v[158:161], v[214:217], v[4:7]
	v_mfma_f32_16x16x32_bf16 v[0:3], v[174:177], v[214:217], v[0:3]
	v_mfma_f32_16x16x32_bf16 v[52:55], v[162:165], v[186:189], v[52:55]
	v_mfma_f32_16x16x32_bf16 v[48:51], v[178:181], v[186:189], v[48:51]
	v_mfma_f32_16x16x32_bf16 v[36:39], v[162:165], v[194:197], v[36:39]
	v_mfma_f32_16x16x32_bf16 v[28:31], v[178:181], v[194:197], v[28:31]
	v_mfma_f32_16x16x32_bf16 v[20:23], v[162:165], v[210:213], v[20:23]
	v_mfma_f32_16x16x32_bf16 v[12:15], v[178:181], v[210:213], v[12:15]
	v_mfma_f32_16x16x32_bf16 v[4:7], v[162:165], v[218:221], v[4:7]
	v_mfma_f32_16x16x32_bf16 v[0:3], v[178:181], v[218:221], v[0:3]
	s_setprio 1
	s_barrier
	s_add_i32 s59, s59, 2
	s_add_u32 s76, s76, 0x100
	s_addc_u32 s77, s77, 0
	s_add_u32 s57, s57, 0x100
	s_addc_u32 s58, s58, 0
	s_cmp_gt_u32 s59, 41
	s_cbranch_scc0 .LBB0_730
	s_and_b64 vcc, exec, s[70:71]
	s_cbranch_vccz .LBB0_733
	s_barrier

; #define PG8_STAGE(bufoff, gbase, voff) do { _Pragma("unroll") for (int _i = 0; _i < 2; ++_i) \
;         __builtin_amdgcn_global_load_lds((const unsigned*)((const char*)(gbase) + (voff)[_i]), (PG8_LAS unsigned*)(lds + (bufoff) + ldsw + _i * 8192), 16, 0, 0); } while (0)
; #define PG8_LDA(dst, b, h) do { _Pragma("unroll") for (int m = 0; m < 4; ++m) _Pragma("unroll") for (int k = 0; k < 2; ++k) dst[m][k] = *(const PG8_LAS bf16x8*)(lds + PG8_SA(b, h) + aoff + m * 2048 + k * 1024); } while (0)
; #define PG8_LDB(dst, b, h) do { _Pragma("unroll") for (int n = 0; n < 2; ++n) _Pragma("unroll") for (int k = 0; k < 2; ++k) dst[n][k] = *(const PG8_LAS bf16x8*)(lds + PG8_SB(b, h) + boff + n * 2048 + k * 1024); } while (0)
; #define PG8_MMA(ai, bj, At, Bt) do { __builtin_amdgcn_s_setprio(1); _Pragma("unroll") for (int m = 0; m < 4; ++m) _Pragma("unroll") for (int n = 0; n < 2; ++n) _Pragma("unroll") for (int k = 0; k < 2; ++k) \
;         acc[ai][bj][m][n] = __builtin_amdgcn_mfma_f32_16x16x32_bf16(Bt[n][k], At[m][k], acc[ai][bj][m][n], 0, 0, 0); __builtin_amdgcn_s_setprio(0); } while (0)
; #define PG8_WAIT_V(n) asm volatile("s_waitcnt vmcnt(" #n ")" ::: "memory")
; #define PG8_WAIT_L(n) asm volatile("s_waitcnt lgkmcnt(" #n ")" ::: "memory")
; #define PG8_BAR __builtin_amdgcn_s_barrier()
; #define PG8_SCHED __builtin_amdgcn_sched_barrier(0)
; template <class Epi, class Sched, bool ALIGN_EPI = false, bool SP2 = false>
; __device__ __forceinline__ void gemm_phase(PG8_LAS unsigned char* lds, const Gemm g, const Sched& S, const Epi& E) {
;     ...
;             PG8_LDB(B0, 0, 0); PG8_LDB(B1, 0, 1); PG8_SCHED; PG8_LDA(At, 0, 0); PG8_STAGE(PG8_SA(1, 1), a1 + hstep, voffA);
;             PG8_WAIT_V(8); PG8_WAIT_L(0); PG8_BAR; PG8_MMA(0, 0, At, B0); PG8_MMA(0, 1, At, B1); PG8_BAR; PG8_SCHED;
;             PG8_LDA(At, 0, 1); PG8_STAGE(PG8_SB(0, 0), b2, voffB); PG8_STAGE(PG8_SB(0, 1), b2 + hstep, voffB); PG8_STAGE(PG8_SA(0, 0), a2, voffA);
;             PG8_WAIT_V(8); PG8_WAIT_L(0); PG8_BAR; PG8_MMA(1, 0, At, B0); PG8_MMA(1, 1, At, B1); PG8_BAR; PG8_SCHED;
.LBB0_958:
	ds_read_b128 v[140:143], v163
	ds_read_b128 v[146:149], v163 offset:1024
	ds_read_b128 v[150:153], v163 offset:2048
	ds_read_b128 v[154:157], v163 offset:3072
	ds_read_b128 v[168:171], v164
	ds_read_b128 v[172:175], v164 offset:1024
	ds_read_b128 v[176:179], v164 offset:2048
	ds_read_b128 v[180:183], v164 offset:3072
	s_add_u32 s59, s86, 0xfffc0080
	s_addc_u32 s60, s87, -1
	s_cmp_eq_u32 s58, 12
	s_cselect_b32 s91, s7, s60
	s_cselect_b32 s90, s75, s59
	s_cselect_b32 s89, s77, vcc_hi
	s_cselect_b32 s88, s85, vcc_lo
	v_lshl_add_u64 v[158:159], s[86:87], 0, v[136:137]
	s_add_i32 m0, s20, 0xc000
	ds_read_b128 v[184:187], v165
	ds_read_b128 v[188:191], v165 offset:1024
	ds_read_b128 v[192:195], v165 offset:2048
	ds_read_b128 v[196:199], v165 offset:3072
	ds_read_b128 v[206:209], v165 offset:4096
	ds_read_b128 v[210:213], v165 offset:5120
	ds_read_b128 v[214:217], v165 offset:6144
	ds_read_b128 v[218:221], v165 offset:7168
	global_load_lds_dwordx4 v[158:159], off
	v_lshl_add_u64 v[158:159], s[86:87], 0, v[138:139]
	s_add_i32 m0, s20, 0xe000
	s_nop 0
	global_load_lds_dwordx4 v[158:159], off
	s_waitcnt vmcnt(8)
	s_waitcnt lgkmcnt(0)
	s_barrier
	s_setprio 0
	s_waitcnt lgkmcnt(0)
	v_mfma_f32_16x16x32_bf16 v[124:127], v[140:143], v[184:187], v[124:127]
	v_mfma_f32_16x16x32_bf16 v[120:123], v[150:153], v[184:187], v[120:123]
	v_mfma_f32_16x16x32_bf16 v[108:111], v[140:143], v[192:195], v[108:111]
	v_mfma_f32_16x16x32_bf16 v[104:107], v[150:153], v[192:195], v[104:107]
	v_mfma_f32_16x16x32_bf16 v[92:95], v[140:143], v[206:209], v[92:95]
	v_mfma_f32_16x16x32_bf16 v[88:91], v[150:153], v[206:209], v[88:91]
	v_mfma_f32_16x16x32_bf16 v[76:79], v[140:143], v[214:217], v[76:79]
	v_mfma_f32_16x16x32_bf16 v[72:75], v[150:153], v[214:217], v[72:75]
	v_mfma_f32_16x16x32_bf16 v[124:127], v[146:149], v[188:191], v[124:127]
	v_mfma_f32_16x16x32_bf16 v[120:123], v[154:157], v[188:191], v[120:123]
	v_mfma_f32_16x16x32_bf16 v[108:111], v[146:149], v[196:199], v[108:111]
	v_mfma_f32_16x16x32_bf16 v[104:107], v[154:157], v[196:199], v[104:107]
	v_mfma_f32_16x16x32_bf16 v[92:95], v[146:149], v[210:213], v[92:95]
	v_mfma_f32_16x16x32_bf16 v[88:91], v[154:157], v[210:213], v[88:91]
	v_mfma_f32_16x16x32_bf16 v[76:79], v[146:149], v[218:221], v[76:79]
	v_mfma_f32_16x16x32_bf16 v[72:75], v[154:157], v[218:221], v[72:75]
	v_mfma_f32_16x16x32_bf16 v[116:119], v[168:171], v[184:187], v[116:119]
	v_mfma_f32_16x16x32_bf16 v[112:115], v[176:179], v[184:187], v[112:115]
	v_mfma_f32_16x16x32_bf16 v[100:103], v[168:171], v[192:195], v[100:103]
	v_mfma_f32_16x16x32_bf16 v[96:99], v[176:179], v[192:195], v[96:99]
	v_mfma_f32_16x16x32_bf16 v[84:87], v[168:171], v[206:209], v[84:87]
	v_mfma_f32_16x16x32_bf16 v[80:83], v[176:179], v[206:209], v[80:83]
	v_mfma_f32_16x16x32_bf16 v[68:71], v[168:171], v[214:217], v[68:71]
	v_mfma_f32_16x16x32_bf16 v[64:67], v[176:179], v[214:217], v[64:67]
	v_mfma_f32_16x16x32_bf16 v[116:119], v[172:175], v[188:191], v[116:119]
	v_mfma_f32_16x16x32_bf16 v[112:115], v[180:183], v[188:191], v[112:115]
	v_mfma_f32_16x16x32_bf16 v[100:103], v[172:175], v[196:199], v[100:103]
	v_mfma_f32_16x16x32_bf16 v[96:99], v[180:183], v[196:199], v[96:99]
	v_mfma_f32_16x16x32_bf16 v[84:87], v[172:175], v[210:213], v[84:87]
	v_mfma_f32_16x16x32_bf16 v[80:83], v[180:183], v[210:213], v[80:83]
	v_mfma_f32_16x16x32_bf16 v[68:71], v[172:175], v[218:221], v[68:71]
	v_mfma_f32_16x16x32_bf16 v[64:67], v[180:183], v[218:221], v[64:67]
	s_setprio 1
	s_barrier
	s_add_i32 s59, s39, s11
	v_lshl_add_u64 v[158:159], s[88:89], 0, v[130:131]
	s_mov_b32 m0, s59
	ds_read_b128 v[184:187], v165 offset:16384
	ds_read_b128 v[188:191], v165 offset:17408
	ds_read_b128 v[192:195], v165 offset:18432
	ds_read_b128 v[196:199], v165 offset:19456
	ds_read_b128 v[206:209], v165 offset:20480
	ds_read_b128 v[210:213], v165 offset:21504
	ds_read_b128 v[214:217], v165 offset:22528
	ds_read_b128 v[218:221], v165 offset:23552
	global_load_lds_dwordx4 v[158:159], off
	s_add_i32 m0, s59, 0x2000
	s_add_u32 s60, s88, 0x40000
	v_lshl_add_u64 v[222:223], s[88:89], 0, v[134:135]
	s_addc_u32 s61, s89, 0
	s_add_i32 s59, s56, s11
	global_load_lds_dwordx4 v[222:223], off
	v_lshl_add_u64 v[224:225], s[60:61], 0, v[130:131]
	s_mov_b32 m0, s59
	v_lshl_add_u64 v[226:227], s[90:91], 0, v[132:133]
	global_load_lds_dwordx4 v[224:225], off
	v_lshl_add_u64 v[224:225], s[60:61], 0, v[134:135]
	s_add_i32 m0, s59, 0x2000
	s_nop 0
	global_load_lds_dwordx4 v[224:225], off
	v_lshl_add_u64 v[224:225], s[90:91], 0, v[128:129]
	s_mov_b32 m0, s20
	s_nop 0
	global_load_lds_dwordx4 v[224:225], off
	s_mov_b32 m0, s21
	s_nop 0
	global_load_lds_dwordx4 v[226:227], off
	s_waitcnt vmcnt(8)
	s_waitcnt lgkmcnt(0)
	s_barrier
; #define PG8_STAGE(bufoff, gbase, voff) do { _Pragma("unroll") for (int _i = 0; _i < 2; ++_i) \
;         __builtin_amdgcn_global_load_lds((const unsigned*)((const char*)(gbase) + (voff)[_i]), (PG8_LAS unsigned*)(lds + (bufoff) + ldsw + _i * 8192), 16, 0, 0); } while (0)
; #define PG8_LDA(dst, b, h) do { _Pragma("unroll") for (int m = 0; m < 4; ++m) _Pragma("unroll") for (int k = 0; k < 2; ++k) dst[m][k] = *(const PG8_LAS bf16x8*)(lds + PG8_SA(b, h) + aoff + m * 2048 + k * 1024); } while (0)
; #define PG8_LDB(dst, b, h) do { _Pragma("unroll") for (int n = 0; n < 2; ++n) _Pragma("unroll") for (int k = 0; k < 2; ++k) dst[n][k] = *(const PG8_LAS bf16x8*)(lds + PG8_SB(b, h) + boff + n * 2048 + k * 1024); } while (0)
; #define PG8_MMA(ai, bj, At, Bt) do { __builtin_amdgcn_s_setprio(1); _Pragma("unroll") for (int m = 0; m < 4; ++m) _Pragma("unroll") for (int n = 0; n < 2; ++n) _Pragma("unroll") for (int k = 0; k < 2; ++k) \
;         acc[ai][bj][m][n] = __builtin_amdgcn_mfma_f32_16x16x32_bf16(Bt[n][k], At[m][k], acc[ai][bj][m][n], 0, 0, 0); __builtin_amdgcn_s_setprio(0); } while (0)
; #define PG8_WAIT_V(n) asm volatile("s_waitcnt vmcnt(" #n ")" ::: "memory")
; #define PG8_WAIT_L(n) asm volatile("s_waitcnt lgkmcnt(" #n ")" ::: "memory")
; #define PG8_BAR __builtin_amdgcn_s_barrier()
; #define PG8_SCHED __builtin_amdgcn_sched_barrier(0)
; template <class Epi, class Sched, bool ALIGN_EPI = false, bool SP2 = false>
; __device__ __forceinline__ void gemm_phase(PG8_LAS unsigned char* lds, const Gemm g, const Sched& S, const Epi& E) {
;     ...
;             PG8_WAIT_V(8); PG8_WAIT_L(0); PG8_BAR; PG8_MMA(1, 0, At, B0); PG8_MMA(1, 1, At, B1); PG8_BAR; PG8_SCHED;
;             PG8_LDB(B0, 1, 0); PG8_LDB(B1, 1, 1); PG8_SCHED; PG8_LDA(At, 1, 0); PG8_STAGE(PG8_SA(0, 1), a2 + hstep, voffA);
;             PG8_WAIT_V(8); PG8_WAIT_L(0); PG8_BAR; PG8_MMA(0, 0, At, B0); PG8_MMA(0, 1, At, B1); PG8_BAR; PG8_SCHED;
	s_setprio 0
	s_waitcnt lgkmcnt(0)
	v_mfma_f32_16x16x32_bf16 v[60:63], v[140:143], v[184:187], v[60:63]
	v_mfma_f32_16x16x32_bf16 v[56:59], v[150:153], v[184:187], v[56:59]
	v_mfma_f32_16x16x32_bf16 v[44:47], v[140:143], v[192:195], v[44:47]
	v_mfma_f32_16x16x32_bf16 v[40:43], v[150:153], v[192:195], v[40:43]
	v_mfma_f32_16x16x32_bf16 v[28:31], v[140:143], v[206:209], v[28:31]
	v_mfma_f32_16x16x32_bf16 v[24:27], v[150:153], v[206:209], v[24:27]
	v_mfma_f32_16x16x32_bf16 v[12:15], v[140:143], v[214:217], v[12:15]
	v_mfma_f32_16x16x32_bf16 v[8:11], v[150:153], v[214:217], v[8:11]
	v_mfma_f32_16x16x32_bf16 v[60:63], v[146:149], v[188:191], v[60:63]
	v_mfma_f32_16x16x32_bf16 v[56:59], v[154:157], v[188:191], v[56:59]
	v_mfma_f32_16x16x32_bf16 v[44:47], v[146:149], v[196:199], v[44:47]
	v_mfma_f32_16x16x32_bf16 v[40:43], v[154:157], v[196:199], v[40:43]
	v_mfma_f32_16x16x32_bf16 v[28:31], v[146:149], v[210:213], v[28:31]
	v_mfma_f32_16x16x32_bf16 v[24:27], v[154:157], v[210:213], v[24:27]
	v_mfma_f32_16x16x32_bf16 v[12:15], v[146:149], v[218:221], v[12:15]
	v_mfma_f32_16x16x32_bf16 v[8:11], v[154:157], v[218:221], v[8:11]
	v_mfma_f32_16x16x32_bf16 v[52:55], v[168:171], v[184:187], v[52:55]
	v_mfma_f32_16x16x32_bf16 v[48:51], v[176:179], v[184:187], v[48:51]
	v_mfma_f32_16x16x32_bf16 v[36:39], v[168:171], v[192:195], v[36:39]
	v_mfma_f32_16x16x32_bf16 v[32:35], v[176:179], v[192:195], v[32:35]
	v_mfma_f32_16x16x32_bf16 v[20:23], v[168:171], v[206:209], v[20:23]
	v_mfma_f32_16x16x32_bf16 v[16:19], v[176:179], v[206:209], v[16:19]
	v_mfma_f32_16x16x32_bf16 v[4:7], v[168:171], v[214:217], v[4:7]
	v_mfma_f32_16x16x32_bf16 v[0:3], v[176:179], v[214:217], v[0:3]
	v_mfma_f32_16x16x32_bf16 v[52:55], v[172:175], v[188:191], v[52:55]
	v_mfma_f32_16x16x32_bf16 v[48:51], v[180:183], v[188:191], v[48:51]
	v_mfma_f32_16x16x32_bf16 v[36:39], v[172:175], v[196:199], v[36:39]
	v_mfma_f32_16x16x32_bf16 v[32:35], v[180:183], v[196:199], v[32:35]
	v_mfma_f32_16x16x32_bf16 v[20:23], v[172:175], v[210:213], v[20:23]
	v_mfma_f32_16x16x32_bf16 v[16:19], v[180:183], v[210:213], v[16:19]
	v_mfma_f32_16x16x32_bf16 v[4:7], v[172:175], v[218:221], v[4:7]
	v_mfma_f32_16x16x32_bf16 v[0:3], v[180:183], v[218:221], v[0:3]
	s_setprio 1
	s_barrier
	s_add_i32 s59, 0, 0x18000
	s_add_i32 s96, 0, 0x1c000
	v_add_u32_e32 v154, s59, v161
	v_add_u32_e32 v180, s96, v161
	ds_read_b128 v[140:143], v154
	ds_read_b128 v[146:149], v154 offset:1024
	ds_read_b128 v[150:153], v154 offset:2048
	ds_read_b128 v[154:157], v154 offset:3072
	ds_read_b128 v[168:171], v180
	ds_read_b128 v[172:175], v180 offset:1024
	ds_read_b128 v[176:179], v180 offset:2048
	ds_read_b128 v[180:183], v180 offset:3072
	s_add_u32 s60, s90, 0x40000
	s_addc_u32 s61, s91, 0
	s_mov_b32 m0, s28
	v_lshl_add_u64 v[228:229], s[60:61], 0, v[128:129]
	ds_read_b128 v[184:187], v165 offset:32768
	ds_read_b128 v[188:191], v165 offset:33792
	ds_read_b128 v[192:195], v165 offset:34816
	ds_read_b128 v[196:199], v165 offset:35840
	ds_read_b128 v[206:209], v165 offset:36864
	ds_read_b128 v[210:213], v165 offset:37888
	ds_read_b128 v[214:217], v165 offset:38912
	ds_read_b128 v[218:221], v165 offset:39936
	global_load_lds_dwordx4 v[228:229], off
	v_lshl_add_u64 v[228:229], s[60:61], 0, v[132:133]
	s_mov_b32 m0, s29
	s_nop 0
	global_load_lds_dwordx4 v[228:229], off
	s_waitcnt vmcnt(8)
	s_waitcnt lgkmcnt(0)
	s_barrier
	s_setprio 0
	s_waitcnt lgkmcnt(0)
	v_mfma_f32_16x16x32_bf16 v[124:127], v[140:143], v[184:187], v[124:127]
	v_mfma_f32_16x16x32_bf16 v[120:123], v[150:153], v[184:187], v[120:123]
	v_mfma_f32_16x16x32_bf16 v[108:111], v[140:143], v[192:195], v[108:111]
	v_mfma_f32_16x16x32_bf16 v[104:107], v[150:153], v[192:195], v[104:107]
	v_mfma_f32_16x16x32_bf16 v[92:95], v[140:143], v[206:209], v[92:95]
	v_mfma_f32_16x16x32_bf16 v[88:91], v[150:153], v[206:209], v[88:91]
	v_mfma_f32_16x16x32_bf16 v[76:79], v[140:143], v[214:217], v[76:79]
	v_mfma_f32_16x16x32_bf16 v[72:75], v[150:153], v[214:217], v[72:75]
	v_mfma_f32_16x16x32_bf16 v[124:127], v[146:149], v[188:191], v[124:127]
	v_mfma_f32_16x16x32_bf16 v[120:123], v[154:157], v[188:191], v[120:123]
	v_mfma_f32_16x16x32_bf16 v[108:111], v[146:149], v[196:199], v[108:111]
	v_mfma_f32_16x16x32_bf16 v[104:107], v[154:157], v[196:199], v[104:107]
	v_mfma_f32_16x16x32_bf16 v[92:95], v[146:149], v[210:213], v[92:95]
	v_mfma_f32_16x16x32_bf16 v[88:91], v[154:157], v[210:213], v[88:91]
	v_mfma_f32_16x16x32_bf16 v[76:79], v[146:149], v[218:221], v[76:79]
	v_mfma_f32_16x16x32_bf16 v[72:75], v[154:157], v[218:221], v[72:75]
	v_mfma_f32_16x16x32_bf16 v[116:119], v[168:171], v[184:187], v[116:119]
	v_mfma_f32_16x16x32_bf16 v[112:115], v[176:179], v[184:187], v[112:115]
	v_mfma_f32_16x16x32_bf16 v[100:103], v[168:171], v[192:195], v[100:103]
	v_mfma_f32_16x16x32_bf16 v[96:99], v[176:179], v[192:195], v[96:99]
	v_mfma_f32_16x16x32_bf16 v[84:87], v[168:171], v[206:209], v[84:87]
	v_mfma_f32_16x16x32_bf16 v[80:83], v[176:179], v[206:209], v[80:83]
	v_mfma_f32_16x16x32_bf16 v[68:71], v[168:171], v[214:217], v[68:71]
	v_mfma_f32_16x16x32_bf16 v[64:67], v[176:179], v[214:217], v[64:67]
	v_mfma_f32_16x16x32_bf16 v[116:119], v[172:175], v[188:191], v[116:119]
	v_mfma_f32_16x16x32_bf16 v[112:115], v[180:183], v[188:191], v[112:115]
	v_mfma_f32_16x16x32_bf16 v[100:103], v[172:175], v[196:199], v[100:103]
	v_mfma_f32_16x16x32_bf16 v[96:99], v[180:183], v[196:199], v[96:99]
	v_mfma_f32_16x16x32_bf16 v[84:87], v[172:175], v[210:213], v[84:87]
	v_mfma_f32_16x16x32_bf16 v[80:83], v[180:183], v[210:213], v[80:83]
	v_mfma_f32_16x16x32_bf16 v[68:71], v[172:175], v[218:221], v[68:71]
	v_mfma_f32_16x16x32_bf16 v[64:67], v[180:183], v[218:221], v[64:67]
	s_setprio 1
	s_barrier
; #define PG8_STAGE(bufoff, gbase, voff) do { _Pragma("unroll") for (int _i = 0; _i < 2; ++_i) \
;         __builtin_amdgcn_global_load_lds((const unsigned*)((const char*)(gbase) + (voff)[_i]), (PG8_LAS unsigned*)(lds + (bufoff) + ldsw + _i * 8192), 16, 0, 0); } while (0)
; #define PG8_LDA(dst, b, h) do { _Pragma("unroll") for (int m = 0; m < 4; ++m) _Pragma("unroll") for (int k = 0; k < 2; ++k) dst[m][k] = *(const PG8_LAS bf16x8*)(lds + PG8_SA(b, h) + aoff + m * 2048 + k * 1024); } while (0)
; #define PG8_MMA(ai, bj, At, Bt) do { __builtin_amdgcn_s_setprio(1); _Pragma("unroll") for (int m = 0; m < 4; ++m) _Pragma("unroll") for (int n = 0; n < 2; ++n) _Pragma("unroll") for (int k = 0; k < 2; ++k) \
;         acc[ai][bj][m][n] = __builtin_amdgcn_mfma_f32_16x16x32_bf16(Bt[n][k], At[m][k], acc[ai][bj][m][n], 0, 0, 0); __builtin_amdgcn_s_setprio(0); } while (0)
; #define PG8_WAIT_V(n) asm volatile("s_waitcnt vmcnt(" #n ")" ::: "memory")
; #define PG8_WAIT_L(n) asm volatile("s_waitcnt lgkmcnt(" #n ")" ::: "memory")
; #define PG8_BAR __builtin_amdgcn_s_barrier()
; #define PG8_SCHED __builtin_amdgcn_sched_barrier(0)
; template <class Epi, class Sched, bool ALIGN_EPI = false, bool SP2 = false>
; __device__ __forceinline__ void gemm_phase(PG8_LAS unsigned char* lds, const Gemm g, const Sched& S, const Epi& E) {
;     ...
;             PG8_LDA(At, 1, 1); PG8_STAGE(PG8_SB(1, 0), b3, voffB); PG8_STAGE(PG8_SB(1, 1), b3 + hstep, voffB); PG8_STAGE(PG8_SA(1, 0), a3, voffA);
;             PG8_WAIT_V(8); PG8_WAIT_L(0); PG8_BAR; PG8_MMA(1, 0, At, B0); PG8_MMA(1, 1, At, B1); PG8_BAR; PG8_SCHED;
	s_add_i32 s59, s59, s11
	v_lshl_add_u64 v[158:159], v[158:159], 0, s[70:71]
	s_mov_b32 m0, s59
	ds_read_b128 v[184:187], v165 offset:49152
	ds_read_b128 v[188:191], v165 offset:50176
	ds_read_b128 v[192:195], v165 offset:51200
	ds_read_b128 v[196:199], v165 offset:52224
	ds_read_b128 v[206:209], v165 offset:53248
	ds_read_b128 v[210:213], v165 offset:54272
	ds_read_b128 v[214:217], v165 offset:55296
	ds_read_b128 v[218:221], v165 offset:56320
	global_load_lds_dwordx4 v[158:159], off
	s_add_i32 m0, s59, 0x2000
	s_add_u32 s60, s88, 0x40080
	v_lshl_add_u64 v[158:159], v[222:223], 0, s[70:71]
	s_addc_u32 s61, s89, 0
	s_add_i32 s59, s96, s11
	global_load_lds_dwordx4 v[158:159], off
	v_lshl_add_u64 v[158:159], s[60:61], 0, v[130:131]
	s_mov_b32 m0, s59
	s_nop 0
	global_load_lds_dwordx4 v[158:159], off
	v_lshl_add_u64 v[158:159], s[60:61], 0, v[134:135]
	s_add_i32 m0, s59, 0x2000
	s_nop 0
	global_load_lds_dwordx4 v[158:159], off
	v_lshl_add_u64 v[158:159], v[224:225], 0, s[70:71]
	s_mov_b32 m0, s31
	s_nop 0
	global_load_lds_dwordx4 v[158:159], off
	v_lshl_add_u64 v[158:159], v[226:227], 0, s[70:71]
	s_mov_b32 m0, s37
	s_nop 0
	global_load_lds_dwordx4 v[158:159], off
	s_waitcnt vmcnt(8)
	s_waitcnt lgkmcnt(0)
	s_barrier
	s_setprio 0
	s_waitcnt lgkmcnt(0)
	v_mfma_f32_16x16x32_bf16 v[60:63], v[140:143], v[184:187], v[60:63]
	v_mfma_f32_16x16x32_bf16 v[56:59], v[150:153], v[184:187], v[56:59]
	v_mfma_f32_16x16x32_bf16 v[44:47], v[140:143], v[192:195], v[44:47]
	v_mfma_f32_16x16x32_bf16 v[40:43], v[150:153], v[192:195], v[40:43]
	v_mfma_f32_16x16x32_bf16 v[28:31], v[140:143], v[206:209], v[28:31]
	v_mfma_f32_16x16x32_bf16 v[24:27], v[150:153], v[206:209], v[24:27]
	v_mfma_f32_16x16x32_bf16 v[12:15], v[140:143], v[214:217], v[12:15]
	v_mfma_f32_16x16x32_bf16 v[8:11], v[150:153], v[214:217], v[8:11]
	v_mfma_f32_16x16x32_bf16 v[60:63], v[146:149], v[188:191], v[60:63]
	v_mfma_f32_16x16x32_bf16 v[56:59], v[154:157], v[188:191], v[56:59]
	v_mfma_f32_16x16x32_bf16 v[44:47], v[146:149], v[196:199], v[44:47]
	v_mfma_f32_16x16x32_bf16 v[40:43], v[154:157], v[196:199], v[40:43]
	v_mfma_f32_16x16x32_bf16 v[28:31], v[146:149], v[210:213], v[28:31]
	v_mfma_f32_16x16x32_bf16 v[24:27], v[154:157], v[210:213], v[24:27]
	v_mfma_f32_16x16x32_bf16 v[12:15], v[146:149], v[218:221], v[12:15]
	v_mfma_f32_16x16x32_bf16 v[8:11], v[154:157], v[218:221], v[8:11]
	v_mfma_f32_16x16x32_bf16 v[52:55], v[168:171], v[184:187], v[52:55]
	v_mfma_f32_16x16x32_bf16 v[48:51], v[176:179], v[184:187], v[48:51]
	v_mfma_f32_16x16x32_bf16 v[36:39], v[168:171], v[192:195], v[36:39]
	v_mfma_f32_16x16x32_bf16 v[32:35], v[176:179], v[192:195], v[32:35]
	v_mfma_f32_16x16x32_bf16 v[20:23], v[168:171], v[206:209], v[20:23]
	v_mfma_f32_16x16x32_bf16 v[16:19], v[176:179], v[206:209], v[16:19]
	v_mfma_f32_16x16x32_bf16 v[4:7], v[168:171], v[214:217], v[4:7]
	v_mfma_f32_16x16x32_bf16 v[0:3], v[176:179], v[214:217], v[0:3]
	v_mfma_f32_16x16x32_bf16 v[52:55], v[172:175], v[188:191], v[52:55]
	v_mfma_f32_16x16x32_bf16 v[48:51], v[180:183], v[188:191], v[48:51]
	v_mfma_f32_16x16x32_bf16 v[36:39], v[172:175], v[196:199], v[36:39]
	v_mfma_f32_16x16x32_bf16 v[32:35], v[180:183], v[196:199], v[32:35]
	v_mfma_f32_16x16x32_bf16 v[20:23], v[172:175], v[210:213], v[20:23]
	v_mfma_f32_16x16x32_bf16 v[16:19], v[180:183], v[210:213], v[16:19]
	v_mfma_f32_16x16x32_bf16 v[4:7], v[172:175], v[218:221], v[4:7]
	v_mfma_f32_16x16x32_bf16 v[0:3], v[180:183], v[218:221], v[0:3]
	s_setprio 1
	s_barrier
	s_add_i32 s58, s58, 2
	s_add_u32 s86, s86, 0x100
	s_addc_u32 s87, s87, 0
	s_add_u32 vcc_lo, vcc_lo, 0x100
	s_addc_u32 vcc_hi, vcc_hi, 0
	s_cmp_gt_u32 s58, 13
	s_cbranch_scc0 .LBB0_958
	s_and_b64 vcc, exec, s[72:73]
	s_cbranch_vccz .LBB0_961
	s_barrier

; #define PG8_STAGE(bufoff, gbase, voff) do { _Pragma("unroll") for (int _i = 0; _i < 2; ++_i) \
;         __builtin_amdgcn_global_load_lds((const unsigned*)((const char*)(gbase) + (voff)[_i]), (PG8_LAS unsigned*)(lds + (bufoff) + ldsw + _i * 8192), 16, 0, 0); } while (0)
; #define PG8_LDA(dst, b, h) do { _Pragma("unroll") for (int m = 0; m < 4; ++m) _Pragma("unroll") for (int k = 0; k < 2; ++k) dst[m][k] = *(const PG8_LAS bf16x8*)(lds + PG8_SA(b, h) + aoff + m * 2048 + k * 1024); } while (0)
; #define PG8_LDB(dst, b, h) do { _Pragma("unroll") for (int n = 0; n < 2; ++n) _Pragma("unroll") for (int k = 0; k < 2; ++k) dst[n][k] = *(const PG8_LAS bf16x8*)(lds + PG8_SB(b, h) + boff + n * 2048 + k * 1024); } while (0)
; #define PG8_MMA(ai, bj, At, Bt) do { __builtin_amdgcn_s_setprio(1); _Pragma("unroll") for (int m = 0; m < 4; ++m) _Pragma("unroll") for (int n = 0; n < 2; ++n) _Pragma("unroll") for (int k = 0; k < 2; ++k) \
;         acc[ai][bj][m][n] = __builtin_amdgcn_mfma_f32_16x16x32_bf16(Bt[n][k], At[m][k], acc[ai][bj][m][n], 0, 0, 0); __builtin_amdgcn_s_setprio(0); } while (0)
; #define PG8_WAIT_V(n) asm volatile("s_waitcnt vmcnt(" #n ")" ::: "memory")
; #define PG8_WAIT_L(n) asm volatile("s_waitcnt lgkmcnt(" #n ")" ::: "memory")
; #define PG8_BAR __builtin_amdgcn_s_barrier()
; #define PG8_SCHED __builtin_amdgcn_sched_barrier(0)
; template <class Epi, class Sched, bool ALIGN_EPI = false, bool SP2 = false>
; __device__ __forceinline__ void gemm_phase(PG8_LAS unsigned char* lds, const Gemm g, const Sched& S, const Epi& E) {
;     ...
;             PG8_LDB(B0, 0, 0); PG8_LDB(B1, 0, 1); PG8_SCHED; PG8_LDA(At, 0, 0); PG8_STAGE(PG8_SA(1, 1), a1 + hstep, voffA);
;             PG8_WAIT_V(8); PG8_WAIT_L(0); PG8_BAR; PG8_MMA(0, 0, At, B0); PG8_MMA(0, 1, At, B1); PG8_BAR; PG8_SCHED;
;             PG8_LDA(At, 0, 1); PG8_STAGE(PG8_SB(0, 0), b2, voffB); PG8_STAGE(PG8_SB(0, 1), b2 + hstep, voffB); PG8_STAGE(PG8_SA(0, 0), a2, voffA);
;             PG8_WAIT_V(8); PG8_WAIT_L(0); PG8_BAR; PG8_MMA(1, 0, At, B0); PG8_MMA(1, 1, At, B1); PG8_BAR; PG8_SCHED;
.LBB0_1215:
	ds_read_b128 v[140:143], v149
	ds_read_b128 v[154:157], v149 offset:1024
	ds_read_b128 v[158:161], v149 offset:2048
	ds_read_b128 v[162:165], v149 offset:3072
	ds_read_b128 v[166:169], v150
	ds_read_b128 v[170:173], v150 offset:1024
	ds_read_b128 v[174:177], v150 offset:2048
	ds_read_b128 v[178:181], v150 offset:3072
	s_add_u32 s60, s58, 0xfffc0080
	s_addc_u32 s61, s59, -1
	s_cmp_eq_u32 s75, 12
	s_cselect_b32 s63, s17, s61
	s_cselect_b32 s62, s51, s60
	s_cselect_b32 s61, s19, s74
	s_cselect_b32 s60, s72, s73
	v_lshl_add_u64 v[144:145], s[58:59], 0, v[136:137]
	s_add_i32 m0, s28, 0xc000
	ds_read_b128 v[182:185], v151
	ds_read_b128 v[186:189], v151 offset:1024
	ds_read_b128 v[190:193], v151 offset:2048
	ds_read_b128 v[194:197], v151 offset:3072
	ds_read_b128 v[202:205], v151 offset:4096
	ds_read_b128 v[206:209], v151 offset:5120
	ds_read_b128 v[210:213], v151 offset:6144
	ds_read_b128 v[214:217], v151 offset:7168
	global_load_lds_dwordx4 v[144:145], off
	v_lshl_add_u64 v[144:145], s[58:59], 0, v[138:139]
	s_add_i32 m0, s28, 0xe000
	s_nop 0
	global_load_lds_dwordx4 v[144:145], off
	s_waitcnt vmcnt(8)
	s_waitcnt lgkmcnt(0)
	s_barrier
	s_setprio 0
	s_waitcnt lgkmcnt(0)
	v_mfma_f32_16x16x32_bf16 v[124:127], v[140:143], v[182:185], v[124:127]
	v_mfma_f32_16x16x32_bf16 v[120:123], v[158:161], v[182:185], v[120:123]
	v_mfma_f32_16x16x32_bf16 v[108:111], v[140:143], v[190:193], v[108:111]
	v_mfma_f32_16x16x32_bf16 v[104:107], v[158:161], v[190:193], v[104:107]
	v_mfma_f32_16x16x32_bf16 v[96:99], v[140:143], v[202:205], v[96:99]
	v_mfma_f32_16x16x32_bf16 v[88:91], v[158:161], v[202:205], v[88:91]
	v_mfma_f32_16x16x32_bf16 v[80:83], v[140:143], v[210:213], v[80:83]
	v_mfma_f32_16x16x32_bf16 v[72:75], v[158:161], v[210:213], v[72:75]
	v_mfma_f32_16x16x32_bf16 v[124:127], v[154:157], v[186:189], v[124:127]
	v_mfma_f32_16x16x32_bf16 v[120:123], v[162:165], v[186:189], v[120:123]
	v_mfma_f32_16x16x32_bf16 v[108:111], v[154:157], v[194:197], v[108:111]
	v_mfma_f32_16x16x32_bf16 v[104:107], v[162:165], v[194:197], v[104:107]
	v_mfma_f32_16x16x32_bf16 v[96:99], v[154:157], v[206:209], v[96:99]
	v_mfma_f32_16x16x32_bf16 v[88:91], v[162:165], v[206:209], v[88:91]
	v_mfma_f32_16x16x32_bf16 v[80:83], v[154:157], v[214:217], v[80:83]
	v_mfma_f32_16x16x32_bf16 v[72:75], v[162:165], v[214:217], v[72:75]
	v_mfma_f32_16x16x32_bf16 v[116:119], v[166:169], v[182:185], v[116:119]
	v_mfma_f32_16x16x32_bf16 v[112:115], v[174:177], v[182:185], v[112:115]
	v_mfma_f32_16x16x32_bf16 v[100:103], v[166:169], v[190:193], v[100:103]
	v_mfma_f32_16x16x32_bf16 v[92:95], v[174:177], v[190:193], v[92:95]
	v_mfma_f32_16x16x32_bf16 v[84:87], v[166:169], v[202:205], v[84:87]
	v_mfma_f32_16x16x32_bf16 v[76:79], v[174:177], v[202:205], v[76:79]
	v_mfma_f32_16x16x32_bf16 v[68:71], v[166:169], v[210:213], v[68:71]
	v_mfma_f32_16x16x32_bf16 v[64:67], v[174:177], v[210:213], v[64:67]
	v_mfma_f32_16x16x32_bf16 v[116:119], v[170:173], v[186:189], v[116:119]
	v_mfma_f32_16x16x32_bf16 v[112:115], v[178:181], v[186:189], v[112:115]
	v_mfma_f32_16x16x32_bf16 v[100:103], v[170:173], v[194:197], v[100:103]
	v_mfma_f32_16x16x32_bf16 v[92:95], v[178:181], v[194:197], v[92:95]
	v_mfma_f32_16x16x32_bf16 v[84:87], v[170:173], v[206:209], v[84:87]
	v_mfma_f32_16x16x32_bf16 v[76:79], v[178:181], v[206:209], v[76:79]
	v_mfma_f32_16x16x32_bf16 v[68:71], v[170:173], v[214:217], v[68:71]
	v_mfma_f32_16x16x32_bf16 v[64:67], v[178:181], v[214:217], v[64:67]
	s_setprio 1
	s_barrier
	s_add_i32 s76, s66, s21
	v_lshl_add_u64 v[144:145], s[60:61], 0, v[130:131]
	s_mov_b32 m0, s76
	ds_read_b128 v[182:185], v151 offset:16384
	ds_read_b128 v[186:189], v151 offset:17408
	ds_read_b128 v[190:193], v151 offset:18432
	ds_read_b128 v[194:197], v151 offset:19456
	ds_read_b128 v[202:205], v151 offset:20480
	ds_read_b128 v[206:209], v151 offset:21504
	ds_read_b128 v[210:213], v151 offset:22528
	ds_read_b128 v[214:217], v151 offset:23552
	global_load_lds_dwordx4 v[144:145], off
	s_add_i32 m0, s76, 0x2000
	s_add_u32 s76, s60, 0x40000
	v_lshl_add_u64 v[198:199], s[60:61], 0, v[134:135]
	s_addc_u32 s77, s61, 0
	s_add_i32 s78, s67, s21
	global_load_lds_dwordx4 v[198:199], off
	v_lshl_add_u64 v[218:219], s[76:77], 0, v[130:131]
	s_mov_b32 m0, s78
	v_lshl_add_u64 v[220:221], s[62:63], 0, v[132:133]
	global_load_lds_dwordx4 v[218:219], off
	v_lshl_add_u64 v[218:219], s[76:77], 0, v[134:135]
	s_add_i32 m0, s78, 0x2000
	s_nop 0
	global_load_lds_dwordx4 v[218:219], off
	v_lshl_add_u64 v[218:219], s[62:63], 0, v[128:129]
	s_mov_b32 m0, s28
	s_nop 0
	global_load_lds_dwordx4 v[218:219], off
	s_mov_b32 m0, s29
	s_nop 0
	global_load_lds_dwordx4 v[220:221], off
	s_waitcnt vmcnt(8)
	s_waitcnt lgkmcnt(0)
	s_barrier
; #define PG8_STAGE(bufoff, gbase, voff) do { _Pragma("unroll") for (int _i = 0; _i < 2; ++_i) \
;         __builtin_amdgcn_global_load_lds((const unsigned*)((const char*)(gbase) + (voff)[_i]), (PG8_LAS unsigned*)(lds + (bufoff) + ldsw + _i * 8192), 16, 0, 0); } while (0)
; #define PG8_LDA(dst, b, h) do { _Pragma("unroll") for (int m = 0; m < 4; ++m) _Pragma("unroll") for (int k = 0; k < 2; ++k) dst[m][k] = *(const PG8_LAS bf16x8*)(lds + PG8_SA(b, h) + aoff + m * 2048 + k * 1024); } while (0)
; #define PG8_LDB(dst, b, h) do { _Pragma("unroll") for (int n = 0; n < 2; ++n) _Pragma("unroll") for (int k = 0; k < 2; ++k) dst[n][k] = *(const PG8_LAS bf16x8*)(lds + PG8_SB(b, h) + boff + n * 2048 + k * 1024); } while (0)
; #define PG8_MMA(ai, bj, At, Bt) do { __builtin_amdgcn_s_setprio(1); _Pragma("unroll") for (int m = 0; m < 4; ++m) _Pragma("unroll") for (int n = 0; n < 2; ++n) _Pragma("unroll") for (int k = 0; k < 2; ++k) \
;         acc[ai][bj][m][n] = __builtin_amdgcn_mfma_f32_16x16x32_bf16(Bt[n][k], At[m][k], acc[ai][bj][m][n], 0, 0, 0); __builtin_amdgcn_s_setprio(0); } while (0)
; #define PG8_WAIT_V(n) asm volatile("s_waitcnt vmcnt(" #n ")" ::: "memory")
; #define PG8_WAIT_L(n) asm volatile("s_waitcnt lgkmcnt(" #n ")" ::: "memory")
; #define PG8_BAR __builtin_amdgcn_s_barrier()
; #define PG8_SCHED __builtin_amdgcn_sched_barrier(0)
; template <class Epi, class Sched, bool ALIGN_EPI = false, bool SP2 = false>
; __device__ __forceinline__ void gemm_phase(PG8_LAS unsigned char* lds, const Gemm g, const Sched& S, const Epi& E) {
;     ...
;             PG8_WAIT_V(8); PG8_WAIT_L(0); PG8_BAR; PG8_MMA(1, 0, At, B0); PG8_MMA(1, 1, At, B1); PG8_BAR; PG8_SCHED;
;             PG8_LDB(B0, 1, 0); PG8_LDB(B1, 1, 1); PG8_SCHED; PG8_LDA(At, 1, 0); PG8_STAGE(PG8_SA(0, 1), a2 + hstep, voffA);
;             PG8_WAIT_V(8); PG8_WAIT_L(0); PG8_BAR; PG8_MMA(0, 0, At, B0); PG8_MMA(0, 1, At, B1); PG8_BAR; PG8_SCHED;
	s_setprio 0
	s_waitcnt lgkmcnt(0)
	v_mfma_f32_16x16x32_bf16 v[60:63], v[140:143], v[182:185], v[60:63]
	v_mfma_f32_16x16x32_bf16 v[56:59], v[158:161], v[182:185], v[56:59]
	v_mfma_f32_16x16x32_bf16 v[48:51], v[140:143], v[190:193], v[48:51]
	v_mfma_f32_16x16x32_bf16 v[40:43], v[158:161], v[190:193], v[40:43]
	v_mfma_f32_16x16x32_bf16 v[32:35], v[140:143], v[202:205], v[32:35]
	v_mfma_f32_16x16x32_bf16 v[24:27], v[158:161], v[202:205], v[24:27]
	v_mfma_f32_16x16x32_bf16 v[16:19], v[140:143], v[210:213], v[16:19]
	v_mfma_f32_16x16x32_bf16 v[8:11], v[158:161], v[210:213], v[8:11]
	v_mfma_f32_16x16x32_bf16 v[60:63], v[154:157], v[186:189], v[60:63]
	v_mfma_f32_16x16x32_bf16 v[56:59], v[162:165], v[186:189], v[56:59]
	v_mfma_f32_16x16x32_bf16 v[48:51], v[154:157], v[194:197], v[48:51]
	v_mfma_f32_16x16x32_bf16 v[40:43], v[162:165], v[194:197], v[40:43]
	v_mfma_f32_16x16x32_bf16 v[32:35], v[154:157], v[206:209], v[32:35]
	v_mfma_f32_16x16x32_bf16 v[24:27], v[162:165], v[206:209], v[24:27]
	v_mfma_f32_16x16x32_bf16 v[16:19], v[154:157], v[214:217], v[16:19]
	v_mfma_f32_16x16x32_bf16 v[8:11], v[162:165], v[214:217], v[8:11]
	v_mfma_f32_16x16x32_bf16 v[52:55], v[166:169], v[182:185], v[52:55]
	v_mfma_f32_16x16x32_bf16 v[44:47], v[174:177], v[182:185], v[44:47]
	v_mfma_f32_16x16x32_bf16 v[36:39], v[166:169], v[190:193], v[36:39]
	v_mfma_f32_16x16x32_bf16 v[28:31], v[174:177], v[190:193], v[28:31]
	v_mfma_f32_16x16x32_bf16 v[20:23], v[166:169], v[202:205], v[20:23]
	v_mfma_f32_16x16x32_bf16 v[12:15], v[174:177], v[202:205], v[12:15]
	v_mfma_f32_16x16x32_bf16 v[4:7], v[166:169], v[210:213], v[4:7]
	v_mfma_f32_16x16x32_bf16 v[0:3], v[174:177], v[210:213], v[0:3]
	v_mfma_f32_16x16x32_bf16 v[52:55], v[170:173], v[186:189], v[52:55]
	v_mfma_f32_16x16x32_bf16 v[44:47], v[178:181], v[186:189], v[44:47]
	v_mfma_f32_16x16x32_bf16 v[36:39], v[170:173], v[194:197], v[36:39]
	v_mfma_f32_16x16x32_bf16 v[28:31], v[178:181], v[194:197], v[28:31]
	v_mfma_f32_16x16x32_bf16 v[20:23], v[170:173], v[206:209], v[20:23]
	v_mfma_f32_16x16x32_bf16 v[12:15], v[178:181], v[206:209], v[12:15]
	v_mfma_f32_16x16x32_bf16 v[4:7], v[170:173], v[214:217], v[4:7]
	v_mfma_f32_16x16x32_bf16 v[0:3], v[178:181], v[214:217], v[0:3]
	s_setprio 1
	s_barrier
	s_add_i32 s76, 0, 0x18000
	v_add_u32_e32 v153, s76, v147
	s_add_i32 s77, 0, 0x1c000
	ds_read_b128 v[140:143], v153
	ds_read_b128 v[154:157], v153 offset:1024
	ds_read_b128 v[158:161], v153 offset:2048
	ds_read_b128 v[162:165], v153 offset:3072
	v_add_u32_e32 v153, s77, v147
	ds_read_b128 v[166:169], v153
	ds_read_b128 v[170:173], v153 offset:1024
	ds_read_b128 v[174:177], v153 offset:2048
	ds_read_b128 v[178:181], v153 offset:3072
	s_add_u32 s62, s62, 0x40000
	s_addc_u32 s63, s63, 0
	s_mov_b32 m0, s30
	v_lshl_add_u64 v[222:223], s[62:63], 0, v[128:129]
	ds_read_b128 v[182:185], v151 offset:32768
	ds_read_b128 v[186:189], v151 offset:33792
	ds_read_b128 v[190:193], v151 offset:34816
	ds_read_b128 v[194:197], v151 offset:35840
	ds_read_b128 v[202:205], v151 offset:36864
	ds_read_b128 v[206:209], v151 offset:37888
	ds_read_b128 v[210:213], v151 offset:38912
	ds_read_b128 v[214:217], v151 offset:39936
	global_load_lds_dwordx4 v[222:223], off
	v_lshl_add_u64 v[222:223], s[62:63], 0, v[132:133]
	s_mov_b32 m0, s31
	s_nop 0
	global_load_lds_dwordx4 v[222:223], off
	s_waitcnt vmcnt(8)
	s_waitcnt lgkmcnt(0)
	s_barrier
	s_setprio 0
	s_waitcnt lgkmcnt(0)
	v_mfma_f32_16x16x32_bf16 v[124:127], v[140:143], v[182:185], v[124:127]
	v_mfma_f32_16x16x32_bf16 v[120:123], v[158:161], v[182:185], v[120:123]
	v_mfma_f32_16x16x32_bf16 v[108:111], v[140:143], v[190:193], v[108:111]
	v_mfma_f32_16x16x32_bf16 v[104:107], v[158:161], v[190:193], v[104:107]
	v_mfma_f32_16x16x32_bf16 v[96:99], v[140:143], v[202:205], v[96:99]
	v_mfma_f32_16x16x32_bf16 v[88:91], v[158:161], v[202:205], v[88:91]
	v_mfma_f32_16x16x32_bf16 v[80:83], v[140:143], v[210:213], v[80:83]
	v_mfma_f32_16x16x32_bf16 v[72:75], v[158:161], v[210:213], v[72:75]
	v_mfma_f32_16x16x32_bf16 v[124:127], v[154:157], v[186:189], v[124:127]
	v_mfma_f32_16x16x32_bf16 v[120:123], v[162:165], v[186:189], v[120:123]
	v_mfma_f32_16x16x32_bf16 v[108:111], v[154:157], v[194:197], v[108:111]
	v_mfma_f32_16x16x32_bf16 v[104:107], v[162:165], v[194:197], v[104:107]
	v_mfma_f32_16x16x32_bf16 v[96:99], v[154:157], v[206:209], v[96:99]
	v_mfma_f32_16x16x32_bf16 v[88:91], v[162:165], v[206:209], v[88:91]
	v_mfma_f32_16x16x32_bf16 v[80:83], v[154:157], v[214:217], v[80:83]
	v_mfma_f32_16x16x32_bf16 v[72:75], v[162:165], v[214:217], v[72:75]
	v_mfma_f32_16x16x32_bf16 v[116:119], v[166:169], v[182:185], v[116:119]
	v_mfma_f32_16x16x32_bf16 v[112:115], v[174:177], v[182:185], v[112:115]
	v_mfma_f32_16x16x32_bf16 v[100:103], v[166:169], v[190:193], v[100:103]
	v_mfma_f32_16x16x32_bf16 v[92:95], v[174:177], v[190:193], v[92:95]
	v_mfma_f32_16x16x32_bf16 v[84:87], v[166:169], v[202:205], v[84:87]
	v_mfma_f32_16x16x32_bf16 v[76:79], v[174:177], v[202:205], v[76:79]
	v_mfma_f32_16x16x32_bf16 v[68:71], v[166:169], v[210:213], v[68:71]
	v_mfma_f32_16x16x32_bf16 v[64:67], v[174:177], v[210:213], v[64:67]
	v_mfma_f32_16x16x32_bf16 v[116:119], v[170:173], v[186:189], v[116:119]
	v_mfma_f32_16x16x32_bf16 v[112:115], v[178:181], v[186:189], v[112:115]
	v_mfma_f32_16x16x32_bf16 v[100:103], v[170:173], v[194:197], v[100:103]
	v_mfma_f32_16x16x32_bf16 v[92:95], v[178:181], v[194:197], v[92:95]
	v_mfma_f32_16x16x32_bf16 v[84:87], v[170:173], v[206:209], v[84:87]
	v_mfma_f32_16x16x32_bf16 v[76:79], v[178:181], v[206:209], v[76:79]
	v_mfma_f32_16x16x32_bf16 v[68:71], v[170:173], v[214:217], v[68:71]
	v_mfma_f32_16x16x32_bf16 v[64:67], v[178:181], v[214:217], v[64:67]
	s_setprio 1
	s_barrier
; #define PG8_STAGE(bufoff, gbase, voff) do { _Pragma("unroll") for (int _i = 0; _i < 2; ++_i) \
;         __builtin_amdgcn_global_load_lds((const unsigned*)((const char*)(gbase) + (voff)[_i]), (PG8_LAS unsigned*)(lds + (bufoff) + ldsw + _i * 8192), 16, 0, 0); } while (0)
; #define PG8_LDA(dst, b, h) do { _Pragma("unroll") for (int m = 0; m < 4; ++m) _Pragma("unroll") for (int k = 0; k < 2; ++k) dst[m][k] = *(const PG8_LAS bf16x8*)(lds + PG8_SA(b, h) + aoff + m * 2048 + k * 1024); } while (0)
; #define PG8_MMA(ai, bj, At, Bt) do { __builtin_amdgcn_s_setprio(1); _Pragma("unroll") for (int m = 0; m < 4; ++m) _Pragma("unroll") for (int n = 0; n < 2; ++n) _Pragma("unroll") for (int k = 0; k < 2; ++k) \
;         acc[ai][bj][m][n] = __builtin_amdgcn_mfma_f32_16x16x32_bf16(Bt[n][k], At[m][k], acc[ai][bj][m][n], 0, 0, 0); __builtin_amdgcn_s_setprio(0); } while (0)
; #define PG8_WAIT_V(n) asm volatile("s_waitcnt vmcnt(" #n ")" ::: "memory")
; #define PG8_WAIT_L(n) asm volatile("s_waitcnt lgkmcnt(" #n ")" ::: "memory")
; #define PG8_BAR __builtin_amdgcn_s_barrier()
; #define PG8_SCHED __builtin_amdgcn_sched_barrier(0)
; template <class Epi, class Sched, bool ALIGN_EPI = false, bool SP2 = false>
; __device__ __forceinline__ void gemm_phase(PG8_LAS unsigned char* lds, const Gemm g, const Sched& S, const Epi& E) {
;     ...
;             PG8_LDA(At, 1, 1); PG8_STAGE(PG8_SB(1, 0), b3, voffB); PG8_STAGE(PG8_SB(1, 1), b3 + hstep, voffB); PG8_STAGE(PG8_SA(1, 0), a3, voffA);
;             PG8_WAIT_V(8); PG8_WAIT_L(0); PG8_BAR; PG8_MMA(1, 0, At, B0); PG8_MMA(1, 1, At, B1); PG8_BAR; PG8_SCHED;
	s_add_i32 s62, s76, s21
	v_lshl_add_u64 v[144:145], v[144:145], 0, s[12:13]
	s_mov_b32 m0, s62
	ds_read_b128 v[182:185], v151 offset:49152
	ds_read_b128 v[186:189], v151 offset:50176
	ds_read_b128 v[190:193], v151 offset:51200
	ds_read_b128 v[194:197], v151 offset:52224
	ds_read_b128 v[202:205], v151 offset:53248
	ds_read_b128 v[206:209], v151 offset:54272
	ds_read_b128 v[210:213], v151 offset:55296
	ds_read_b128 v[214:217], v151 offset:56320
	global_load_lds_dwordx4 v[144:145], off
	s_add_i32 m0, s62, 0x2000
	s_add_u32 s60, s60, 0x40080
	v_lshl_add_u64 v[144:145], v[198:199], 0, s[12:13]
	s_addc_u32 s61, s61, 0
	s_add_i32 s62, s77, s21
	global_load_lds_dwordx4 v[144:145], off
	v_lshl_add_u64 v[144:145], s[60:61], 0, v[130:131]
	s_mov_b32 m0, s62
	s_nop 0
	global_load_lds_dwordx4 v[144:145], off
	v_lshl_add_u64 v[144:145], s[60:61], 0, v[134:135]
	s_add_i32 m0, s62, 0x2000
	s_nop 0
	global_load_lds_dwordx4 v[144:145], off
	v_lshl_add_u64 v[144:145], v[218:219], 0, s[12:13]
	s_mov_b32 m0, s57
	s_nop 0
	global_load_lds_dwordx4 v[144:145], off
	v_lshl_add_u64 v[144:145], v[220:221], 0, s[12:13]
	s_mov_b32 m0, s64
	s_nop 0
	global_load_lds_dwordx4 v[144:145], off
	s_waitcnt vmcnt(8)
	s_waitcnt lgkmcnt(0)
	s_barrier
	s_setprio 0
	s_waitcnt lgkmcnt(0)
	v_mfma_f32_16x16x32_bf16 v[60:63], v[140:143], v[182:185], v[60:63]
	v_mfma_f32_16x16x32_bf16 v[56:59], v[158:161], v[182:185], v[56:59]
	v_mfma_f32_16x16x32_bf16 v[48:51], v[140:143], v[190:193], v[48:51]
	v_mfma_f32_16x16x32_bf16 v[40:43], v[158:161], v[190:193], v[40:43]
	v_mfma_f32_16x16x32_bf16 v[32:35], v[140:143], v[202:205], v[32:35]
	v_mfma_f32_16x16x32_bf16 v[24:27], v[158:161], v[202:205], v[24:27]
	v_mfma_f32_16x16x32_bf16 v[16:19], v[140:143], v[210:213], v[16:19]
	v_mfma_f32_16x16x32_bf16 v[8:11], v[158:161], v[210:213], v[8:11]
	v_mfma_f32_16x16x32_bf16 v[60:63], v[154:157], v[186:189], v[60:63]
	v_mfma_f32_16x16x32_bf16 v[56:59], v[162:165], v[186:189], v[56:59]
	v_mfma_f32_16x16x32_bf16 v[48:51], v[154:157], v[194:197], v[48:51]
	v_mfma_f32_16x16x32_bf16 v[40:43], v[162:165], v[194:197], v[40:43]
	v_mfma_f32_16x16x32_bf16 v[32:35], v[154:157], v[206:209], v[32:35]
	v_mfma_f32_16x16x32_bf16 v[24:27], v[162:165], v[206:209], v[24:27]
	v_mfma_f32_16x16x32_bf16 v[16:19], v[154:157], v[214:217], v[16:19]
	v_mfma_f32_16x16x32_bf16 v[8:11], v[162:165], v[214:217], v[8:11]
	v_mfma_f32_16x16x32_bf16 v[52:55], v[166:169], v[182:185], v[52:55]
	v_mfma_f32_16x16x32_bf16 v[44:47], v[174:177], v[182:185], v[44:47]
	v_mfma_f32_16x16x32_bf16 v[36:39], v[166:169], v[190:193], v[36:39]
	v_mfma_f32_16x16x32_bf16 v[28:31], v[174:177], v[190:193], v[28:31]
	v_mfma_f32_16x16x32_bf16 v[20:23], v[166:169], v[202:205], v[20:23]
	v_mfma_f32_16x16x32_bf16 v[12:15], v[174:177], v[202:205], v[12:15]
	v_mfma_f32_16x16x32_bf16 v[4:7], v[166:169], v[210:213], v[4:7]
	v_mfma_f32_16x16x32_bf16 v[0:3], v[174:177], v[210:213], v[0:3]
	v_mfma_f32_16x16x32_bf16 v[52:55], v[170:173], v[186:189], v[52:55]
	v_mfma_f32_16x16x32_bf16 v[44:47], v[178:181], v[186:189], v[44:47]
	v_mfma_f32_16x16x32_bf16 v[36:39], v[170:173], v[194:197], v[36:39]
	v_mfma_f32_16x16x32_bf16 v[28:31], v[178:181], v[194:197], v[28:31]
	v_mfma_f32_16x16x32_bf16 v[20:23], v[170:173], v[206:209], v[20:23]
	v_mfma_f32_16x16x32_bf16 v[12:15], v[178:181], v[206:209], v[12:15]
	v_mfma_f32_16x16x32_bf16 v[4:7], v[170:173], v[214:217], v[4:7]
	v_mfma_f32_16x16x32_bf16 v[0:3], v[178:181], v[214:217], v[0:3]
	s_setprio 1
	s_barrier
	s_add_i32 s75, s75, 2
	s_add_u32 s58, s58, 0x100
	s_addc_u32 s59, s59, 0
	s_add_u32 s73, s73, 0x100
	s_addc_u32 s74, s74, 0
	s_cmp_gt_u32 s75, 13
	s_cbranch_scc0 .LBB0_1215
	s_and_b64 vcc, exec, s[14:15]
	s_cbranch_vccz .LBB0_1218
	s_barrier

; #define PG8_STAGE(bufoff, gbase, voff) do { _Pragma("unroll") for (int _i = 0; _i < 2; ++_i) \
;         __builtin_amdgcn_global_load_lds((const unsigned*)((const char*)(gbase) + (voff)[_i]), (PG8_LAS unsigned*)(lds + (bufoff) + ldsw + _i * 8192), 16, 0, 0); } while (0)
; #define PG8_LDA(dst, b, h) do { _Pragma("unroll") for (int m = 0; m < 4; ++m) _Pragma("unroll") for (int k = 0; k < 2; ++k) dst[m][k] = *(const PG8_LAS bf16x8*)(lds + PG8_SA(b, h) + aoff + m * 2048 + k * 1024); } while (0)
; #define PG8_LDB(dst, b, h) do { _Pragma("unroll") for (int n = 0; n < 2; ++n) _Pragma("unroll") for (int k = 0; k < 2; ++k) dst[n][k] = *(const PG8_LAS bf16x8*)(lds + PG8_SB(b, h) + boff + n * 2048 + k * 1024); } while (0)
; #define PG8_MMA(ai, bj, At, Bt) do { __builtin_amdgcn_s_setprio(1); _Pragma("unroll") for (int m = 0; m < 4; ++m) _Pragma("unroll") for (int n = 0; n < 2; ++n) _Pragma("unroll") for (int k = 0; k < 2; ++k) \
;         acc[ai][bj][m][n] = __builtin_amdgcn_mfma_f32_16x16x32_bf16(Bt[n][k], At[m][k], acc[ai][bj][m][n], 0, 0, 0); __builtin_amdgcn_s_setprio(0); } while (0)
; #define PG8_WAIT_V(n) asm volatile("s_waitcnt vmcnt(" #n ")" ::: "memory")
; #define PG8_WAIT_L(n) asm volatile("s_waitcnt lgkmcnt(" #n ")" ::: "memory")
; #define PG8_BAR __builtin_amdgcn_s_barrier()
; #define PG8_SCHED __builtin_amdgcn_sched_barrier(0)
; template <class Epi, class Sched, bool ALIGN_EPI = false, bool SP2 = false>
; __device__ __forceinline__ void gemm_phase(PG8_LAS unsigned char* lds, const Gemm g, const Sched& S, const Epi& E) {
;     ...
;             PG8_LDB(B0, 0, 0); PG8_LDB(B1, 0, 1); PG8_SCHED; PG8_LDA(At, 0, 0); PG8_STAGE(PG8_SA(1, 1), a1 + hstep, voffA);
;             PG8_WAIT_V(8); PG8_WAIT_L(0); PG8_BAR; PG8_MMA(0, 0, At, B0); PG8_MMA(0, 1, At, B1); PG8_BAR; PG8_SCHED;
;             PG8_LDA(At, 0, 1); PG8_STAGE(PG8_SB(0, 0), b2, voffB); PG8_STAGE(PG8_SB(0, 1), b2 + hstep, voffB); PG8_STAGE(PG8_SA(0, 0), a2, voffA);
;             PG8_WAIT_V(8); PG8_WAIT_L(0); PG8_BAR; PG8_MMA(1, 0, At, B0); PG8_MMA(1, 1, At, B1); PG8_BAR; PG8_SCHED;
.LBB0_1293:
	ds_read_b128 v[140:143], v189
	ds_read_b128 v[144:147], v189 offset:1024
	ds_read_b128 v[148:151], v189 offset:2048
	ds_read_b128 v[152:155], v189 offset:3072
	ds_read_b128 v[156:159], v190
	ds_read_b128 v[160:163], v190 offset:1024
	ds_read_b128 v[164:167], v190 offset:2048
	ds_read_b128 v[168:171], v190 offset:3072
	s_add_u32 s50, s48, 0xfffc0080
	s_addc_u32 s51, s49, -1
	s_cmp_eq_u32 s66, 12
	s_cselect_b32 s57, s3, s51
	s_cselect_b32 s56, s17, s50
	s_cselect_b32 s51, s19, s65
	s_cselect_b32 s50, s63, s64
	v_lshl_add_u64 v[184:185], s[48:49], 0, v[136:137]
	s_add_i32 m0, s28, 0xc000
	ds_read_b128 v[172:175], v191
	ds_read_b128 v[176:179], v191 offset:1024
	ds_read_b128 v[180:183], v191 offset:2048
	ds_read_b128 v[194:197], v191 offset:3072
	ds_read_b128 v[202:205], v191 offset:4096
	ds_read_b128 v[206:209], v191 offset:5120
	ds_read_b128 v[210:213], v191 offset:6144
	ds_read_b128 v[214:217], v191 offset:7168
	global_load_lds_dwordx4 v[184:185], off
	v_lshl_add_u64 v[184:185], s[48:49], 0, v[138:139]
	s_add_i32 m0, s28, 0xe000
	s_nop 0
	global_load_lds_dwordx4 v[184:185], off
	s_waitcnt vmcnt(8)
	s_waitcnt lgkmcnt(0)
	s_barrier
	s_setprio 0
	s_waitcnt lgkmcnt(0)
	v_mfma_f32_16x16x32_bf16 v[124:127], v[140:143], v[172:175], v[124:127]
	v_mfma_f32_16x16x32_bf16 v[120:123], v[148:151], v[172:175], v[120:123]
	v_mfma_f32_16x16x32_bf16 v[108:111], v[140:143], v[180:183], v[108:111]
	v_mfma_f32_16x16x32_bf16 v[104:107], v[148:151], v[180:183], v[104:107]
	v_mfma_f32_16x16x32_bf16 v[92:95], v[140:143], v[202:205], v[92:95]
	v_mfma_f32_16x16x32_bf16 v[88:91], v[148:151], v[202:205], v[88:91]
	v_mfma_f32_16x16x32_bf16 v[76:79], v[140:143], v[210:213], v[76:79]
	v_mfma_f32_16x16x32_bf16 v[72:75], v[148:151], v[210:213], v[72:75]
	v_mfma_f32_16x16x32_bf16 v[124:127], v[144:147], v[176:179], v[124:127]
	v_mfma_f32_16x16x32_bf16 v[120:123], v[152:155], v[176:179], v[120:123]
	v_mfma_f32_16x16x32_bf16 v[108:111], v[144:147], v[194:197], v[108:111]
	v_mfma_f32_16x16x32_bf16 v[104:107], v[152:155], v[194:197], v[104:107]
	v_mfma_f32_16x16x32_bf16 v[92:95], v[144:147], v[206:209], v[92:95]
	v_mfma_f32_16x16x32_bf16 v[88:91], v[152:155], v[206:209], v[88:91]
	v_mfma_f32_16x16x32_bf16 v[76:79], v[144:147], v[214:217], v[76:79]
	v_mfma_f32_16x16x32_bf16 v[72:75], v[152:155], v[214:217], v[72:75]
	v_mfma_f32_16x16x32_bf16 v[116:119], v[156:159], v[172:175], v[116:119]
	v_mfma_f32_16x16x32_bf16 v[112:115], v[164:167], v[172:175], v[112:115]
	v_mfma_f32_16x16x32_bf16 v[100:103], v[156:159], v[180:183], v[100:103]
	v_mfma_f32_16x16x32_bf16 v[96:99], v[164:167], v[180:183], v[96:99]
	v_mfma_f32_16x16x32_bf16 v[84:87], v[156:159], v[202:205], v[84:87]
	v_mfma_f32_16x16x32_bf16 v[80:83], v[164:167], v[202:205], v[80:83]
	v_mfma_f32_16x16x32_bf16 v[68:71], v[156:159], v[210:213], v[68:71]
	v_mfma_f32_16x16x32_bf16 v[64:67], v[164:167], v[210:213], v[64:67]
	v_mfma_f32_16x16x32_bf16 v[116:119], v[160:163], v[176:179], v[116:119]
	v_mfma_f32_16x16x32_bf16 v[112:115], v[168:171], v[176:179], v[112:115]
	v_mfma_f32_16x16x32_bf16 v[100:103], v[160:163], v[194:197], v[100:103]
	v_mfma_f32_16x16x32_bf16 v[96:99], v[168:171], v[194:197], v[96:99]
	v_mfma_f32_16x16x32_bf16 v[84:87], v[160:163], v[206:209], v[84:87]
	v_mfma_f32_16x16x32_bf16 v[80:83], v[168:171], v[206:209], v[80:83]
	v_mfma_f32_16x16x32_bf16 v[68:71], v[160:163], v[214:217], v[68:71]
	v_mfma_f32_16x16x32_bf16 v[64:67], v[168:171], v[214:217], v[64:67]
	s_setprio 1
	s_barrier
	s_add_i32 s67, s59, s21
	v_lshl_add_u64 v[184:185], s[50:51], 0, v[132:133]
	s_mov_b32 m0, s67
	ds_read_b128 v[172:175], v191 offset:16384
	ds_read_b128 v[176:179], v191 offset:17408
	ds_read_b128 v[180:183], v191 offset:18432
	ds_read_b128 v[194:197], v191 offset:19456
	ds_read_b128 v[202:205], v191 offset:20480
	ds_read_b128 v[206:209], v191 offset:21504
	ds_read_b128 v[210:213], v191 offset:22528
	ds_read_b128 v[214:217], v191 offset:23552
	global_load_lds_dwordx4 v[184:185], off
	s_add_i32 m0, s67, 0x2000
	s_add_u32 s68, s50, 0x40000
	v_lshl_add_u64 v[198:199], s[50:51], 0, v[128:129]
	s_addc_u32 s69, s51, 0
	s_add_i32 s67, s60, s21
	global_load_lds_dwordx4 v[198:199], off
	v_lshl_add_u64 v[218:219], s[68:69], 0, v[132:133]
	s_mov_b32 m0, s67
	v_lshl_add_u64 v[220:221], s[56:57], 0, v[130:131]
	global_load_lds_dwordx4 v[218:219], off
	v_lshl_add_u64 v[218:219], s[68:69], 0, v[128:129]
	s_add_i32 m0, s67, 0x2000
	s_nop 0
	global_load_lds_dwordx4 v[218:219], off
	v_lshl_add_u64 v[218:219], s[56:57], 0, v[134:135]
	s_mov_b32 m0, s28
	s_nop 0
	global_load_lds_dwordx4 v[218:219], off
	s_mov_b32 m0, s29
	s_nop 0
	global_load_lds_dwordx4 v[220:221], off
	s_waitcnt vmcnt(8)
	s_waitcnt lgkmcnt(0)
	s_barrier
; #define PG8_STAGE(bufoff, gbase, voff) do { _Pragma("unroll") for (int _i = 0; _i < 2; ++_i) \
;         __builtin_amdgcn_global_load_lds((const unsigned*)((const char*)(gbase) + (voff)[_i]), (PG8_LAS unsigned*)(lds + (bufoff) + ldsw + _i * 8192), 16, 0, 0); } while (0)
; #define PG8_LDA(dst, b, h) do { _Pragma("unroll") for (int m = 0; m < 4; ++m) _Pragma("unroll") for (int k = 0; k < 2; ++k) dst[m][k] = *(const PG8_LAS bf16x8*)(lds + PG8_SA(b, h) + aoff + m * 2048 + k * 1024); } while (0)
; #define PG8_LDB(dst, b, h) do { _Pragma("unroll") for (int n = 0; n < 2; ++n) _Pragma("unroll") for (int k = 0; k < 2; ++k) dst[n][k] = *(const PG8_LAS bf16x8*)(lds + PG8_SB(b, h) + boff + n * 2048 + k * 1024); } while (0)
; #define PG8_MMA(ai, bj, At, Bt) do { __builtin_amdgcn_s_setprio(1); _Pragma("unroll") for (int m = 0; m < 4; ++m) _Pragma("unroll") for (int n = 0; n < 2; ++n) _Pragma("unroll") for (int k = 0; k < 2; ++k) \
;         acc[ai][bj][m][n] = __builtin_amdgcn_mfma_f32_16x16x32_bf16(Bt[n][k], At[m][k], acc[ai][bj][m][n], 0, 0, 0); __builtin_amdgcn_s_setprio(0); } while (0)
; #define PG8_WAIT_V(n) asm volatile("s_waitcnt vmcnt(" #n ")" ::: "memory")
; #define PG8_WAIT_L(n) asm volatile("s_waitcnt lgkmcnt(" #n ")" ::: "memory")
; #define PG8_BAR __builtin_amdgcn_s_barrier()
; #define PG8_SCHED __builtin_amdgcn_sched_barrier(0)
; template <class Epi, class Sched, bool ALIGN_EPI = false, bool SP2 = false>
; __device__ __forceinline__ void gemm_phase(PG8_LAS unsigned char* lds, const Gemm g, const Sched& S, const Epi& E) {
;     ...
;             PG8_WAIT_V(8); PG8_WAIT_L(0); PG8_BAR; PG8_MMA(1, 0, At, B0); PG8_MMA(1, 1, At, B1); PG8_BAR; PG8_SCHED;
;             PG8_LDB(B0, 1, 0); PG8_LDB(B1, 1, 1); PG8_SCHED; PG8_LDA(At, 1, 0); PG8_STAGE(PG8_SA(0, 1), a2 + hstep, voffA);
;             PG8_WAIT_V(8); PG8_WAIT_L(0); PG8_BAR; PG8_MMA(0, 0, At, B0); PG8_MMA(0, 1, At, B1); PG8_BAR; PG8_SCHED;
	s_setprio 0
	s_waitcnt lgkmcnt(0)
	v_mfma_f32_16x16x32_bf16 v[60:63], v[140:143], v[172:175], v[60:63]
	v_mfma_f32_16x16x32_bf16 v[56:59], v[148:151], v[172:175], v[56:59]
	v_mfma_f32_16x16x32_bf16 v[44:47], v[140:143], v[180:183], v[44:47]
	v_mfma_f32_16x16x32_bf16 v[40:43], v[148:151], v[180:183], v[40:43]
	v_mfma_f32_16x16x32_bf16 v[28:31], v[140:143], v[202:205], v[28:31]
	v_mfma_f32_16x16x32_bf16 v[24:27], v[148:151], v[202:205], v[24:27]
	v_mfma_f32_16x16x32_bf16 v[12:15], v[140:143], v[210:213], v[12:15]
	v_mfma_f32_16x16x32_bf16 v[8:11], v[148:151], v[210:213], v[8:11]
	v_mfma_f32_16x16x32_bf16 v[60:63], v[144:147], v[176:179], v[60:63]
	v_mfma_f32_16x16x32_bf16 v[56:59], v[152:155], v[176:179], v[56:59]
	v_mfma_f32_16x16x32_bf16 v[44:47], v[144:147], v[194:197], v[44:47]
	v_mfma_f32_16x16x32_bf16 v[40:43], v[152:155], v[194:197], v[40:43]
	v_mfma_f32_16x16x32_bf16 v[28:31], v[144:147], v[206:209], v[28:31]
	v_mfma_f32_16x16x32_bf16 v[24:27], v[152:155], v[206:209], v[24:27]
	v_mfma_f32_16x16x32_bf16 v[12:15], v[144:147], v[214:217], v[12:15]
	v_mfma_f32_16x16x32_bf16 v[8:11], v[152:155], v[214:217], v[8:11]
	v_mfma_f32_16x16x32_bf16 v[52:55], v[156:159], v[172:175], v[52:55]
	v_mfma_f32_16x16x32_bf16 v[48:51], v[164:167], v[172:175], v[48:51]
	v_mfma_f32_16x16x32_bf16 v[36:39], v[156:159], v[180:183], v[36:39]
	v_mfma_f32_16x16x32_bf16 v[32:35], v[164:167], v[180:183], v[32:35]
	v_mfma_f32_16x16x32_bf16 v[20:23], v[156:159], v[202:205], v[20:23]
	v_mfma_f32_16x16x32_bf16 v[16:19], v[164:167], v[202:205], v[16:19]
	v_mfma_f32_16x16x32_bf16 v[4:7], v[156:159], v[210:213], v[4:7]
	v_mfma_f32_16x16x32_bf16 v[0:3], v[164:167], v[210:213], v[0:3]
	v_mfma_f32_16x16x32_bf16 v[52:55], v[160:163], v[176:179], v[52:55]
	v_mfma_f32_16x16x32_bf16 v[48:51], v[168:171], v[176:179], v[48:51]
	v_mfma_f32_16x16x32_bf16 v[36:39], v[160:163], v[194:197], v[36:39]
	v_mfma_f32_16x16x32_bf16 v[32:35], v[168:171], v[194:197], v[32:35]
	v_mfma_f32_16x16x32_bf16 v[20:23], v[160:163], v[206:209], v[20:23]
	v_mfma_f32_16x16x32_bf16 v[16:19], v[168:171], v[206:209], v[16:19]
	v_mfma_f32_16x16x32_bf16 v[4:7], v[160:163], v[214:217], v[4:7]
	v_mfma_f32_16x16x32_bf16 v[0:3], v[168:171], v[214:217], v[0:3]
	s_setprio 1
	s_barrier
	s_add_i32 s67, 0, 0x18000
	s_add_i32 s68, 0, 0x1c000
	v_add_u32_e32 v152, s67, v187
	v_add_u32_e32 v168, s68, v187
	ds_read_b128 v[140:143], v152
	ds_read_b128 v[144:147], v152 offset:1024
	ds_read_b128 v[148:151], v152 offset:2048
	ds_read_b128 v[152:155], v152 offset:3072
	ds_read_b128 v[156:159], v168
	ds_read_b128 v[160:163], v168 offset:1024
	ds_read_b128 v[164:167], v168 offset:2048
	ds_read_b128 v[168:171], v168 offset:3072
	s_add_u32 s56, s56, 0x40000
	s_addc_u32 s57, s57, 0
	s_mov_b32 m0, s30
	v_lshl_add_u64 v[222:223], s[56:57], 0, v[134:135]
	ds_read_b128 v[172:175], v191 offset:32768
	ds_read_b128 v[176:179], v191 offset:33792
	ds_read_b128 v[180:183], v191 offset:34816
	ds_read_b128 v[194:197], v191 offset:35840
	ds_read_b128 v[202:205], v191 offset:36864
	ds_read_b128 v[206:209], v191 offset:37888
	ds_read_b128 v[210:213], v191 offset:38912
	ds_read_b128 v[214:217], v191 offset:39936
	global_load_lds_dwordx4 v[222:223], off
	v_lshl_add_u64 v[222:223], s[56:57], 0, v[130:131]
	s_mov_b32 m0, s31
	s_nop 0
	global_load_lds_dwordx4 v[222:223], off
	s_waitcnt vmcnt(8)
	s_waitcnt lgkmcnt(0)
	s_barrier
	s_setprio 0
	s_waitcnt lgkmcnt(0)
	v_mfma_f32_16x16x32_bf16 v[124:127], v[140:143], v[172:175], v[124:127]
	v_mfma_f32_16x16x32_bf16 v[120:123], v[148:151], v[172:175], v[120:123]
	v_mfma_f32_16x16x32_bf16 v[108:111], v[140:143], v[180:183], v[108:111]
	v_mfma_f32_16x16x32_bf16 v[104:107], v[148:151], v[180:183], v[104:107]
	v_mfma_f32_16x16x32_bf16 v[92:95], v[140:143], v[202:205], v[92:95]
	v_mfma_f32_16x16x32_bf16 v[88:91], v[148:151], v[202:205], v[88:91]
	v_mfma_f32_16x16x32_bf16 v[76:79], v[140:143], v[210:213], v[76:79]
	v_mfma_f32_16x16x32_bf16 v[72:75], v[148:151], v[210:213], v[72:75]
	v_mfma_f32_16x16x32_bf16 v[124:127], v[144:147], v[176:179], v[124:127]
	v_mfma_f32_16x16x32_bf16 v[120:123], v[152:155], v[176:179], v[120:123]
	v_mfma_f32_16x16x32_bf16 v[108:111], v[144:147], v[194:197], v[108:111]
	v_mfma_f32_16x16x32_bf16 v[104:107], v[152:155], v[194:197], v[104:107]
	v_mfma_f32_16x16x32_bf16 v[92:95], v[144:147], v[206:209], v[92:95]
	v_mfma_f32_16x16x32_bf16 v[88:91], v[152:155], v[206:209], v[88:91]
	v_mfma_f32_16x16x32_bf16 v[76:79], v[144:147], v[214:217], v[76:79]
	v_mfma_f32_16x16x32_bf16 v[72:75], v[152:155], v[214:217], v[72:75]
	v_mfma_f32_16x16x32_bf16 v[116:119], v[156:159], v[172:175], v[116:119]
	v_mfma_f32_16x16x32_bf16 v[112:115], v[164:167], v[172:175], v[112:115]
	v_mfma_f32_16x16x32_bf16 v[100:103], v[156:159], v[180:183], v[100:103]
	v_mfma_f32_16x16x32_bf16 v[96:99], v[164:167], v[180:183], v[96:99]
	v_mfma_f32_16x16x32_bf16 v[84:87], v[156:159], v[202:205], v[84:87]
	v_mfma_f32_16x16x32_bf16 v[80:83], v[164:167], v[202:205], v[80:83]
	v_mfma_f32_16x16x32_bf16 v[68:71], v[156:159], v[210:213], v[68:71]
	v_mfma_f32_16x16x32_bf16 v[64:67], v[164:167], v[210:213], v[64:67]
	v_mfma_f32_16x16x32_bf16 v[116:119], v[160:163], v[176:179], v[116:119]
	v_mfma_f32_16x16x32_bf16 v[112:115], v[168:171], v[176:179], v[112:115]
	v_mfma_f32_16x16x32_bf16 v[100:103], v[160:163], v[194:197], v[100:103]
	v_mfma_f32_16x16x32_bf16 v[96:99], v[168:171], v[194:197], v[96:99]
	v_mfma_f32_16x16x32_bf16 v[84:87], v[160:163], v[206:209], v[84:87]
	v_mfma_f32_16x16x32_bf16 v[80:83], v[168:171], v[206:209], v[80:83]
	v_mfma_f32_16x16x32_bf16 v[68:71], v[160:163], v[214:217], v[68:71]
	v_mfma_f32_16x16x32_bf16 v[64:67], v[168:171], v[214:217], v[64:67]
	s_setprio 1
	s_barrier
; #define PG8_STAGE(bufoff, gbase, voff) do { _Pragma("unroll") for (int _i = 0; _i < 2; ++_i) \
;         __builtin_amdgcn_global_load_lds((const unsigned*)((const char*)(gbase) + (voff)[_i]), (PG8_LAS unsigned*)(lds + (bufoff) + ldsw + _i * 8192), 16, 0, 0); } while (0)
; #define PG8_LDA(dst, b, h) do { _Pragma("unroll") for (int m = 0; m < 4; ++m) _Pragma("unroll") for (int k = 0; k < 2; ++k) dst[m][k] = *(const PG8_LAS bf16x8*)(lds + PG8_SA(b, h) + aoff + m * 2048 + k * 1024); } while (0)
; #define PG8_MMA(ai, bj, At, Bt) do { __builtin_amdgcn_s_setprio(1); _Pragma("unroll") for (int m = 0; m < 4; ++m) _Pragma("unroll") for (int n = 0; n < 2; ++n) _Pragma("unroll") for (int k = 0; k < 2; ++k) \
;         acc[ai][bj][m][n] = __builtin_amdgcn_mfma_f32_16x16x32_bf16(Bt[n][k], At[m][k], acc[ai][bj][m][n], 0, 0, 0); __builtin_amdgcn_s_setprio(0); } while (0)
; #define PG8_WAIT_V(n) asm volatile("s_waitcnt vmcnt(" #n ")" ::: "memory")
; #define PG8_WAIT_L(n) asm volatile("s_waitcnt lgkmcnt(" #n ")" ::: "memory")
; #define PG8_BAR __builtin_amdgcn_s_barrier()
; #define PG8_SCHED __builtin_amdgcn_sched_barrier(0)
; template <class Epi, class Sched, bool ALIGN_EPI = false, bool SP2 = false>
; __device__ __forceinline__ void gemm_phase(PG8_LAS unsigned char* lds, const Gemm g, const Sched& S, const Epi& E) {
;     ...
;             PG8_LDA(At, 1, 1); PG8_STAGE(PG8_SB(1, 0), b3, voffB); PG8_STAGE(PG8_SB(1, 1), b3 + hstep, voffB); PG8_STAGE(PG8_SA(1, 0), a3, voffA);
;             PG8_WAIT_V(8); PG8_WAIT_L(0); PG8_BAR; PG8_MMA(1, 0, At, B0); PG8_MMA(1, 1, At, B1); PG8_BAR; PG8_SCHED;
	s_add_i32 s56, s67, s21
	v_lshl_add_u64 v[184:185], v[184:185], 0, s[12:13]
	s_mov_b32 m0, s56
	ds_read_b128 v[172:175], v191 offset:49152
	ds_read_b128 v[176:179], v191 offset:50176
	ds_read_b128 v[180:183], v191 offset:51200
	ds_read_b128 v[194:197], v191 offset:52224
	ds_read_b128 v[202:205], v191 offset:53248
	ds_read_b128 v[206:209], v191 offset:54272
	ds_read_b128 v[210:213], v191 offset:55296
	ds_read_b128 v[214:217], v191 offset:56320
	global_load_lds_dwordx4 v[184:185], off
	s_add_i32 m0, s56, 0x2000
	s_add_u32 s50, s50, 0x40080
	v_lshl_add_u64 v[184:185], v[198:199], 0, s[12:13]
	s_addc_u32 s51, s51, 0
	s_add_i32 s56, s68, s21
	global_load_lds_dwordx4 v[184:185], off
	v_lshl_add_u64 v[184:185], s[50:51], 0, v[132:133]
	s_mov_b32 m0, s56
	s_nop 0
	global_load_lds_dwordx4 v[184:185], off
	v_lshl_add_u64 v[184:185], s[50:51], 0, v[128:129]
	s_add_i32 m0, s56, 0x2000
	s_nop 0
	global_load_lds_dwordx4 v[184:185], off
	v_lshl_add_u64 v[184:185], v[218:219], 0, s[12:13]
	s_mov_b32 m0, s39
	s_nop 0
	global_load_lds_dwordx4 v[184:185], off
	v_lshl_add_u64 v[184:185], v[220:221], 0, s[12:13]
	s_mov_b32 m0, s58
	s_nop 0
	global_load_lds_dwordx4 v[184:185], off
	s_waitcnt vmcnt(8)
	s_waitcnt lgkmcnt(0)
	s_barrier
	s_setprio 0
	s_waitcnt lgkmcnt(0)
	v_mfma_f32_16x16x32_bf16 v[60:63], v[140:143], v[172:175], v[60:63]
	v_mfma_f32_16x16x32_bf16 v[56:59], v[148:151], v[172:175], v[56:59]
	v_mfma_f32_16x16x32_bf16 v[44:47], v[140:143], v[180:183], v[44:47]
	v_mfma_f32_16x16x32_bf16 v[40:43], v[148:151], v[180:183], v[40:43]
	v_mfma_f32_16x16x32_bf16 v[28:31], v[140:143], v[202:205], v[28:31]
	v_mfma_f32_16x16x32_bf16 v[24:27], v[148:151], v[202:205], v[24:27]
	v_mfma_f32_16x16x32_bf16 v[12:15], v[140:143], v[210:213], v[12:15]
	v_mfma_f32_16x16x32_bf16 v[8:11], v[148:151], v[210:213], v[8:11]
	v_mfma_f32_16x16x32_bf16 v[60:63], v[144:147], v[176:179], v[60:63]
	v_mfma_f32_16x16x32_bf16 v[56:59], v[152:155], v[176:179], v[56:59]
	v_mfma_f32_16x16x32_bf16 v[44:47], v[144:147], v[194:197], v[44:47]
	v_mfma_f32_16x16x32_bf16 v[40:43], v[152:155], v[194:197], v[40:43]
	v_mfma_f32_16x16x32_bf16 v[28:31], v[144:147], v[206:209], v[28:31]
	v_mfma_f32_16x16x32_bf16 v[24:27], v[152:155], v[206:209], v[24:27]
	v_mfma_f32_16x16x32_bf16 v[12:15], v[144:147], v[214:217], v[12:15]
	v_mfma_f32_16x16x32_bf16 v[8:11], v[152:155], v[214:217], v[8:11]
	v_mfma_f32_16x16x32_bf16 v[52:55], v[156:159], v[172:175], v[52:55]
	v_mfma_f32_16x16x32_bf16 v[48:51], v[164:167], v[172:175], v[48:51]
	v_mfma_f32_16x16x32_bf16 v[36:39], v[156:159], v[180:183], v[36:39]
	v_mfma_f32_16x16x32_bf16 v[32:35], v[164:167], v[180:183], v[32:35]
	v_mfma_f32_16x16x32_bf16 v[20:23], v[156:159], v[202:205], v[20:23]
	v_mfma_f32_16x16x32_bf16 v[16:19], v[164:167], v[202:205], v[16:19]
	v_mfma_f32_16x16x32_bf16 v[4:7], v[156:159], v[210:213], v[4:7]
	v_mfma_f32_16x16x32_bf16 v[0:3], v[164:167], v[210:213], v[0:3]
	v_mfma_f32_16x16x32_bf16 v[52:55], v[160:163], v[176:179], v[52:55]
	v_mfma_f32_16x16x32_bf16 v[48:51], v[168:171], v[176:179], v[48:51]
	v_mfma_f32_16x16x32_bf16 v[36:39], v[160:163], v[194:197], v[36:39]
	v_mfma_f32_16x16x32_bf16 v[32:35], v[168:171], v[194:197], v[32:35]
	v_mfma_f32_16x16x32_bf16 v[20:23], v[160:163], v[206:209], v[20:23]
	v_mfma_f32_16x16x32_bf16 v[16:19], v[168:171], v[206:209], v[16:19]
	v_mfma_f32_16x16x32_bf16 v[4:7], v[160:163], v[214:217], v[4:7]
	v_mfma_f32_16x16x32_bf16 v[0:3], v[168:171], v[214:217], v[0:3]
	s_setprio 1
	s_barrier
	s_add_i32 s66, s66, 2
	s_add_u32 s48, s48, 0x100
	s_addc_u32 s49, s49, 0
	s_add_u32 s64, s64, 0x100
	s_addc_u32 s65, s65, 0
	s_cmp_gt_u32 s66, 13
	s_cbranch_scc0 .LBB0_1293
	s_and_b64 vcc, exec, s[14:15]
	s_cbranch_vccz .LBB0_1296
	s_barrier

; #define PG8_STAGE(bufoff, gbase, voff) do { _Pragma("unroll") for (int _i = 0; _i < 2; ++_i) \
;         __builtin_amdgcn_global_load_lds((const unsigned*)((const char*)(gbase) + (voff)[_i]), (PG8_LAS unsigned*)(lds + (bufoff) + ldsw + _i * 8192), 16, 0, 0); } while (0)
; #define PG8_LDA(dst, b, h) do { _Pragma("unroll") for (int m = 0; m < 4; ++m) _Pragma("unroll") for (int k = 0; k < 2; ++k) dst[m][k] = *(const PG8_LAS bf16x8*)(lds + PG8_SA(b, h) + aoff + m * 2048 + k * 1024); } while (0)
; #define PG8_LDB(dst, b, h) do { _Pragma("unroll") for (int n = 0; n < 2; ++n) _Pragma("unroll") for (int k = 0; k < 2; ++k) dst[n][k] = *(const PG8_LAS bf16x8*)(lds + PG8_SB(b, h) + boff + n * 2048 + k * 1024); } while (0)
; #define PG8_MMA(ai, bj, At, Bt) do { __builtin_amdgcn_s_setprio(1); _Pragma("unroll") for (int m = 0; m < 4; ++m) _Pragma("unroll") for (int n = 0; n < 2; ++n) _Pragma("unroll") for (int k = 0; k < 2; ++k) \
;         acc[ai][bj][m][n] = __builtin_amdgcn_mfma_f32_16x16x32_bf16(Bt[n][k], At[m][k], acc[ai][bj][m][n], 0, 0, 0); __builtin_amdgcn_s_setprio(0); } while (0)
; #define PG8_WAIT_V(n) asm volatile("s_waitcnt vmcnt(" #n ")" ::: "memory")
; #define PG8_WAIT_L(n) asm volatile("s_waitcnt lgkmcnt(" #n ")" ::: "memory")
; #define PG8_BAR __builtin_amdgcn_s_barrier()
; #define PG8_SCHED __builtin_amdgcn_sched_barrier(0)
; template <class Epi, class Sched, bool ALIGN_EPI = false, bool SP2 = false>
; __device__ __forceinline__ void gemm_phase(PG8_LAS unsigned char* lds, const Gemm g, const Sched& S, const Epi& E) {
;     ...
;             PG8_LDB(B0, 0, 0); PG8_LDB(B1, 0, 1); PG8_SCHED; PG8_LDA(At, 0, 0); PG8_STAGE(PG8_SA(1, 1), a1 + hstep, voffA);
;             PG8_WAIT_V(8); PG8_WAIT_L(0); PG8_BAR; PG8_MMA(0, 0, At, B0); PG8_MMA(0, 1, At, B1); PG8_BAR; PG8_SCHED;
;             PG8_LDA(At, 0, 1); PG8_STAGE(PG8_SB(0, 0), b2, voffB); PG8_STAGE(PG8_SB(0, 1), b2 + hstep, voffB); PG8_STAGE(PG8_SA(0, 0), a2, voffA);
;             PG8_WAIT_V(8); PG8_WAIT_L(0); PG8_BAR; PG8_MMA(1, 0, At, B0); PG8_MMA(1, 1, At, B1); PG8_BAR; PG8_SCHED;
.LBB0_1363:
	ds_read_b128 v[128:131], v156
	ds_read_b128 v[132:135], v156 offset:1024
	ds_read_b128 v[148:151], v156 offset:2048
	ds_read_b128 v[162:165], v156 offset:3072
	ds_read_b128 v[166:169], v157
	ds_read_b128 v[170:173], v157 offset:1024
	ds_read_b128 v[174:177], v157 offset:2048
	ds_read_b128 v[178:181], v157 offset:3072
	s_add_u32 s42, s26, 0xfff50080
	s_addc_u32 s43, s27, -1
	s_cmp_eq_u32 s72, 40
	s_cselect_b32 s45, s17, s43
	s_cselect_b32 s44, s16, s42
	s_cselect_b32 s43, s19, s71
	s_cselect_b32 s42, s18, s70
	s_mov_b32 m0, s58
	v_lshl_add_u64 v[152:153], s[26:27], 0, v[144:145]
	ds_read_b128 v[182:185], v158
	ds_read_b128 v[186:189], v158 offset:1024
	ds_read_b128 v[190:193], v158 offset:2048
	ds_read_b128 v[194:197], v158 offset:3072
	ds_read_b128 v[202:205], v158 offset:4096
	ds_read_b128 v[206:209], v158 offset:5120
	ds_read_b128 v[210:213], v158 offset:6144
	ds_read_b128 v[214:217], v158 offset:7168
	global_load_lds_dwordx4 v[152:153], off
	v_lshl_add_u64 v[152:153], s[26:27], 0, v[146:147]
	s_mov_b32 m0, s59
	s_nop 0
	global_load_lds_dwordx4 v[152:153], off
	s_waitcnt vmcnt(8)
	s_waitcnt lgkmcnt(0)
	s_barrier
	s_setprio 0
	s_waitcnt lgkmcnt(0)
	v_mfma_f32_16x16x32_bf16 v[124:127], v[128:131], v[182:185], v[124:127]
	v_mfma_f32_16x16x32_bf16 v[120:123], v[148:151], v[182:185], v[120:123]
	v_mfma_f32_16x16x32_bf16 v[108:111], v[128:131], v[190:193], v[108:111]
	v_mfma_f32_16x16x32_bf16 v[104:107], v[148:151], v[190:193], v[104:107]
	v_mfma_f32_16x16x32_bf16 v[92:95], v[128:131], v[202:205], v[92:95]
	v_mfma_f32_16x16x32_bf16 v[88:91], v[148:151], v[202:205], v[88:91]
	v_mfma_f32_16x16x32_bf16 v[76:79], v[128:131], v[210:213], v[76:79]
	v_mfma_f32_16x16x32_bf16 v[72:75], v[148:151], v[210:213], v[72:75]
	v_mfma_f32_16x16x32_bf16 v[124:127], v[132:135], v[186:189], v[124:127]
	v_mfma_f32_16x16x32_bf16 v[120:123], v[162:165], v[186:189], v[120:123]
	v_mfma_f32_16x16x32_bf16 v[108:111], v[132:135], v[194:197], v[108:111]
	v_mfma_f32_16x16x32_bf16 v[104:107], v[162:165], v[194:197], v[104:107]
	v_mfma_f32_16x16x32_bf16 v[92:95], v[132:135], v[206:209], v[92:95]
	v_mfma_f32_16x16x32_bf16 v[88:91], v[162:165], v[206:209], v[88:91]
	v_mfma_f32_16x16x32_bf16 v[76:79], v[132:135], v[214:217], v[76:79]
	v_mfma_f32_16x16x32_bf16 v[72:75], v[162:165], v[214:217], v[72:75]
	v_mfma_f32_16x16x32_bf16 v[116:119], v[166:169], v[182:185], v[116:119]
	v_mfma_f32_16x16x32_bf16 v[112:115], v[174:177], v[182:185], v[112:115]
	v_mfma_f32_16x16x32_bf16 v[100:103], v[166:169], v[190:193], v[100:103]
	v_mfma_f32_16x16x32_bf16 v[96:99], v[174:177], v[190:193], v[96:99]
	v_mfma_f32_16x16x32_bf16 v[84:87], v[166:169], v[202:205], v[84:87]
	v_mfma_f32_16x16x32_bf16 v[80:83], v[174:177], v[202:205], v[80:83]
	v_mfma_f32_16x16x32_bf16 v[68:71], v[166:169], v[210:213], v[68:71]
	v_mfma_f32_16x16x32_bf16 v[64:67], v[174:177], v[210:213], v[64:67]
	v_mfma_f32_16x16x32_bf16 v[116:119], v[170:173], v[186:189], v[116:119]
	v_mfma_f32_16x16x32_bf16 v[112:115], v[178:181], v[186:189], v[112:115]
	v_mfma_f32_16x16x32_bf16 v[100:103], v[170:173], v[194:197], v[100:103]
	v_mfma_f32_16x16x32_bf16 v[96:99], v[178:181], v[194:197], v[96:99]
	v_mfma_f32_16x16x32_bf16 v[84:87], v[170:173], v[206:209], v[84:87]
	v_mfma_f32_16x16x32_bf16 v[80:83], v[178:181], v[206:209], v[80:83]
	v_mfma_f32_16x16x32_bf16 v[68:71], v[170:173], v[214:217], v[68:71]
	v_mfma_f32_16x16x32_bf16 v[64:67], v[178:181], v[214:217], v[64:67]
	s_setprio 1
	s_barrier
	s_mov_b32 m0, s60
	v_lshl_add_u64 v[152:153], s[42:43], 0, v[138:139]
	s_add_u32 s74, s42, 0xb0000
	ds_read_b128 v[182:185], v158 offset:16384
	ds_read_b128 v[186:189], v158 offset:17408
	ds_read_b128 v[190:193], v158 offset:18432
	ds_read_b128 v[194:197], v158 offset:19456
	ds_read_b128 v[202:205], v158 offset:20480
	ds_read_b128 v[206:209], v158 offset:21504
	ds_read_b128 v[210:213], v158 offset:22528
	ds_read_b128 v[214:217], v158 offset:23552
	global_load_lds_dwordx4 v[152:153], off
	v_lshl_add_u64 v[198:199], s[42:43], 0, v[142:143]
	s_mov_b32 m0, s61
	s_addc_u32 s75, s43, 0
	global_load_lds_dwordx4 v[198:199], off
	v_lshl_add_u64 v[218:219], s[74:75], 0, v[138:139]
	s_mov_b32 m0, s62
	v_lshl_add_u64 v[220:221], s[44:45], 0, v[140:141]
	global_load_lds_dwordx4 v[218:219], off
	v_lshl_add_u64 v[218:219], s[74:75], 0, v[142:143]
	s_mov_b32 m0, s63
	s_nop 0
	global_load_lds_dwordx4 v[218:219], off
	v_lshl_add_u64 v[218:219], s[44:45], 0, v[136:137]
	s_mov_b32 m0, s29
	s_nop 0
	global_load_lds_dwordx4 v[218:219], off
	s_mov_b32 m0, s30
	s_nop 0
	global_load_lds_dwordx4 v[220:221], off
	s_waitcnt vmcnt(8)
	s_waitcnt lgkmcnt(0)
	s_barrier
; #define PG8_STAGE(bufoff, gbase, voff) do { _Pragma("unroll") for (int _i = 0; _i < 2; ++_i) \
;         __builtin_amdgcn_global_load_lds((const unsigned*)((const char*)(gbase) + (voff)[_i]), (PG8_LAS unsigned*)(lds + (bufoff) + ldsw + _i * 8192), 16, 0, 0); } while (0)
; #define PG8_LDA(dst, b, h) do { _Pragma("unroll") for (int m = 0; m < 4; ++m) _Pragma("unroll") for (int k = 0; k < 2; ++k) dst[m][k] = *(const PG8_LAS bf16x8*)(lds + PG8_SA(b, h) + aoff + m * 2048 + k * 1024); } while (0)
; #define PG8_LDB(dst, b, h) do { _Pragma("unroll") for (int n = 0; n < 2; ++n) _Pragma("unroll") for (int k = 0; k < 2; ++k) dst[n][k] = *(const PG8_LAS bf16x8*)(lds + PG8_SB(b, h) + boff + n * 2048 + k * 1024); } while (0)
; #define PG8_MMA(ai, bj, At, Bt) do { __builtin_amdgcn_s_setprio(1); _Pragma("unroll") for (int m = 0; m < 4; ++m) _Pragma("unroll") for (int n = 0; n < 2; ++n) _Pragma("unroll") for (int k = 0; k < 2; ++k) \
;         acc[ai][bj][m][n] = __builtin_amdgcn_mfma_f32_16x16x32_bf16(Bt[n][k], At[m][k], acc[ai][bj][m][n], 0, 0, 0); __builtin_amdgcn_s_setprio(0); } while (0)
; #define PG8_WAIT_V(n) asm volatile("s_waitcnt vmcnt(" #n ")" ::: "memory")
; #define PG8_WAIT_L(n) asm volatile("s_waitcnt lgkmcnt(" #n ")" ::: "memory")
; #define PG8_BAR __builtin_amdgcn_s_barrier()
; #define PG8_SCHED __builtin_amdgcn_sched_barrier(0)
; template <class Epi, class Sched, bool ALIGN_EPI = false, bool SP2 = false>
; __device__ __forceinline__ void gemm_phase(PG8_LAS unsigned char* lds, const Gemm g, const Sched& S, const Epi& E) {
;     ...
;             PG8_WAIT_V(8); PG8_WAIT_L(0); PG8_BAR; PG8_MMA(1, 0, At, B0); PG8_MMA(1, 1, At, B1); PG8_BAR; PG8_SCHED;
;             PG8_LDB(B0, 1, 0); PG8_LDB(B1, 1, 1); PG8_SCHED; PG8_LDA(At, 1, 0); PG8_STAGE(PG8_SA(0, 1), a2 + hstep, voffA);
;             PG8_WAIT_V(8); PG8_WAIT_L(0); PG8_BAR; PG8_MMA(0, 0, At, B0); PG8_MMA(0, 1, At, B1); PG8_BAR; PG8_SCHED;
	s_setprio 0
	s_waitcnt lgkmcnt(0)
	v_mfma_f32_16x16x32_bf16 v[60:63], v[128:131], v[182:185], v[60:63]
	v_mfma_f32_16x16x32_bf16 v[56:59], v[148:151], v[182:185], v[56:59]
	v_mfma_f32_16x16x32_bf16 v[44:47], v[128:131], v[190:193], v[44:47]
	v_mfma_f32_16x16x32_bf16 v[40:43], v[148:151], v[190:193], v[40:43]
	v_mfma_f32_16x16x32_bf16 v[32:35], v[128:131], v[202:205], v[32:35]
	v_mfma_f32_16x16x32_bf16 v[24:27], v[148:151], v[202:205], v[24:27]
	v_mfma_f32_16x16x32_bf16 v[16:19], v[128:131], v[210:213], v[16:19]
	v_mfma_f32_16x16x32_bf16 v[8:11], v[148:151], v[210:213], v[8:11]
	v_mfma_f32_16x16x32_bf16 v[60:63], v[132:135], v[186:189], v[60:63]
	v_mfma_f32_16x16x32_bf16 v[56:59], v[162:165], v[186:189], v[56:59]
	v_mfma_f32_16x16x32_bf16 v[44:47], v[132:135], v[194:197], v[44:47]
	v_mfma_f32_16x16x32_bf16 v[40:43], v[162:165], v[194:197], v[40:43]
	v_mfma_f32_16x16x32_bf16 v[32:35], v[132:135], v[206:209], v[32:35]
	v_mfma_f32_16x16x32_bf16 v[24:27], v[162:165], v[206:209], v[24:27]
	v_mfma_f32_16x16x32_bf16 v[16:19], v[132:135], v[214:217], v[16:19]
	v_mfma_f32_16x16x32_bf16 v[8:11], v[162:165], v[214:217], v[8:11]
	v_mfma_f32_16x16x32_bf16 v[52:55], v[166:169], v[182:185], v[52:55]
	v_mfma_f32_16x16x32_bf16 v[48:51], v[174:177], v[182:185], v[48:51]
	v_mfma_f32_16x16x32_bf16 v[36:39], v[166:169], v[190:193], v[36:39]
	v_mfma_f32_16x16x32_bf16 v[28:31], v[174:177], v[190:193], v[28:31]
	v_mfma_f32_16x16x32_bf16 v[20:23], v[166:169], v[202:205], v[20:23]
	v_mfma_f32_16x16x32_bf16 v[12:15], v[174:177], v[202:205], v[12:15]
	v_mfma_f32_16x16x32_bf16 v[4:7], v[166:169], v[210:213], v[4:7]
	v_mfma_f32_16x16x32_bf16 v[0:3], v[174:177], v[210:213], v[0:3]
	v_mfma_f32_16x16x32_bf16 v[52:55], v[170:173], v[186:189], v[52:55]
	v_mfma_f32_16x16x32_bf16 v[48:51], v[178:181], v[186:189], v[48:51]
	v_mfma_f32_16x16x32_bf16 v[36:39], v[170:173], v[194:197], v[36:39]
	v_mfma_f32_16x16x32_bf16 v[28:31], v[178:181], v[194:197], v[28:31]
	v_mfma_f32_16x16x32_bf16 v[20:23], v[170:173], v[206:209], v[20:23]
	v_mfma_f32_16x16x32_bf16 v[12:15], v[178:181], v[206:209], v[12:15]
	v_mfma_f32_16x16x32_bf16 v[4:7], v[170:173], v[214:217], v[4:7]
	v_mfma_f32_16x16x32_bf16 v[0:3], v[178:181], v[214:217], v[0:3]
	s_setprio 1
	s_barrier
	ds_read_b128 v[128:131], v160
	ds_read_b128 v[132:135], v160 offset:1024
	ds_read_b128 v[148:151], v160 offset:2048
	ds_read_b128 v[162:165], v160 offset:3072
	ds_read_b128 v[166:169], v161
	ds_read_b128 v[170:173], v161 offset:1024
	ds_read_b128 v[174:177], v161 offset:2048
	ds_read_b128 v[178:181], v161 offset:3072
	s_add_u32 s44, s44, 0xb0000
	s_addc_u32 s45, s45, 0
	s_mov_b32 m0, s31
	v_lshl_add_u64 v[222:223], s[44:45], 0, v[136:137]
	ds_read_b128 v[182:185], v158 offset:32768
	ds_read_b128 v[186:189], v158 offset:33792
	ds_read_b128 v[190:193], v158 offset:34816
	ds_read_b128 v[194:197], v158 offset:35840
	ds_read_b128 v[202:205], v158 offset:36864
	ds_read_b128 v[206:209], v158 offset:37888
	ds_read_b128 v[210:213], v158 offset:38912
	ds_read_b128 v[214:217], v158 offset:39936
	global_load_lds_dwordx4 v[222:223], off
	v_lshl_add_u64 v[222:223], s[44:45], 0, v[140:141]
	s_mov_b32 m0, s37
	s_nop 0
	global_load_lds_dwordx4 v[222:223], off
	s_waitcnt vmcnt(8)
	s_waitcnt lgkmcnt(0)
	s_barrier
	s_setprio 0
	s_waitcnt lgkmcnt(0)
	v_mfma_f32_16x16x32_bf16 v[124:127], v[128:131], v[182:185], v[124:127]
	v_mfma_f32_16x16x32_bf16 v[120:123], v[148:151], v[182:185], v[120:123]
	v_mfma_f32_16x16x32_bf16 v[108:111], v[128:131], v[190:193], v[108:111]
	v_mfma_f32_16x16x32_bf16 v[104:107], v[148:151], v[190:193], v[104:107]
	v_mfma_f32_16x16x32_bf16 v[92:95], v[128:131], v[202:205], v[92:95]
	v_mfma_f32_16x16x32_bf16 v[88:91], v[148:151], v[202:205], v[88:91]
	v_mfma_f32_16x16x32_bf16 v[76:79], v[128:131], v[210:213], v[76:79]
	v_mfma_f32_16x16x32_bf16 v[72:75], v[148:151], v[210:213], v[72:75]
	v_mfma_f32_16x16x32_bf16 v[124:127], v[132:135], v[186:189], v[124:127]
	v_mfma_f32_16x16x32_bf16 v[120:123], v[162:165], v[186:189], v[120:123]
	v_mfma_f32_16x16x32_bf16 v[108:111], v[132:135], v[194:197], v[108:111]
	v_mfma_f32_16x16x32_bf16 v[104:107], v[162:165], v[194:197], v[104:107]
	v_mfma_f32_16x16x32_bf16 v[92:95], v[132:135], v[206:209], v[92:95]
	v_mfma_f32_16x16x32_bf16 v[88:91], v[162:165], v[206:209], v[88:91]
	v_mfma_f32_16x16x32_bf16 v[76:79], v[132:135], v[214:217], v[76:79]
	v_mfma_f32_16x16x32_bf16 v[72:75], v[162:165], v[214:217], v[72:75]
	v_mfma_f32_16x16x32_bf16 v[116:119], v[166:169], v[182:185], v[116:119]
	v_mfma_f32_16x16x32_bf16 v[112:115], v[174:177], v[182:185], v[112:115]
	v_mfma_f32_16x16x32_bf16 v[100:103], v[166:169], v[190:193], v[100:103]
	v_mfma_f32_16x16x32_bf16 v[96:99], v[174:177], v[190:193], v[96:99]
	v_mfma_f32_16x16x32_bf16 v[84:87], v[166:169], v[202:205], v[84:87]
	v_mfma_f32_16x16x32_bf16 v[80:83], v[174:177], v[202:205], v[80:83]
	v_mfma_f32_16x16x32_bf16 v[68:71], v[166:169], v[210:213], v[68:71]
	v_mfma_f32_16x16x32_bf16 v[64:67], v[174:177], v[210:213], v[64:67]
	v_mfma_f32_16x16x32_bf16 v[116:119], v[170:173], v[186:189], v[116:119]
	v_mfma_f32_16x16x32_bf16 v[112:115], v[178:181], v[186:189], v[112:115]
	v_mfma_f32_16x16x32_bf16 v[100:103], v[170:173], v[194:197], v[100:103]
	v_mfma_f32_16x16x32_bf16 v[96:99], v[178:181], v[194:197], v[96:99]
	v_mfma_f32_16x16x32_bf16 v[84:87], v[170:173], v[206:209], v[84:87]
	v_mfma_f32_16x16x32_bf16 v[80:83], v[178:181], v[206:209], v[80:83]
	v_mfma_f32_16x16x32_bf16 v[68:71], v[170:173], v[214:217], v[68:71]
	v_mfma_f32_16x16x32_bf16 v[64:67], v[178:181], v[214:217], v[64:67]
	s_setprio 1
	s_barrier
; #define PG8_STAGE(bufoff, gbase, voff) do { _Pragma("unroll") for (int _i = 0; _i < 2; ++_i) \
;         __builtin_amdgcn_global_load_lds((const unsigned*)((const char*)(gbase) + (voff)[_i]), (PG8_LAS unsigned*)(lds + (bufoff) + ldsw + _i * 8192), 16, 0, 0); } while (0)
; #define PG8_LDA(dst, b, h) do { _Pragma("unroll") for (int m = 0; m < 4; ++m) _Pragma("unroll") for (int k = 0; k < 2; ++k) dst[m][k] = *(const PG8_LAS bf16x8*)(lds + PG8_SA(b, h) + aoff + m * 2048 + k * 1024); } while (0)
; #define PG8_MMA(ai, bj, At, Bt) do { __builtin_amdgcn_s_setprio(1); _Pragma("unroll") for (int m = 0; m < 4; ++m) _Pragma("unroll") for (int n = 0; n < 2; ++n) _Pragma("unroll") for (int k = 0; k < 2; ++k) \
;         acc[ai][bj][m][n] = __builtin_amdgcn_mfma_f32_16x16x32_bf16(Bt[n][k], At[m][k], acc[ai][bj][m][n], 0, 0, 0); __builtin_amdgcn_s_setprio(0); } while (0)
; #define PG8_WAIT_V(n) asm volatile("s_waitcnt vmcnt(" #n ")" ::: "memory")
; #define PG8_WAIT_L(n) asm volatile("s_waitcnt lgkmcnt(" #n ")" ::: "memory")
; #define PG8_BAR __builtin_amdgcn_s_barrier()
; #define PG8_SCHED __builtin_amdgcn_sched_barrier(0)
; template <class Epi, class Sched, bool ALIGN_EPI = false, bool SP2 = false>
; __device__ __forceinline__ void gemm_phase(PG8_LAS unsigned char* lds, const Gemm g, const Sched& S, const Epi& E) {
;     ...
;             PG8_LDA(At, 1, 1); PG8_STAGE(PG8_SB(1, 0), b3, voffB); PG8_STAGE(PG8_SB(1, 1), b3 + hstep, voffB); PG8_STAGE(PG8_SA(1, 0), a3, voffA);
;             PG8_WAIT_V(8); PG8_WAIT_L(0); PG8_BAR; PG8_MMA(1, 0, At, B0); PG8_MMA(1, 1, At, B1); PG8_BAR; PG8_SCHED;
	s_add_i32 s44, s64, s28
	v_lshl_add_u64 v[152:153], v[152:153], 0, s[12:13]
	s_mov_b32 m0, s44
	ds_read_b128 v[182:185], v158 offset:49152
	ds_read_b128 v[186:189], v158 offset:50176
	ds_read_b128 v[190:193], v158 offset:51200
	ds_read_b128 v[194:197], v158 offset:52224
	ds_read_b128 v[202:205], v158 offset:53248
	ds_read_b128 v[206:209], v158 offset:54272
	ds_read_b128 v[210:213], v158 offset:55296
	ds_read_b128 v[214:217], v158 offset:56320
	global_load_lds_dwordx4 v[152:153], off
	s_add_i32 m0, s44, 0x2000
	s_add_u32 s42, s42, 0xb0080
	v_lshl_add_u64 v[152:153], v[198:199], 0, s[12:13]
	s_addc_u32 s43, s43, 0
	s_add_i32 s44, s65, s28
	global_load_lds_dwordx4 v[152:153], off
	v_lshl_add_u64 v[152:153], s[42:43], 0, v[138:139]
	s_mov_b32 m0, s44
	s_nop 0
	global_load_lds_dwordx4 v[152:153], off
	v_lshl_add_u64 v[152:153], s[42:43], 0, v[142:143]
	s_add_i32 m0, s44, 0x2000
	s_nop 0
	global_load_lds_dwordx4 v[152:153], off
	v_lshl_add_u64 v[152:153], v[218:219], 0, s[12:13]
	s_mov_b32 m0, s47
	s_nop 0
	global_load_lds_dwordx4 v[152:153], off
	v_lshl_add_u64 v[152:153], v[220:221], 0, s[12:13]
	s_mov_b32 m0, s48
	s_nop 0
	global_load_lds_dwordx4 v[152:153], off
	s_waitcnt vmcnt(8)
	s_waitcnt lgkmcnt(0)
	s_barrier
	s_setprio 0
	s_waitcnt lgkmcnt(0)
	v_mfma_f32_16x16x32_bf16 v[60:63], v[128:131], v[182:185], v[60:63]
	v_mfma_f32_16x16x32_bf16 v[56:59], v[148:151], v[182:185], v[56:59]
	v_mfma_f32_16x16x32_bf16 v[44:47], v[128:131], v[190:193], v[44:47]
	v_mfma_f32_16x16x32_bf16 v[40:43], v[148:151], v[190:193], v[40:43]
	v_mfma_f32_16x16x32_bf16 v[32:35], v[128:131], v[202:205], v[32:35]
	v_mfma_f32_16x16x32_bf16 v[24:27], v[148:151], v[202:205], v[24:27]
	v_mfma_f32_16x16x32_bf16 v[16:19], v[128:131], v[210:213], v[16:19]
	v_mfma_f32_16x16x32_bf16 v[8:11], v[148:151], v[210:213], v[8:11]
	v_mfma_f32_16x16x32_bf16 v[60:63], v[132:135], v[186:189], v[60:63]
	v_mfma_f32_16x16x32_bf16 v[56:59], v[162:165], v[186:189], v[56:59]
	v_mfma_f32_16x16x32_bf16 v[44:47], v[132:135], v[194:197], v[44:47]
	v_mfma_f32_16x16x32_bf16 v[40:43], v[162:165], v[194:197], v[40:43]
	v_mfma_f32_16x16x32_bf16 v[32:35], v[132:135], v[206:209], v[32:35]
	v_mfma_f32_16x16x32_bf16 v[24:27], v[162:165], v[206:209], v[24:27]
	v_mfma_f32_16x16x32_bf16 v[16:19], v[132:135], v[214:217], v[16:19]
	v_mfma_f32_16x16x32_bf16 v[8:11], v[162:165], v[214:217], v[8:11]
	v_mfma_f32_16x16x32_bf16 v[52:55], v[166:169], v[182:185], v[52:55]
	v_mfma_f32_16x16x32_bf16 v[48:51], v[174:177], v[182:185], v[48:51]
	v_mfma_f32_16x16x32_bf16 v[36:39], v[166:169], v[190:193], v[36:39]
	v_mfma_f32_16x16x32_bf16 v[28:31], v[174:177], v[190:193], v[28:31]
	v_mfma_f32_16x16x32_bf16 v[20:23], v[166:169], v[202:205], v[20:23]
	v_mfma_f32_16x16x32_bf16 v[12:15], v[174:177], v[202:205], v[12:15]
	v_mfma_f32_16x16x32_bf16 v[4:7], v[166:169], v[210:213], v[4:7]
	v_mfma_f32_16x16x32_bf16 v[0:3], v[174:177], v[210:213], v[0:3]
	v_mfma_f32_16x16x32_bf16 v[52:55], v[170:173], v[186:189], v[52:55]
	v_mfma_f32_16x16x32_bf16 v[48:51], v[178:181], v[186:189], v[48:51]
	v_mfma_f32_16x16x32_bf16 v[36:39], v[170:173], v[194:197], v[36:39]
	v_mfma_f32_16x16x32_bf16 v[28:31], v[178:181], v[194:197], v[28:31]
	v_mfma_f32_16x16x32_bf16 v[20:23], v[170:173], v[206:209], v[20:23]
	v_mfma_f32_16x16x32_bf16 v[12:15], v[178:181], v[206:209], v[12:15]
	v_mfma_f32_16x16x32_bf16 v[4:7], v[170:173], v[214:217], v[4:7]
	v_mfma_f32_16x16x32_bf16 v[0:3], v[178:181], v[214:217], v[0:3]
	s_setprio 1
	s_barrier
	s_add_i32 s72, s72, 2
	s_add_u32 s26, s26, 0x100
	s_addc_u32 s27, s27, 0
	s_add_u32 s70, s70, 0x100
	s_addc_u32 s71, s71, 0
	s_cmp_gt_u32 s72, 41
	s_cbranch_scc0 .LBB0_1363
	s_and_b64 vcc, exec, s[14:15]
	s_cbranch_vccz .LBB0_1366
	s_barrier
